# hyena: also hoisted K-coefficient global loads to f1 and gate-row global loads to i2 start (longer prefetch distance)
# speedup vs baseline: 1.0019x; 1.0019x over previous
; #define LAS __attribute__((address_space(3)))
; #define OPAQUE_I(x) asm volatile("" : "+v"(x))
; template <int R, bool INV> DEV void dft_regs(cf (&v)[R]) {
; #pragma unroll
;     for (int s = R; s >= 2; s >>= 1) {
;         const int h = s >> 1;
; #pragma unroll
;         for (int b = 0; b < R; b += s) {
; #pragma unroll
;             for (int k = 0; k < h; ++k) {
;                 const cf a = v[b + k], c = v[b + k + h];
;                 v[b + k] = a + c;
;                 const cf d = a - c;
;                 const int m = k * (32 / s);
;                 const float wr = tw_cos(m), wi = INV ? tw_sin(m) : -tw_sin(m);
;                 v[b + k + h] = cf{d.x * wr - d.y * wi, d.x * wi + d.y * wr};
;             }
;         }
;     }
; DEV void fft_f1x2(LAS cf* buf0, LAS cf* buf1, const cf (&z0)[8], const cf (&z1)[8], int tid) {
;     OPAQUE_I(tid);
;     cf v[16], u[16];
; #pragma unroll
;     for (int q = 0; q < 8; ++q) { v[q] = z0[q]; v[q + 8] = cf{0.f, 0.f}; u[q] = z1[q]; u[q + 8] = cf{0.f, 0.f}; }
;     dft_regs<16, false>(v); dft_regs<16, false>(u);
.LBB0_519:
	v_pk_mul_f32 v[16:17], v[26:27], s[16:17] op_sel_hi:[1,0]
	v_pk_add_f32 v[0:1], v[24:25], 0 op_sel_hi:[1,0]
	v_pk_fma_f32 v[18:19], v[26:27], s[84:85], v[16:17] op_sel:[0,0,1] op_sel_hi:[1,0,0]
	v_pk_fma_f32 v[16:17], v[26:27], s[84:85], v[16:17] op_sel:[0,0,1] op_sel_hi:[1,0,0] neg_lo:[0,0,1] neg_hi:[0,0,1]
	v_pk_mul_f32 v[2:3], v[24:25], 0 op_sel_hi:[1,0]
	v_mov_b32_e32 v19, v17
	v_pk_add_f32 v[16:17], v[22:23], 0 op_sel_hi:[1,0]
	v_pk_add_f32 v[4:5], v[24:25], v[2:3] op_sel:[0,1] op_sel_hi:[1,0] neg_lo:[0,1] neg_hi:[0,1]
	v_pk_add_f32 v[80:81], v[0:1], v[16:17]
	v_pk_add_f32 v[0:1], v[0:1], v[16:17] neg_lo:[0,1] neg_hi:[0,1]
	v_pk_add_f32 v[2:3], v[24:25], v[2:3] op_sel:[0,1] op_sel_hi:[1,0]
	v_pk_fma_f32 v[66:67], v[22:23], 0, v[22:23] op_sel:[0,0,1] op_sel_hi:[1,0,0]
	v_pk_fma_f32 v[68:69], v[22:23], 0, v[22:23] op_sel:[0,0,1] op_sel_hi:[1,0,0] neg_lo:[0,0,1] neg_hi:[0,0,1]
	v_pk_mul_f32 v[16:17], v[0:1], 0 op_sel_hi:[1,0]
	v_mov_b32_e32 v5, v3
	v_pk_add_f32 v[2:3], v[30:31], 0 op_sel_hi:[1,0]
	v_pk_mul_f32 v[6:7], v[30:31], s[84:85] op_sel_hi:[1,0]
	v_mov_b32_e32 v67, v69
	v_pk_add_f32 v[68:69], v[32:33], 0 op_sel_hi:[1,0]
	v_pk_add_f32 v[82:83], v[0:1], v[16:17] op_sel:[0,1] op_sel_hi:[1,0] neg_lo:[0,1] neg_hi:[0,1]
	v_pk_add_f32 v[0:1], v[0:1], v[16:17] op_sel:[0,1] op_sel_hi:[1,0]
	v_pk_fma_f32 v[8:9], v[30:31], s[16:17], v[6:7] op_sel:[0,0,1] op_sel_hi:[1,0,0]
	v_pk_fma_f32 v[6:7], v[30:31], s[16:17], v[6:7] op_sel:[0,0,1] op_sel_hi:[1,0,0] neg_lo:[0,0,1] neg_hi:[0,0,1]
	v_mov_b32_e32 v83, v1
	v_pk_add_f32 v[0:1], v[2:3], v[68:69]
	v_pk_add_f32 v[2:3], v[2:3], v[68:69] neg_lo:[0,1] neg_hi:[0,1]
	v_mov_b32_e32 v9, v7
	v_pk_add_f32 v[6:7], v[28:29], 0 op_sel_hi:[1,0]
	v_pk_add_f32 v[72:73], v[34:35], 0 op_sel_hi:[1,0]
	v_pk_mul_f32 v[16:17], v[2:3], s[18:19] op_sel_hi:[1,0]
	v_pk_mul_f32 v[10:11], v[28:29], s[18:19] op_sel_hi:[1,0]
	v_pk_fma_f32 v[68:69], v[2:3], s[18:19], v[16:17] op_sel:[0,0,1] op_sel_hi:[1,0,0]
	v_pk_fma_f32 v[2:3], v[2:3], s[18:19], v[16:17] op_sel_hi:[1,0,0] neg_lo:[0,0,1] neg_hi:[0,0,1]
	v_pk_add_f32 v[16:17], v[6:7], v[72:73]
	v_pk_add_f32 v[6:7], v[6:7], v[72:73] neg_lo:[0,1] neg_hi:[0,1]
	v_pk_add_f32 v[14:15], v[26:27], 0 op_sel_hi:[1,0]
	v_pk_add_f32 v[76:77], v[36:37], 0 op_sel_hi:[1,0]
	v_pk_fma_f32 v[72:73], v[6:7], 0, v[6:7] op_sel:[0,0,1] op_sel_hi:[1,0,0]
	v_pk_fma_f32 v[6:7], v[6:7], 0, v[6:7] op_sel:[0,0,1] op_sel_hi:[1,0,0] neg_lo:[0,0,1] neg_hi:[0,0,1]
	v_pk_fma_f32 v[12:13], v[28:29], s[18:19], v[10:11] op_sel:[0,0,1] op_sel_hi:[1,0,0]
	v_pk_fma_f32 v[10:11], v[28:29], s[18:19], v[10:11] op_sel_hi:[1,0,0] neg_lo:[0,0,1] neg_hi:[0,0,1]
	v_mov_b32_e32 v73, v7
	v_pk_add_f32 v[6:7], v[14:15], v[76:77]
	v_pk_add_f32 v[14:15], v[14:15], v[76:77] neg_lo:[0,1] neg_hi:[0,1]
	v_pk_add_f32 v[76:77], v[4:5], v[66:67]
	v_pk_add_f32 v[4:5], v[4:5], v[66:67] neg_lo:[0,1] neg_hi:[0,1]
	v_mov_b32_e32 v10, v33
	s_mov_b32 s30, s85
	s_mov_b32 s31, s0
	v_pk_mul_f32 v[70:71], v[32:33], s[84:85] op_sel_hi:[0,1]
	v_pk_mul_f32 v[66:67], v[4:5], 0 op_sel_hi:[1,0]
	v_pk_fma_f32 v[70:71], v[10:11], s[30:31], v[70:71] op_sel_hi:[0,1,1] neg_lo:[0,0,1] neg_hi:[0,0,1]
	v_pk_add_f32 v[84:85], v[4:5], v[66:67] op_sel:[0,1] op_sel_hi:[1,0] neg_lo:[0,1] neg_hi:[0,1]
	v_pk_add_f32 v[4:5], v[4:5], v[66:67] op_sel:[0,1] op_sel_hi:[1,0]
	v_mul_f32_e32 v10, 0x3f3504f3, v34
	v_mov_b32_e32 v74, v35
	s_mov_b32 s28, s97
	s_mov_b32 s29, s96
	s_mov_b32 s24, s85
	s_mov_b32 s25, s84
	v_mov_b32_e32 v85, v5
	v_pk_add_f32 v[4:5], v[8:9], v[70:71]
	v_pk_add_f32 v[8:9], v[8:9], v[70:71] neg_lo:[0,1] neg_hi:[0,1]
	v_pk_fma_f32 v[74:75], v[74:75], s[28:29], v[10:11] op_sel_hi:[0,1,0] neg_lo:[0,0,1] neg_hi:[0,0,1]
	v_mov_b32_e32 v10, v37
	s_mov_b32 s34, s84
	s_mov_b32 s35, s88
	v_pk_mul_f32 v[78:79], v[36:37], s[24:25] op_sel_hi:[0,1]
	v_pk_mul_f32 v[66:67], v[8:9], s[18:19] op_sel_hi:[1,0]
	v_mov_b32_e32 v13, v11
	v_pk_fma_f32 v[78:79], v[10:11], s[34:35], v[78:79] op_sel_hi:[0,1,1] neg_lo:[0,0,1] neg_hi:[0,0,1]
	v_pk_fma_f32 v[70:71], v[8:9], s[18:19], v[66:67] op_sel:[0,0,1] op_sel_hi:[1,0,0]
	v_pk_fma_f32 v[8:9], v[8:9], s[18:19], v[66:67] op_sel_hi:[1,0,0] neg_lo:[0,0,1] neg_hi:[0,0,1]
	v_pk_add_f32 v[10:11], v[12:13], v[74:75] neg_lo:[0,1] neg_hi:[0,1]
	v_pk_add_f32 v[66:67], v[80:81], v[16:17]
	v_pk_add_f32 v[16:17], v[80:81], v[16:17] neg_lo:[0,1] neg_hi:[0,1]
	v_mov_b32_e32 v71, v9
	v_pk_add_f32 v[8:9], v[12:13], v[74:75]
	v_pk_fma_f32 v[12:13], v[10:11], 0, v[10:11] op_sel:[0,0,1] op_sel_hi:[1,0,0]
	v_pk_fma_f32 v[10:11], v[10:11], 0, v[10:11] op_sel:[0,0,1] op_sel_hi:[1,0,0] neg_lo:[0,0,1] neg_hi:[0,0,1]
	v_pk_mul_f32 v[74:75], v[16:17], 0 op_sel_hi:[1,0]
	v_mov_b32_e32 v13, v11
	v_pk_add_f32 v[10:11], v[18:19], v[78:79]
	v_pk_add_f32 v[18:19], v[18:19], v[78:79] neg_lo:[0,1] neg_hi:[0,1]
	v_pk_add_f32 v[78:79], v[16:17], v[74:75] op_sel:[0,1] op_sel_hi:[1,0] neg_lo:[0,1] neg_hi:[0,1]
	v_pk_add_f32 v[16:17], v[16:17], v[74:75] op_sel:[0,1] op_sel_hi:[1,0]
	v_mul_f32_e32 v2, 0x3f3504f3, v14
	v_mov_b32_e32 v79, v17
	v_pk_add_f32 v[16:17], v[0:1], v[6:7]
	v_pk_add_f32 v[0:1], v[0:1], v[6:7] neg_lo:[0,1] neg_hi:[0,1]
	v_pk_add_f32 v[74:75], v[82:83], v[72:73]
	v_pk_fma_f32 v[6:7], v[0:1], 0, v[0:1] op_sel:[0,0,1] op_sel_hi:[1,0,0]
	v_pk_fma_f32 v[0:1], v[0:1], 0, v[0:1] op_sel:[0,0,1] op_sel_hi:[1,0,0] neg_lo:[0,0,1] neg_hi:[0,0,1]
	v_pk_fma_f32 v[14:15], v[14:15], s[28:29], v[2:3] op_sel:[1,0,0] op_sel_hi:[1,1,0] neg_lo:[0,0,1] neg_hi:[0,0,1]
	v_mov_b32_e32 v7, v1
	v_pk_add_f32 v[0:1], v[82:83], v[72:73] neg_lo:[0,1] neg_hi:[0,1]
	v_mov_b32_e32 v69, v3
	v_pk_mul_f32 v[72:73], v[0:1], 0 op_sel_hi:[1,0]
	v_mul_f32_e32 v2, 0x3f3504f3, v18
; template <int R, bool INV> DEV void dft_regs(cf (&v)[R]) {
; #pragma unroll
;     for (int s = R; s >= 2; s >>= 1) {
;         const int h = s >> 1;
; #pragma unroll
;         for (int b = 0; b < R; b += s) {
; #pragma unroll
;             for (int k = 0; k < h; ++k) {
;                 const cf a = v[b + k], c = v[b + k + h];
;                 v[b + k] = a + c;
;                 const cf d = a - c;
;                 const int m = k * (32 / s);
;                 const float wr = tw_cos(m), wi = INV ? tw_sin(m) : -tw_sin(m);
;                 v[b + k + h] = cf{d.x * wr - d.y * wi, d.x * wi + d.y * wr};
;             }
;         }
;     }
	v_pk_add_f32 v[80:81], v[0:1], v[72:73] op_sel:[0,1] op_sel_hi:[1,0] neg_lo:[0,1] neg_hi:[0,1]
	v_pk_add_f32 v[0:1], v[0:1], v[72:73] op_sel:[0,1] op_sel_hi:[1,0]
	v_pk_fma_f32 v[18:19], v[18:19], s[28:29], v[2:3] op_sel:[1,0,0] op_sel_hi:[1,1,0] neg_lo:[0,0,1] neg_hi:[0,0,1]
	v_mov_b32_e32 v81, v1
	v_pk_add_f32 v[0:1], v[68:69], v[14:15] neg_lo:[0,1] neg_hi:[0,1]
	v_pk_add_f32 v[2:3], v[68:69], v[14:15]
	v_pk_fma_f32 v[14:15], v[0:1], 0, v[0:1] op_sel:[0,0,1] op_sel_hi:[1,0,0]
	v_pk_fma_f32 v[0:1], v[0:1], 0, v[0:1] op_sel:[0,0,1] op_sel_hi:[1,0,0] neg_lo:[0,0,1] neg_hi:[0,0,1]
	v_pk_add_f32 v[72:73], v[76:77], v[8:9]
	v_mov_b32_e32 v15, v1
	v_pk_add_f32 v[0:1], v[76:77], v[8:9] neg_lo:[0,1] neg_hi:[0,1]
	v_pk_add_f32 v[86:87], v[84:85], v[12:13]
	v_pk_mul_f32 v[8:9], v[0:1], 0 op_sel_hi:[1,0]
	v_pk_add_f32 v[68:69], v[66:67], v[16:17]
	v_pk_add_f32 v[82:83], v[0:1], v[8:9] op_sel:[0,1] op_sel_hi:[1,0] neg_lo:[0,1] neg_hi:[0,1]
	v_pk_add_f32 v[0:1], v[0:1], v[8:9] op_sel:[0,1] op_sel_hi:[1,0]
	v_pk_add_f32 v[8:9], v[4:5], v[10:11]
	v_mov_b32_e32 v83, v1
	v_pk_add_f32 v[0:1], v[4:5], v[10:11] neg_lo:[0,1] neg_hi:[0,1]
	v_pk_add_f32 v[88:89], v[70:71], v[18:19]
	v_pk_fma_f32 v[10:11], v[0:1], 0, v[0:1] op_sel:[0,0,1] op_sel_hi:[1,0,0]
	v_pk_fma_f32 v[0:1], v[0:1], 0, v[0:1] op_sel:[0,0,1] op_sel_hi:[1,0,0] neg_lo:[0,0,1] neg_hi:[0,0,1]
	v_pk_add_f32 v[76:77], v[72:73], v[8:9]
	v_mov_b32_e32 v11, v1
	v_pk_add_f32 v[0:1], v[84:85], v[12:13] neg_lo:[0,1] neg_hi:[0,1]
	v_pk_add_f32 v[8:9], v[72:73], v[8:9] neg_lo:[0,1] neg_hi:[0,1]
	v_pk_mul_f32 v[4:5], v[0:1], 0 op_sel_hi:[1,0]
	v_pk_add_f32 v[72:73], v[82:83], v[10:11]
	v_pk_add_f32 v[84:85], v[0:1], v[4:5] op_sel:[0,1] op_sel_hi:[1,0] neg_lo:[0,1] neg_hi:[0,1]
	v_pk_add_f32 v[0:1], v[0:1], v[4:5] op_sel:[0,1] op_sel_hi:[1,0]
	v_pk_add_f32 v[10:11], v[82:83], v[10:11] neg_lo:[0,1] neg_hi:[0,1]
	v_mov_b32_e32 v85, v1
	v_pk_add_f32 v[0:1], v[70:71], v[18:19] neg_lo:[0,1] neg_hi:[0,1]
	v_pk_add_f32 v[70:71], v[74:75], v[2:3]
	v_pk_fma_f32 v[90:91], v[0:1], 0, v[0:1] op_sel:[0,0,1] op_sel_hi:[1,0,0]
	v_pk_fma_f32 v[0:1], v[0:1], 0, v[0:1] op_sel:[0,0,1] op_sel_hi:[1,0,0] neg_lo:[0,0,1] neg_hi:[0,0,1]
	v_pk_add_f32 v[2:3], v[74:75], v[2:3] neg_lo:[0,1] neg_hi:[0,1]
	v_mov_b32_e32 v91, v1
	v_pk_add_f32 v[0:1], v[66:67], v[16:17] neg_lo:[0,1] neg_hi:[0,1]
	v_pk_add_f32 v[16:17], v[78:79], v[6:7]
	v_pk_mul_f32 v[12:13], v[0:1], 0 op_sel_hi:[1,0]
	v_pk_add_f32 v[6:7], v[78:79], v[6:7] neg_lo:[0,1] neg_hi:[0,1]
	v_pk_add_f32 v[4:5], v[0:1], v[12:13] op_sel:[0,1] op_sel_hi:[1,0] neg_lo:[0,1] neg_hi:[0,1]
	v_pk_add_f32 v[0:1], v[0:1], v[12:13] op_sel:[0,1] op_sel_hi:[1,0]
	v_pk_mul_f32 v[12:13], v[6:7], 0 op_sel_hi:[1,0]
	v_mov_b32_e32 v5, v1
	v_pk_add_f32 v[0:1], v[6:7], v[12:13] op_sel:[0,1] op_sel_hi:[1,0] neg_lo:[0,1] neg_hi:[0,1]
	v_pk_add_f32 v[6:7], v[6:7], v[12:13] op_sel:[0,1] op_sel_hi:[1,0]
	v_pk_mul_f32 v[12:13], v[2:3], 0 op_sel_hi:[1,0]
	v_mov_b32_e32 v1, v7
	v_pk_add_f32 v[6:7], v[2:3], v[12:13] op_sel:[0,1] op_sel_hi:[1,0] neg_lo:[0,1] neg_hi:[0,1]
	v_pk_add_f32 v[2:3], v[2:3], v[12:13] op_sel:[0,1] op_sel_hi:[1,0]
	v_pk_add_f32 v[12:13], v[80:81], v[14:15] neg_lo:[0,1] neg_hi:[0,1]
	v_pk_add_f32 v[18:19], v[80:81], v[14:15]
	v_pk_mul_f32 v[14:15], v[12:13], 0 op_sel_hi:[1,0]
	v_mov_b32_e32 v7, v3
	v_pk_add_f32 v[2:3], v[12:13], v[14:15] op_sel:[0,1] op_sel_hi:[1,0] neg_lo:[0,1] neg_hi:[0,1]
	v_pk_add_f32 v[12:13], v[12:13], v[14:15] op_sel:[0,1] op_sel_hi:[1,0]
	v_pk_mul_f32 v[14:15], v[8:9], 0 op_sel_hi:[1,0]
	v_mov_b32_e32 v3, v13
	v_pk_add_f32 v[12:13], v[8:9], v[14:15] op_sel:[0,1] op_sel_hi:[1,0] neg_lo:[0,1] neg_hi:[0,1]
	v_pk_add_f32 v[8:9], v[8:9], v[14:15] op_sel:[0,1] op_sel_hi:[1,0]
	v_pk_mul_f32 v[14:15], v[10:11], 0 op_sel_hi:[1,0]
	v_mov_b32_e32 v13, v9
	v_pk_add_f32 v[8:9], v[10:11], v[14:15] op_sel:[0,1] op_sel_hi:[1,0] neg_lo:[0,1] neg_hi:[0,1]
	v_pk_add_f32 v[10:11], v[10:11], v[14:15] op_sel:[0,1] op_sel_hi:[1,0]
	v_pk_mul_f32 v[92:93], v[50:51], s[16:17] op_sel_hi:[1,0]
	v_mov_b32_e32 v9, v11
	v_pk_add_f32 v[10:11], v[86:87], v[88:89] neg_lo:[0,1] neg_hi:[0,1]
	v_pk_fma_f32 v[94:95], v[50:51], s[84:85], v[92:93] op_sel:[0,0,1] op_sel_hi:[1,0,0]
	v_pk_mul_f32 v[66:67], v[10:11], 0 op_sel_hi:[1,0]
	v_pk_fma_f32 v[92:93], v[50:51], s[84:85], v[92:93] op_sel:[0,0,1] op_sel_hi:[1,0,0] neg_lo:[0,0,1] neg_hi:[0,0,1]
	v_pk_add_f32 v[14:15], v[10:11], v[66:67] op_sel:[0,1] op_sel_hi:[1,0] neg_lo:[0,1] neg_hi:[0,1]
	v_pk_add_f32 v[10:11], v[10:11], v[66:67] op_sel:[0,1] op_sel_hi:[1,0]
	v_pk_add_f32 v[66:67], v[84:85], v[90:91] neg_lo:[0,1] neg_hi:[0,1]
	v_mov_b32_e32 v15, v11
	v_pk_mul_f32 v[80:81], v[66:67], 0 op_sel_hi:[1,0]
	v_mov_b32_e32 v95, v93
	v_pk_add_f32 v[10:11], v[66:67], v[80:81] op_sel:[0,1] op_sel_hi:[1,0] neg_lo:[0,1] neg_hi:[0,1]
	v_pk_add_f32 v[66:67], v[66:67], v[80:81] op_sel:[0,1] op_sel_hi:[1,0]
	v_pk_add_f32 v[92:93], v[46:47], 0 op_sel_hi:[1,0]
	v_mov_b32_e32 v11, v67
	v_pk_add_f32 v[66:67], v[38:39], 0 op_sel_hi:[1,0]
	v_mov_b32_e32 v108, v41
	v_pk_mul_f32 v[110:111], v[40:41], s[24:25] op_sel_hi:[0,1]
	v_pk_mul_f32 v[80:81], v[38:39], 0 op_sel_hi:[1,0]
	v_pk_fma_f32 v[108:109], v[108:109], s[34:35], v[110:111] op_sel_hi:[0,1,1] neg_lo:[0,0,1] neg_hi:[0,0,1]
	v_pk_add_f32 v[110:111], v[66:67], v[92:93]
	v_pk_add_f32 v[66:67], v[66:67], v[92:93] neg_lo:[0,1] neg_hi:[0,1]
	v_pk_add_f32 v[82:83], v[38:39], v[80:81] op_sel:[0,1] op_sel_hi:[1,0] neg_lo:[0,1] neg_hi:[0,1]
	v_pk_add_f32 v[80:81], v[38:39], v[80:81] op_sel:[0,1] op_sel_hi:[1,0]
	v_pk_fma_f32 v[96:97], v[46:47], 0, v[46:47] op_sel:[0,0,1] op_sel_hi:[1,0,0]
; template <int R, bool INV> DEV void dft_regs(cf (&v)[R]) {
; #pragma unroll
;     for (int s = R; s >= 2; s >>= 1) {
;         const int h = s >> 1;
; #pragma unroll
;         for (int b = 0; b < R; b += s) {
; #pragma unroll
;             for (int k = 0; k < h; ++k) {
;                 const cf a = v[b + k], c = v[b + k + h];
;                 v[b + k] = a + c;
;                 const cf d = a - c;
;                 const int m = k * (32 / s);
;                 const float wr = tw_cos(m), wi = INV ? tw_sin(m) : -tw_sin(m);
;                 v[b + k + h] = cf{d.x * wr - d.y * wi, d.x * wi + d.y * wr};
;             }
;         }
;     }
; DEV void fft_midx2(LAS cf* buf0, LAS cf* buf1, const unsigned* Kp, int blk) {
;     ...
;     u32x4 kw[4];
; #pragma unroll
;     for (int j = 0; j < 4; ++j) kw[j] = *(const u32x4*)(Kp + base + 4 * j);
	v_pk_fma_f32 v[98:99], v[46:47], 0, v[46:47] op_sel:[0,0,1] op_sel_hi:[1,0,0] neg_lo:[0,0,1] neg_hi:[0,0,1]
	v_pk_mul_f32 v[92:93], v[66:67], 0 op_sel_hi:[1,0]
	v_mov_b32_e32 v83, v81
	v_pk_add_f32 v[80:81], v[42:43], 0 op_sel_hi:[1,0]
	v_mov_b32_e32 v97, v99
	v_pk_add_f32 v[98:99], v[48:49], 0 op_sel_hi:[1,0]
	v_pk_add_f32 v[112:113], v[66:67], v[92:93] op_sel:[0,1] op_sel_hi:[1,0] neg_lo:[0,1] neg_hi:[0,1]
	v_pk_add_f32 v[66:67], v[66:67], v[92:93] op_sel:[0,1] op_sel_hi:[1,0]
	v_pk_add_f32 v[74:75], v[84:85], v[90:91]
	v_pk_mul_f32 v[84:85], v[42:43], s[84:85] op_sel_hi:[1,0]
	v_mov_b32_e32 v113, v67
	v_pk_add_f32 v[66:67], v[80:81], v[98:99]
	v_pk_add_f32 v[80:81], v[80:81], v[98:99] neg_lo:[0,1] neg_hi:[0,1]
	v_pk_add_f32 v[78:79], v[86:87], v[88:89]
	v_pk_fma_f32 v[86:87], v[42:43], s[16:17], v[84:85] op_sel:[0,0,1] op_sel_hi:[1,0,0]
	v_pk_fma_f32 v[84:85], v[42:43], s[16:17], v[84:85] op_sel:[0,0,1] op_sel_hi:[1,0,0] neg_lo:[0,0,1] neg_hi:[0,0,1]
	v_mov_b32_e32 v100, v49
	v_pk_mul_f32 v[102:103], v[48:49], s[84:85] op_sel_hi:[0,1]
	v_pk_mul_f32 v[92:93], v[80:81], s[18:19] op_sel_hi:[1,0]
	v_mov_b32_e32 v87, v85
	v_pk_add_f32 v[84:85], v[44:45], 0 op_sel_hi:[1,0]
	v_pk_mul_f32 v[88:89], v[44:45], s[18:19] op_sel_hi:[1,0]
	v_pk_fma_f32 v[100:101], v[100:101], s[30:31], v[102:103] op_sel_hi:[0,1,1] neg_lo:[0,0,1] neg_hi:[0,0,1]
	v_pk_add_f32 v[102:103], v[52:53], 0 op_sel_hi:[1,0]
	v_pk_fma_f32 v[98:99], v[80:81], s[18:19], v[92:93] op_sel:[0,0,1] op_sel_hi:[1,0,0]
	v_pk_fma_f32 v[80:81], v[80:81], s[18:19], v[92:93] op_sel_hi:[1,0,0] neg_lo:[0,0,1] neg_hi:[0,0,1]
	v_pk_fma_f32 v[90:91], v[44:45], s[18:19], v[88:89] op_sel:[0,0,1] op_sel_hi:[1,0,0]
	v_pk_fma_f32 v[88:89], v[44:45], s[18:19], v[88:89] op_sel_hi:[1,0,0] neg_lo:[0,0,1] neg_hi:[0,0,1]
	v_mul_f32_e32 v104, 0x3f3504f3, v52
	v_mov_b32_e32 v106, v53
	v_mov_b32_e32 v99, v81
	v_pk_add_f32 v[80:81], v[84:85], v[102:103]
	v_pk_add_f32 v[84:85], v[84:85], v[102:103] neg_lo:[0,1] neg_hi:[0,1]
	v_mov_b32_e32 v91, v89
	v_pk_add_f32 v[88:89], v[50:51], 0 op_sel_hi:[1,0]
	v_pk_fma_f32 v[104:105], v[106:107], s[28:29], v[104:105] op_sel_hi:[0,1,0] neg_lo:[0,0,1] neg_hi:[0,0,1]
	v_pk_add_f32 v[106:107], v[40:41], 0 op_sel_hi:[1,0]
	v_pk_fma_f32 v[92:93], v[84:85], 0, v[84:85] op_sel:[0,0,1] op_sel_hi:[1,0,0]
	v_pk_fma_f32 v[84:85], v[84:85], 0, v[84:85] op_sel:[0,0,1] op_sel_hi:[1,0,0] neg_lo:[0,0,1] neg_hi:[0,0,1]
	v_mov_b32_e32 v114, v21
	v_mov_b32_e32 v93, v85
	v_pk_add_f32 v[84:85], v[88:89], v[106:107]
	v_pk_add_f32 v[88:89], v[88:89], v[106:107] neg_lo:[0,1] neg_hi:[0,1]
	s_mov_b32 s2, s86
	v_mul_f32_e32 v102, 0x3f3504f3, v88
	v_pk_fma_f32 v[88:89], v[88:89], s[28:29], v[102:103] op_sel:[1,0,0] op_sel_hi:[1,1,0] neg_lo:[0,0,1] neg_hi:[0,0,1]
	v_pk_add_f32 v[102:103], v[82:83], v[96:97]
	v_pk_add_f32 v[82:83], v[82:83], v[96:97] neg_lo:[0,1] neg_hi:[0,1]
	s_mov_b32 s3, s4
	v_pk_mul_f32 v[96:97], v[82:83], 0 op_sel_hi:[1,0]
	s_mov_b32 s10, s4
	v_pk_add_f32 v[106:107], v[82:83], v[96:97] op_sel:[0,1] op_sel_hi:[1,0] neg_lo:[0,1] neg_hi:[0,1]
	v_pk_add_f32 v[82:83], v[82:83], v[96:97] op_sel:[0,1] op_sel_hi:[1,0]
	s_mov_b32 s6, s94
	v_mov_b32_e32 v107, v83
	v_pk_add_f32 v[82:83], v[86:87], v[100:101]
	v_pk_add_f32 v[86:87], v[86:87], v[100:101] neg_lo:[0,1] neg_hi:[0,1]
	s_mov_b32 s7, s82
	v_pk_mul_f32 v[96:97], v[86:87], s[18:19] op_sel_hi:[1,0]
	s_mov_b32 s8, s82
	v_pk_fma_f32 v[100:101], v[86:87], s[18:19], v[96:97] op_sel:[0,0,1] op_sel_hi:[1,0,0]
	v_pk_fma_f32 v[86:87], v[86:87], s[18:19], v[96:97] op_sel_hi:[1,0,0] neg_lo:[0,0,1] neg_hi:[0,0,1]
	s_lshl_b32 s92, s19, 13
	v_lshl_add_u64 v[232:233], s[92:93], 2, v[54:55]
	global_load_dwordx4 v[170:173], v[232:233], off offset:48
	global_load_dwordx4 v[174:177], v[232:233], off offset:32
	global_load_dwordx4 v[178:181], v[232:233], off offset:16
	global_load_dwordx4 v[182:185], v[232:233], off
	v_mov_b32_e32 v101, v87
	v_pk_add_f32 v[86:87], v[90:91], v[104:105]
	v_pk_add_f32 v[90:91], v[90:91], v[104:105] neg_lo:[0,1] neg_hi:[0,1]
	s_mov_b32 s1, s85
	v_pk_fma_f32 v[96:97], v[90:91], 0, v[90:91] op_sel:[0,0,1] op_sel_hi:[1,0,0]
	v_pk_fma_f32 v[90:91], v[90:91], 0, v[90:91] op_sel:[0,0,1] op_sel_hi:[1,0,0] neg_lo:[0,0,1] neg_hi:[0,0,1]
	s_mov_b32 s89, s84
	v_mov_b32_e32 v97, v91
	v_pk_add_f32 v[90:91], v[94:95], v[108:109]
	v_pk_add_f32 v[94:95], v[94:95], v[108:109] neg_lo:[0,1] neg_hi:[0,1]
	v_mul_f32_e32 v104, 0x3f3504f3, v94
	v_pk_fma_f32 v[94:95], v[94:95], s[28:29], v[104:105] op_sel:[1,0,0] op_sel_hi:[1,1,0] neg_lo:[0,0,1] neg_hi:[0,0,1]
	v_pk_add_f32 v[104:105], v[110:111], v[80:81]
	v_pk_add_f32 v[80:81], v[110:111], v[80:81] neg_lo:[0,1] neg_hi:[0,1]
	v_pk_mul_f32 v[108:109], v[80:81], 0 op_sel_hi:[1,0]
	v_pk_add_f32 v[110:111], v[80:81], v[108:109] op_sel:[0,1] op_sel_hi:[1,0] neg_lo:[0,1] neg_hi:[0,1]
	v_pk_add_f32 v[80:81], v[80:81], v[108:109] op_sel:[0,1] op_sel_hi:[1,0]
	v_mov_b32_e32 v111, v81
	v_pk_add_f32 v[80:81], v[66:67], v[84:85]
	v_pk_add_f32 v[66:67], v[66:67], v[84:85] neg_lo:[0,1] neg_hi:[0,1]
	v_pk_fma_f32 v[84:85], v[66:67], 0, v[66:67] op_sel:[0,0,1] op_sel_hi:[1,0,0]
	v_pk_fma_f32 v[66:67], v[66:67], 0, v[66:67] op_sel:[0,0,1] op_sel_hi:[1,0,0] neg_lo:[0,0,1] neg_hi:[0,0,1]
	v_mov_b32_e32 v85, v67
	v_pk_add_f32 v[66:67], v[112:113], v[92:93]
	v_pk_add_f32 v[92:93], v[112:113], v[92:93] neg_lo:[0,1] neg_hi:[0,1]
	v_pk_mul_f32 v[108:109], v[92:93], 0 op_sel_hi:[1,0]
	v_pk_add_f32 v[112:113], v[92:93], v[108:109] op_sel:[0,1] op_sel_hi:[1,0] neg_lo:[0,1] neg_hi:[0,1]
	v_pk_add_f32 v[92:93], v[92:93], v[108:109] op_sel:[0,1] op_sel_hi:[1,0]
	v_mov_b32_e32 v113, v93
	v_pk_add_f32 v[92:93], v[98:99], v[88:89]
; #define LAS __attribute__((address_space(3)))
; #define SINCOSPI(x, s, c) do { const float hx_ = 0.5f * (x); *(s) = __builtin_amdgcn_sinf(hx_); *(c) = __builtin_amdgcn_cosf(hx_); } while (0)
; template <int R, bool INV> DEV void dft_regs(cf (&v)[R]) {
; #pragma unroll
;     for (int s = R; s >= 2; s >>= 1) {
;         const int h = s >> 1;
; #pragma unroll
;         for (int b = 0; b < R; b += s) {
; #pragma unroll
;             for (int k = 0; k < h; ++k) {
;                 const cf a = v[b + k], c = v[b + k + h];
;                 v[b + k] = a + c;
;                 const cf d = a - c;
;                 const int m = k * (32 / s);
;                 const float wr = tw_cos(m), wi = INV ? tw_sin(m) : -tw_sin(m);
;                 v[b + k + h] = cf{d.x * wr - d.y * wi, d.x * wi + d.y * wr};
;             }
;         }
;     }
; DEV void fft_f1x2(LAS cf* buf0, LAS cf* buf1, const cf (&z0)[8], const cf (&z1)[8], int tid) {
;     ...
;     float sn, cs; SINCOSPI(-(float)tid * (2.0f / 8192.0f), &sn, &cs);
;     const cf w = cf{cs, sn}; cf wp = cf{1.f, 0.f};
;     LAS cf* p0 = buf0 + PADI(tid); LAS cf* p1 = buf1 + PADI(tid);
; #pragma unroll
;     for (int p = 0; p < 16; ++p) { p0[544 * p] = cmul(v[BR16[p]], wp); p1[544 * p] = cmul(u[BR16[p]], wp); wp = cmul(wp, w); }
	v_pk_add_f32 v[88:89], v[98:99], v[88:89] neg_lo:[0,1] neg_hi:[0,1]
	v_pk_fma_f32 v[98:99], v[88:89], 0, v[88:89] op_sel:[0,0,1] op_sel_hi:[1,0,0]
	v_pk_fma_f32 v[88:89], v[88:89], 0, v[88:89] op_sel:[0,0,1] op_sel_hi:[1,0,0] neg_lo:[0,0,1] neg_hi:[0,0,1]
	v_mov_b32_e32 v99, v89
	v_pk_add_f32 v[88:89], v[102:103], v[86:87]
	v_pk_add_f32 v[86:87], v[102:103], v[86:87] neg_lo:[0,1] neg_hi:[0,1]
	v_pk_mul_f32 v[102:103], v[86:87], 0 op_sel_hi:[1,0]
	v_pk_add_f32 v[108:109], v[86:87], v[102:103] op_sel:[0,1] op_sel_hi:[1,0] neg_lo:[0,1] neg_hi:[0,1]
	v_pk_add_f32 v[86:87], v[86:87], v[102:103] op_sel:[0,1] op_sel_hi:[1,0]
	v_mov_b32_e32 v109, v87
	v_pk_add_f32 v[86:87], v[82:83], v[90:91]
	v_pk_add_f32 v[82:83], v[82:83], v[90:91] neg_lo:[0,1] neg_hi:[0,1]
	v_pk_fma_f32 v[90:91], v[82:83], 0, v[82:83] op_sel:[0,0,1] op_sel_hi:[1,0,0]
	v_pk_fma_f32 v[82:83], v[82:83], 0, v[82:83] op_sel:[0,0,1] op_sel_hi:[1,0,0] neg_lo:[0,0,1] neg_hi:[0,0,1]
	v_mov_b32_e32 v91, v83
	v_pk_add_f32 v[82:83], v[106:107], v[96:97]
	v_pk_add_f32 v[96:97], v[106:107], v[96:97] neg_lo:[0,1] neg_hi:[0,1]
	v_pk_mul_f32 v[102:103], v[96:97], 0 op_sel_hi:[1,0]
	v_pk_add_f32 v[106:107], v[96:97], v[102:103] op_sel:[0,1] op_sel_hi:[1,0] neg_lo:[0,1] neg_hi:[0,1]
	v_pk_add_f32 v[96:97], v[96:97], v[102:103] op_sel:[0,1] op_sel_hi:[1,0]
	v_mov_b32_e32 v107, v97
	v_pk_add_f32 v[96:97], v[100:101], v[94:95]
	v_pk_add_f32 v[94:95], v[100:101], v[94:95] neg_lo:[0,1] neg_hi:[0,1]
	v_pk_fma_f32 v[100:101], v[94:95], 0, v[94:95] op_sel:[0,0,1] op_sel_hi:[1,0,0]
	v_pk_fma_f32 v[94:95], v[94:95], 0, v[94:95] op_sel:[0,0,1] op_sel_hi:[1,0,0] neg_lo:[0,0,1] neg_hi:[0,0,1]
	v_mov_b32_e32 v101, v95
	v_pk_add_f32 v[94:95], v[104:105], v[80:81]
	v_pk_add_f32 v[80:81], v[104:105], v[80:81] neg_lo:[0,1] neg_hi:[0,1]
	v_pk_mul_f32 v[102:103], v[80:81], 0 op_sel_hi:[1,0]
	v_pk_add_f32 v[104:105], v[80:81], v[102:103] op_sel:[0,1] op_sel_hi:[1,0] neg_lo:[0,1] neg_hi:[0,1]
	v_pk_add_f32 v[80:81], v[80:81], v[102:103] op_sel:[0,1] op_sel_hi:[1,0]
	v_mov_b32_e32 v105, v81
	v_pk_add_f32 v[80:81], v[110:111], v[84:85]
	v_pk_add_f32 v[84:85], v[110:111], v[84:85] neg_lo:[0,1] neg_hi:[0,1]
	v_pk_mul_f32 v[102:103], v[84:85], 0 op_sel_hi:[1,0]
	v_pk_add_f32 v[110:111], v[84:85], v[102:103] op_sel:[0,1] op_sel_hi:[1,0] neg_lo:[0,1] neg_hi:[0,1]
	v_pk_add_f32 v[84:85], v[84:85], v[102:103] op_sel:[0,1] op_sel_hi:[1,0]
	v_mov_b32_e32 v111, v85
	v_pk_add_f32 v[84:85], v[66:67], v[92:93]
	v_pk_add_f32 v[66:67], v[66:67], v[92:93] neg_lo:[0,1] neg_hi:[0,1]
	v_pk_mul_f32 v[92:93], v[66:67], 0 op_sel_hi:[1,0]
	v_pk_add_f32 v[102:103], v[66:67], v[92:93] op_sel:[0,1] op_sel_hi:[1,0] neg_lo:[0,1] neg_hi:[0,1]
	v_pk_add_f32 v[66:67], v[66:67], v[92:93] op_sel:[0,1] op_sel_hi:[1,0]
	v_pk_add_f32 v[92:93], v[112:113], v[98:99]
	v_mov_b32_e32 v103, v67
	v_pk_add_f32 v[66:67], v[112:113], v[98:99] neg_lo:[0,1] neg_hi:[0,1]
	v_pk_mul_f32 v[98:99], v[66:67], 0 op_sel_hi:[1,0]
	v_pk_add_f32 v[112:113], v[66:67], v[98:99] op_sel:[0,1] op_sel_hi:[1,0] neg_lo:[0,1] neg_hi:[0,1]
	v_pk_add_f32 v[66:67], v[66:67], v[98:99] op_sel:[0,1] op_sel_hi:[1,0]
	v_pk_add_f32 v[98:99], v[88:89], v[86:87]
	v_mov_b32_e32 v113, v67
	v_pk_add_f32 v[66:67], v[88:89], v[86:87] neg_lo:[0,1] neg_hi:[0,1]
	v_pk_mul_f32 v[86:87], v[66:67], 0 op_sel_hi:[1,0]
	v_pk_add_f32 v[88:89], v[66:67], v[86:87] op_sel:[0,1] op_sel_hi:[1,0] neg_lo:[0,1] neg_hi:[0,1]
	v_pk_add_f32 v[66:67], v[66:67], v[86:87] op_sel:[0,1] op_sel_hi:[1,0]
	v_pk_add_f32 v[86:87], v[108:109], v[90:91]
	v_mov_b32_e32 v89, v67
	v_pk_add_f32 v[66:67], v[108:109], v[90:91] neg_lo:[0,1] neg_hi:[0,1]
	v_pk_mul_f32 v[90:91], v[66:67], 0 op_sel_hi:[1,0]
	v_pk_add_f32 v[108:109], v[66:67], v[90:91] op_sel:[0,1] op_sel_hi:[1,0] neg_lo:[0,1] neg_hi:[0,1]
	v_pk_add_f32 v[66:67], v[66:67], v[90:91] op_sel:[0,1] op_sel_hi:[1,0]
	v_pk_add_f32 v[90:91], v[82:83], v[96:97]
	v_mov_b32_e32 v109, v67
	v_pk_add_f32 v[66:67], v[82:83], v[96:97] neg_lo:[0,1] neg_hi:[0,1]
	v_pk_mul_f32 v[82:83], v[66:67], 0 op_sel_hi:[1,0]
	v_pk_add_f32 v[96:97], v[66:67], v[82:83] op_sel:[0,1] op_sel_hi:[1,0] neg_lo:[0,1] neg_hi:[0,1]
	v_pk_add_f32 v[66:67], v[66:67], v[82:83] op_sel:[0,1] op_sel_hi:[1,0]
	v_pk_add_f32 v[82:83], v[106:107], v[100:101]
	v_mov_b32_e32 v97, v67
	v_pk_add_f32 v[66:67], v[106:107], v[100:101] neg_lo:[0,1] neg_hi:[0,1]
	v_pk_mul_f32 v[100:101], v[66:67], 0 op_sel_hi:[1,0]
	v_pk_add_f32 v[106:107], v[66:67], v[100:101] op_sel:[0,1] op_sel_hi:[1,0] neg_lo:[0,1] neg_hi:[0,1]
	v_pk_add_f32 v[66:67], v[66:67], v[100:101] op_sel:[0,1] op_sel_hi:[1,0]
	s_nop 0
	v_cvt_f32_i32_e32 v66, v114
	v_mov_b32_e32 v107, v67
	v_mul_f32_e32 v66, 0xb9800000, v66
	v_mul_f32_e32 v66, 0.5, v66
	v_sin_f32_e32 v101, v66
	v_cos_f32_e32 v100, v66
	v_ashrrev_i32_e32 v66, 4, v114
	v_add_lshl_u32 v66, v66, v114, 3
	v_add_u32_e32 v116, 0, v66
	v_add_u32_e32 v117, s33, v66
	v_mov_b64_e32 v[66:67], s[90:91]
	v_pk_mul_f32 v[114:115], v[68:69], v[66:67] op_sel:[1,1] op_sel_hi:[1,0] neg_lo:[1,0]
	v_pk_fma_f32 v[68:69], v[68:69], v[66:67], v[114:115] op_sel_hi:[0,1,1]
	ds_write_b64 v116, v[68:69]
	v_pk_mul_f32 v[114:115], v[94:95], v[66:67] op_sel:[1,1] op_sel_hi:[1,0] neg_lo:[1,0]
	v_pk_fma_f32 v[68:69], v[94:95], v[66:67], v[114:115] op_sel_hi:[0,1,1]
	ds_write_b64 v117, v[68:69]
	v_pk_mul_f32 v[68:69], v[66:67], v[100:101] op_sel:[1,1] op_sel_hi:[1,0] neg_lo:[1,0]
	v_pk_fma_f32 v[94:95], v[66:67], v[100:101], v[68:69] op_sel_hi:[0,1,1]
	v_pk_mul_f32 v[114:115], v[76:77], v[94:95] op_sel:[1,1] op_sel_hi:[1,0] neg_lo:[1,0]
	v_pk_fma_f32 v[68:69], v[76:77], v[94:95], v[114:115] op_sel_hi:[0,1,1]
	ds_write_b64 v116, v[68:69] offset:4352
; #define LAS __attribute__((address_space(3)))
; #define SINCOSPI(x, s, c) do { const float hx_ = 0.5f * (x); *(s) = __builtin_amdgcn_sinf(hx_); *(c) = __builtin_amdgcn_cosf(hx_); } while (0)
; DEV void fft_f1x2(LAS cf* buf0, LAS cf* buf1, const cf (&z0)[8], const cf (&z1)[8], int tid) {
;     ...
;     float sn, cs; SINCOSPI(-(float)tid * (2.0f / 8192.0f), &sn, &cs);
;     const cf w = cf{cs, sn}; cf wp = cf{1.f, 0.f};
;     LAS cf* p0 = buf0 + PADI(tid); LAS cf* p1 = buf1 + PADI(tid);
; #pragma unroll
;     for (int p = 0; p < 16; ++p) { p0[544 * p] = cmul(v[BR16[p]], wp); p1[544 * p] = cmul(u[BR16[p]], wp); wp = cmul(wp, w); }
	v_pk_mul_f32 v[76:77], v[98:99], v[94:95] op_sel:[1,1] op_sel_hi:[1,0] neg_lo:[1,0]
	v_pk_fma_f32 v[68:69], v[98:99], v[94:95], v[76:77] op_sel_hi:[0,1,1]
	ds_write_b64 v117, v[68:69] offset:4352
	v_pk_mul_f32 v[68:69], v[94:95], v[100:101] op_sel:[1,1] op_sel_hi:[1,0] neg_lo:[1,0]
	v_pk_fma_f32 v[76:77], v[94:95], v[100:101], v[68:69] op_sel_hi:[0,1,1]
	v_pk_mul_f32 v[94:95], v[70:71], v[76:77] op_sel:[1,1] op_sel_hi:[1,0] neg_lo:[1,0]
	v_pk_fma_f32 v[68:69], v[70:71], v[76:77], v[94:95] op_sel_hi:[0,1,1]
	ds_write_b64 v116, v[68:69] offset:8704
	v_pk_mul_f32 v[70:71], v[84:85], v[76:77] op_sel:[1,1] op_sel_hi:[1,0] neg_lo:[1,0]
	v_pk_fma_f32 v[68:69], v[84:85], v[76:77], v[70:71] op_sel_hi:[0,1,1]
	ds_write_b64 v117, v[68:69] offset:8704
	v_pk_mul_f32 v[68:69], v[76:77], v[100:101] op_sel:[1,1] op_sel_hi:[1,0] neg_lo:[1,0]
	v_pk_fma_f32 v[70:71], v[76:77], v[100:101], v[68:69] op_sel_hi:[0,1,1]
	v_pk_mul_f32 v[76:77], v[78:79], v[70:71] op_sel:[1,1] op_sel_hi:[1,0] neg_lo:[1,0]
	v_pk_fma_f32 v[68:69], v[78:79], v[70:71], v[76:77] op_sel_hi:[0,1,1]
	ds_write_b64 v116, v[68:69] offset:13056
	v_pk_mul_f32 v[76:77], v[90:91], v[70:71] op_sel:[1,1] op_sel_hi:[1,0] neg_lo:[1,0]
	v_pk_fma_f32 v[68:69], v[90:91], v[70:71], v[76:77] op_sel_hi:[0,1,1]
	ds_write_b64 v117, v[68:69] offset:13056
	v_pk_mul_f32 v[68:69], v[70:71], v[100:101] op_sel:[1,1] op_sel_hi:[1,0] neg_lo:[1,0]
	v_pk_fma_f32 v[70:71], v[70:71], v[100:101], v[68:69] op_sel_hi:[0,1,1]
	v_pk_mul_f32 v[68:69], v[16:17], v[70:71] op_sel:[1,1] op_sel_hi:[1,0] neg_lo:[1,0]
	v_pk_fma_f32 v[16:17], v[16:17], v[70:71], v[68:69] op_sel_hi:[0,1,1]
	ds_write_b64 v116, v[16:17] offset:17408
	v_pk_mul_f32 v[68:69], v[80:81], v[70:71] op_sel:[1,1] op_sel_hi:[1,0] neg_lo:[1,0]
	v_pk_fma_f32 v[16:17], v[80:81], v[70:71], v[68:69] op_sel_hi:[0,1,1]
	ds_write_b64 v117, v[16:17] offset:17408
	v_pk_mul_f32 v[16:17], v[70:71], v[100:101] op_sel:[1,1] op_sel_hi:[1,0] neg_lo:[1,0]
	v_pk_fma_f32 v[68:69], v[70:71], v[100:101], v[16:17] op_sel_hi:[0,1,1]
	v_pk_mul_f32 v[70:71], v[72:73], v[68:69] op_sel:[1,1] op_sel_hi:[1,0] neg_lo:[1,0]
	v_pk_fma_f32 v[16:17], v[72:73], v[68:69], v[70:71] op_sel_hi:[0,1,1]
	ds_write_b64 v116, v[16:17] offset:21760
	v_pk_mul_f32 v[70:71], v[86:87], v[68:69] op_sel:[1,1] op_sel_hi:[1,0] neg_lo:[1,0]
	v_pk_fma_f32 v[16:17], v[86:87], v[68:69], v[70:71] op_sel_hi:[0,1,1]
	ds_write_b64 v117, v[16:17] offset:21760
	v_pk_mul_f32 v[16:17], v[68:69], v[100:101] op_sel:[1,1] op_sel_hi:[1,0] neg_lo:[1,0]
	v_pk_fma_f32 v[68:69], v[68:69], v[100:101], v[16:17] op_sel_hi:[0,1,1]
	v_pk_mul_f32 v[70:71], v[18:19], v[68:69] op_sel:[1,1] op_sel_hi:[1,0] neg_lo:[1,0]
	v_pk_fma_f32 v[16:17], v[18:19], v[68:69], v[70:71] op_sel_hi:[0,1,1]
	ds_write_b64 v116, v[16:17] offset:26112
	v_pk_mul_f32 v[18:19], v[92:93], v[68:69] op_sel:[1,1] op_sel_hi:[1,0] neg_lo:[1,0]
	v_pk_fma_f32 v[16:17], v[92:93], v[68:69], v[18:19] op_sel_hi:[0,1,1]
	ds_write_b64 v117, v[16:17] offset:26112
	v_pk_mul_f32 v[16:17], v[68:69], v[100:101] op_sel:[1,1] op_sel_hi:[1,0] neg_lo:[1,0]
	v_pk_fma_f32 v[18:19], v[68:69], v[100:101], v[16:17] op_sel_hi:[0,1,1]
	v_pk_mul_f32 v[68:69], v[74:75], v[18:19] op_sel:[1,1] op_sel_hi:[1,0] neg_lo:[1,0]
	v_pk_fma_f32 v[16:17], v[74:75], v[18:19], v[68:69] op_sel_hi:[0,1,1]
	ds_write_b64 v116, v[16:17] offset:30464
	v_pk_mul_f32 v[68:69], v[82:83], v[18:19] op_sel:[1,1] op_sel_hi:[1,0] neg_lo:[1,0]
	v_pk_fma_f32 v[16:17], v[82:83], v[18:19], v[68:69] op_sel_hi:[0,1,1]
	ds_write_b64 v117, v[16:17] offset:30464
	v_pk_mul_f32 v[16:17], v[18:19], v[100:101] op_sel:[1,1] op_sel_hi:[1,0] neg_lo:[1,0]
	v_pk_fma_f32 v[18:19], v[18:19], v[100:101], v[16:17] op_sel_hi:[0,1,1]
	v_pk_mul_f32 v[16:17], v[4:5], v[18:19] op_sel:[1,1] op_sel_hi:[1,0] neg_lo:[1,0]
	v_pk_fma_f32 v[4:5], v[4:5], v[18:19], v[16:17] op_sel_hi:[0,1,1]
	ds_write_b64 v116, v[4:5] offset:34816
	v_pk_mul_f32 v[16:17], v[104:105], v[18:19] op_sel:[1,1] op_sel_hi:[1,0] neg_lo:[1,0]
	v_pk_fma_f32 v[4:5], v[104:105], v[18:19], v[16:17] op_sel_hi:[0,1,1]
	ds_write_b64 v117, v[4:5] offset:34816
	v_pk_mul_f32 v[4:5], v[18:19], v[100:101] op_sel:[1,1] op_sel_hi:[1,0] neg_lo:[1,0]
	v_pk_fma_f32 v[16:17], v[18:19], v[100:101], v[4:5] op_sel_hi:[0,1,1]
	v_pk_mul_f32 v[18:19], v[12:13], v[16:17] op_sel:[1,1] op_sel_hi:[1,0] neg_lo:[1,0]
	v_pk_fma_f32 v[4:5], v[12:13], v[16:17], v[18:19] op_sel_hi:[0,1,1]
	ds_write_b64 v116, v[4:5] offset:39168
	v_pk_mul_f32 v[12:13], v[88:89], v[16:17] op_sel:[1,1] op_sel_hi:[1,0] neg_lo:[1,0]
	v_pk_fma_f32 v[4:5], v[88:89], v[16:17], v[12:13] op_sel_hi:[0,1,1]
	ds_write_b64 v117, v[4:5] offset:39168
	v_pk_mul_f32 v[4:5], v[16:17], v[100:101] op_sel:[1,1] op_sel_hi:[1,0] neg_lo:[1,0]
	v_pk_fma_f32 v[12:13], v[16:17], v[100:101], v[4:5] op_sel_hi:[0,1,1]
	v_pk_mul_f32 v[16:17], v[6:7], v[12:13] op_sel:[1,1] op_sel_hi:[1,0] neg_lo:[1,0]
	v_pk_fma_f32 v[4:5], v[6:7], v[12:13], v[16:17] op_sel_hi:[0,1,1]
	ds_write_b64 v116, v[4:5] offset:43520
	v_pk_mul_f32 v[6:7], v[102:103], v[12:13] op_sel:[1,1] op_sel_hi:[1,0] neg_lo:[1,0]
	v_pk_fma_f32 v[4:5], v[102:103], v[12:13], v[6:7] op_sel_hi:[0,1,1]
	ds_write_b64 v117, v[4:5] offset:43520
	v_pk_mul_f32 v[4:5], v[12:13], v[100:101] op_sel:[1,1] op_sel_hi:[1,0] neg_lo:[1,0]
	v_pk_fma_f32 v[6:7], v[12:13], v[100:101], v[4:5] op_sel_hi:[0,1,1]
	v_pk_mul_f32 v[12:13], v[14:15], v[6:7] op_sel:[1,1] op_sel_hi:[1,0] neg_lo:[1,0]
	v_pk_fma_f32 v[4:5], v[14:15], v[6:7], v[12:13] op_sel_hi:[0,1,1]
	ds_write_b64 v116, v[4:5] offset:47872
	v_pk_mul_f32 v[12:13], v[96:97], v[6:7] op_sel:[1,1] op_sel_hi:[1,0] neg_lo:[1,0]
	v_pk_fma_f32 v[4:5], v[96:97], v[6:7], v[12:13] op_sel_hi:[0,1,1]
; #define LAS __attribute__((address_space(3)))
; #define SINCOSPI(x, s, c) do { const float hx_ = 0.5f * (x); *(s) = __builtin_amdgcn_sinf(hx_); *(c) = __builtin_amdgcn_cosf(hx_); } while (0)
; #define OPAQUE_I(x) asm volatile("" : "+v"(x))
; DEV void fft_f1x2(LAS cf* buf0, LAS cf* buf1, const cf (&z0)[8], const cf (&z1)[8], int tid) {
;     ...
;     float sn, cs; SINCOSPI(-(float)tid * (2.0f / 8192.0f), &sn, &cs);
;     const cf w = cf{cs, sn}; cf wp = cf{1.f, 0.f};
;     LAS cf* p0 = buf0 + PADI(tid); LAS cf* p1 = buf1 + PADI(tid);
; #pragma unroll
;     for (int p = 0; p < 16; ++p) { p0[544 * p] = cmul(v[BR16[p]], wp); p1[544 * p] = cmul(u[BR16[p]], wp); wp = cmul(wp, w); }
; DEV void fft_f2(LAS cf* buf, int t8) {
;     OPAQUE_I(t8);
;     LAS cf* pb = buf + (t8 >> 4) * 544 + (t8 & 15);
;     cf v[32];
; #pragma unroll
;     for (int q = 0; q < 32; ++q) v[q] = pb[17 * q];
;     dft_regs<32, false>(v);
;     float sn, cs; SINCOSPI(-(float)(t8 & 15) * (2.0f / 512.0f), &sn, &cs);
	ds_write_b64 v117, v[4:5] offset:47872
	v_pk_mul_f32 v[4:5], v[6:7], v[100:101] op_sel:[1,1] op_sel_hi:[1,0] neg_lo:[1,0]
	v_pk_fma_f32 v[6:7], v[6:7], v[100:101], v[4:5] op_sel_hi:[0,1,1]
	v_pk_mul_f32 v[4:5], v[0:1], v[6:7] op_sel:[1,1] op_sel_hi:[1,0] neg_lo:[1,0]
	v_pk_fma_f32 v[0:1], v[0:1], v[6:7], v[4:5] op_sel_hi:[0,1,1]
	ds_write_b64 v116, v[0:1] offset:52224
	v_pk_mul_f32 v[4:5], v[110:111], v[6:7] op_sel:[1,1] op_sel_hi:[1,0] neg_lo:[1,0]
	v_pk_fma_f32 v[0:1], v[110:111], v[6:7], v[4:5] op_sel_hi:[0,1,1]
	ds_write_b64 v117, v[0:1] offset:52224
	v_pk_mul_f32 v[0:1], v[6:7], v[100:101] op_sel:[1,1] op_sel_hi:[1,0] neg_lo:[1,0]
	v_pk_fma_f32 v[4:5], v[6:7], v[100:101], v[0:1] op_sel_hi:[0,1,1]
	v_pk_mul_f32 v[6:7], v[8:9], v[4:5] op_sel:[1,1] op_sel_hi:[1,0] neg_lo:[1,0]
	v_pk_fma_f32 v[0:1], v[8:9], v[4:5], v[6:7] op_sel_hi:[0,1,1]
	ds_write_b64 v116, v[0:1] offset:56576
	v_pk_mul_f32 v[6:7], v[108:109], v[4:5] op_sel:[1,1] op_sel_hi:[1,0] neg_lo:[1,0]
	v_pk_fma_f32 v[0:1], v[108:109], v[4:5], v[6:7] op_sel_hi:[0,1,1]
	ds_write_b64 v117, v[0:1] offset:56576
	v_pk_mul_f32 v[0:1], v[4:5], v[100:101] op_sel:[1,1] op_sel_hi:[1,0] neg_lo:[1,0]
	v_pk_fma_f32 v[4:5], v[4:5], v[100:101], v[0:1] op_sel_hi:[0,1,1]
	v_pk_mul_f32 v[6:7], v[2:3], v[4:5] op_sel:[1,1] op_sel_hi:[1,0] neg_lo:[1,0]
	v_pk_fma_f32 v[0:1], v[2:3], v[4:5], v[6:7] op_sel_hi:[0,1,1]
	ds_write_b64 v116, v[0:1] offset:60928
	v_pk_mul_f32 v[2:3], v[112:113], v[4:5] op_sel:[1,1] op_sel_hi:[1,0] neg_lo:[1,0]
	v_pk_fma_f32 v[0:1], v[112:113], v[4:5], v[2:3] op_sel_hi:[0,1,1]
	ds_write_b64 v117, v[0:1] offset:60928
	v_pk_mul_f32 v[0:1], v[4:5], v[100:101] op_sel:[1,1] op_sel_hi:[1,0] neg_lo:[1,0]
	v_pk_fma_f32 v[2:3], v[4:5], v[100:101], v[0:1] op_sel_hi:[0,1,1]
	v_pk_mul_f32 v[4:5], v[10:11], v[2:3] op_sel:[1,1] op_sel_hi:[1,0] neg_lo:[1,0]
	v_pk_fma_f32 v[0:1], v[10:11], v[2:3], v[4:5] op_sel_hi:[0,1,1]
	ds_write_b64 v116, v[0:1] offset:65280
	v_pk_mul_f32 v[4:5], v[106:107], v[2:3] op_sel:[1,1] op_sel_hi:[1,0] neg_lo:[1,0]
	v_pk_fma_f32 v[0:1], v[106:107], v[2:3], v[4:5] op_sel_hi:[0,1,1]
	ds_write_b64 v117, v[0:1] offset:65280
	v_mov_b32_e32 v0, v160
	s_waitcnt lgkmcnt(0)
	s_barrier
	s_nop 0
	v_lshrrev_b32_e32 v1, 4, v0
	v_and_b32_e32 v3, 15, v0
	v_mul_lo_u32 v1, v1, s15
	v_lshlrev_b32_e32 v0, 3, v3
	v_add3_u32 v2, v159, v1, v0
	ds_read2_b64 v[4:7], v2 offset1:17
	ds_read2_b64 v[8:11], v2 offset0:34 offset1:51
	ds_read2_b64 v[12:15], v2 offset0:68 offset1:85
	ds_read2_b64 v[16:19], v2 offset0:102 offset1:119
	ds_read2_b64 v[68:71], v2 offset0:136 offset1:153
	ds_read2_b64 v[72:75], v2 offset0:170 offset1:187
	ds_read2_b64 v[76:79], v2 offset0:204 offset1:221
	ds_read2_b64 v[80:83], v2 offset0:238 offset1:255
	v_add_u32_e32 v0, 0x800, v2
	ds_read2_b64 v[84:87], v0 offset0:16 offset1:33
	ds_read2_b64 v[88:91], v0 offset0:50 offset1:67
	ds_read2_b64 v[92:95], v0 offset0:84 offset1:101
	ds_read2_b64 v[96:99], v0 offset0:118 offset1:135
	ds_read2_b64 v[100:103], v0 offset0:152 offset1:169
	ds_read2_b64 v[104:107], v0 offset0:186 offset1:203
	ds_read2_b64 v[108:111], v0 offset0:220 offset1:237
	s_waitcnt lgkmcnt(6)
	v_pk_add_f32 v[116:117], v[4:5], v[84:85]
	v_pk_add_f32 v[4:5], v[4:5], v[84:85] neg_lo:[0,1] neg_hi:[0,1]
	v_add_u32_e32 v1, 0xc00, v2
	v_pk_mul_f32 v[84:85], v[4:5], 0 op_sel_hi:[1,0]
	ds_read2_b64 v[112:115], v1 offset0:126 offset1:143
	v_pk_add_f32 v[118:119], v[4:5], v[84:85] op_sel:[0,1] op_sel_hi:[1,0] neg_lo:[0,1] neg_hi:[0,1]
	v_pk_add_f32 v[4:5], v[4:5], v[84:85] op_sel:[0,1] op_sel_hi:[1,0]
	v_cvt_f32_ubyte0_e32 v3, v3
	v_mov_b32_e32 v119, v5
	v_pk_add_f32 v[4:5], v[6:7], v[86:87]
	v_pk_add_f32 v[6:7], v[6:7], v[86:87] neg_lo:[0,1] neg_hi:[0,1]
	v_mul_f32_e32 v3, 0xbb800000, v3
	v_pk_mul_f32 v[84:85], v[6:7], s[82:83] op_sel_hi:[1,0]
	v_mul_f32_e32 v3, 0.5, v3
	v_pk_fma_f32 v[86:87], v[6:7], s[94:95], v[84:85] op_sel:[0,0,1] op_sel_hi:[1,0,0]
	v_pk_fma_f32 v[6:7], v[6:7], s[94:95], v[84:85] op_sel:[0,0,1] op_sel_hi:[1,0,0] neg_lo:[0,0,1] neg_hi:[0,0,1]
	v_mov_b32_e32 v87, v7
	s_waitcnt lgkmcnt(6)
	v_pk_add_f32 v[6:7], v[8:9], v[88:89]
	v_pk_add_f32 v[8:9], v[8:9], v[88:89] neg_lo:[0,1] neg_hi:[0,1]
	v_pk_mul_f32 v[84:85], v[8:9], s[84:85] op_sel_hi:[1,0]
	v_pk_fma_f32 v[88:89], v[8:9], s[16:17], v[84:85] op_sel:[0,0,1] op_sel_hi:[1,0,0]
	v_pk_fma_f32 v[8:9], v[8:9], s[16:17], v[84:85] op_sel:[0,0,1] op_sel_hi:[1,0,0] neg_lo:[0,0,1] neg_hi:[0,0,1]
	v_mov_b32_e32 v89, v9
	v_pk_add_f32 v[8:9], v[10:11], v[90:91]
	v_pk_add_f32 v[10:11], v[10:11], v[90:91] neg_lo:[0,1] neg_hi:[0,1]
	v_pk_mul_f32 v[84:85], v[10:11], s[4:5] op_sel_hi:[1,0]
	v_pk_fma_f32 v[90:91], v[10:11], s[86:87], v[84:85] op_sel:[0,0,1] op_sel_hi:[1,0,0]
	v_pk_fma_f32 v[10:11], v[10:11], s[86:87], v[84:85] op_sel:[0,0,1] op_sel_hi:[1,0,0] neg_lo:[0,0,1] neg_hi:[0,0,1]
	v_mov_b32_e32 v91, v11
	s_waitcnt lgkmcnt(5)
	v_pk_add_f32 v[10:11], v[12:13], v[92:93]
	v_pk_add_f32 v[12:13], v[12:13], v[92:93] neg_lo:[0,1] neg_hi:[0,1]
	v_pk_mul_f32 v[84:85], v[12:13], s[18:19] op_sel_hi:[1,0]
	v_pk_fma_f32 v[92:93], v[12:13], s[18:19], v[84:85] op_sel:[0,0,1] op_sel_hi:[1,0,0]
	v_pk_fma_f32 v[12:13], v[12:13], s[18:19], v[84:85] op_sel_hi:[1,0,0] neg_lo:[0,0,1] neg_hi:[0,0,1]
	v_mov_b32_e32 v93, v13
	v_pk_add_f32 v[12:13], v[14:15], v[94:95]
	v_pk_add_f32 v[14:15], v[14:15], v[94:95] neg_lo:[0,1] neg_hi:[0,1]
	v_pk_mul_f32 v[84:85], v[14:15], s[86:87] op_sel_hi:[1,0]
	v_pk_fma_f32 v[94:95], v[14:15], s[4:5], v[84:85] op_sel:[0,0,1] op_sel_hi:[1,0,0]
	v_pk_fma_f32 v[14:15], v[14:15], s[4:5], v[84:85] op_sel:[0,0,1] op_sel_hi:[1,0,0] neg_lo:[0,0,1] neg_hi:[0,0,1]
	s_mov_b32 s5, s86
	v_mov_b32_e32 v95, v15
	s_waitcnt lgkmcnt(4)
; #define SINCOSPI(x, s, c) do { const float hx_ = 0.5f * (x); *(s) = __builtin_amdgcn_sinf(hx_); *(c) = __builtin_amdgcn_cosf(hx_); } while (0)
; template <int R, bool INV> DEV void dft_regs(cf (&v)[R]) {
; #pragma unroll
;     for (int s = R; s >= 2; s >>= 1) {
;         const int h = s >> 1;
; #pragma unroll
;         for (int b = 0; b < R; b += s) {
; #pragma unroll
;             for (int k = 0; k < h; ++k) {
;                 const cf a = v[b + k], c = v[b + k + h];
;                 v[b + k] = a + c;
;                 const cf d = a - c;
;                 const int m = k * (32 / s);
;                 const float wr = tw_cos(m), wi = INV ? tw_sin(m) : -tw_sin(m);
;                 v[b + k + h] = cf{d.x * wr - d.y * wi, d.x * wi + d.y * wr};
;             }
;         }
;     }
; DEV void fft_f2(LAS cf* buf, int t8) {
;     ...
;     for (int q = 0; q < 32; ++q) v[q] = pb[17 * q];
;     dft_regs<32, false>(v);
;     float sn, cs; SINCOSPI(-(float)(t8 & 15) * (2.0f / 512.0f), &sn, &cs);
	v_pk_add_f32 v[14:15], v[16:17], v[96:97]
	v_pk_add_f32 v[16:17], v[16:17], v[96:97] neg_lo:[0,1] neg_hi:[0,1]
	v_pk_mul_f32 v[84:85], v[16:17], s[16:17] op_sel_hi:[1,0]
	v_pk_fma_f32 v[96:97], v[16:17], s[84:85], v[84:85] op_sel:[0,0,1] op_sel_hi:[1,0,0]
	v_pk_fma_f32 v[16:17], v[16:17], s[84:85], v[84:85] op_sel:[0,0,1] op_sel_hi:[1,0,0] neg_lo:[0,0,1] neg_hi:[0,0,1]
	v_mov_b32_e32 v97, v17
	v_pk_add_f32 v[16:17], v[18:19], v[98:99]
	v_pk_add_f32 v[18:19], v[18:19], v[98:99] neg_lo:[0,1] neg_hi:[0,1]
	v_pk_mul_f32 v[84:85], v[18:19], s[94:95] op_sel_hi:[1,0]
	v_pk_fma_f32 v[98:99], v[18:19], s[82:83], v[84:85] op_sel:[0,0,1] op_sel_hi:[1,0,0]
	v_pk_fma_f32 v[18:19], v[18:19], s[82:83], v[84:85] op_sel:[0,0,1] op_sel_hi:[1,0,0] neg_lo:[0,0,1] neg_hi:[0,0,1]
	s_mov_b32 s83, s94
	v_mov_b32_e32 v99, v19
	s_waitcnt lgkmcnt(3)
	v_pk_add_f32 v[18:19], v[68:69], v[100:101]
	v_pk_add_f32 v[68:69], v[68:69], v[100:101] neg_lo:[0,1] neg_hi:[0,1]
	v_pk_fma_f32 v[84:85], v[68:69], 0, v[68:69] op_sel:[0,0,1] op_sel_hi:[1,0,0]
	v_pk_fma_f32 v[68:69], v[68:69], 0, v[68:69] op_sel:[0,0,1] op_sel_hi:[1,0,0] neg_lo:[0,0,1] neg_hi:[0,0,1]
	v_mov_b32_e32 v85, v69
	v_pk_add_f32 v[68:69], v[70:71], v[102:103]
	v_pk_add_f32 v[70:71], v[70:71], v[102:103] neg_lo:[0,1] neg_hi:[0,1]
	v_pk_mul_f32 v[100:101], v[70:71], s[82:83] op_sel_hi:[0,1]
	v_pk_fma_f32 v[70:71], v[70:71], s[94:95], v[100:101] op_sel:[1,0,0] neg_lo:[0,0,1] neg_hi:[0,0,1]
	s_waitcnt lgkmcnt(2)
	v_pk_add_f32 v[100:101], v[72:73], v[104:105]
	v_pk_add_f32 v[72:73], v[72:73], v[104:105] neg_lo:[0,1] neg_hi:[0,1]
	v_pk_mul_f32 v[102:103], v[72:73], s[84:85] op_sel_hi:[0,1]
	v_pk_fma_f32 v[72:73], v[72:73], s[30:31], v[102:103] op_sel:[1,0,0] neg_lo:[0,0,1] neg_hi:[0,0,1]
	v_pk_add_f32 v[102:103], v[74:75], v[106:107]
	v_pk_add_f32 v[74:75], v[74:75], v[106:107] neg_lo:[0,1] neg_hi:[0,1]
	v_pk_mul_f32 v[104:105], v[74:75], s[4:5] op_sel_hi:[0,1]
	v_pk_fma_f32 v[74:75], v[74:75], s[86:87], v[104:105] op_sel:[1,0,0] neg_lo:[0,0,1] neg_hi:[0,0,1]
	s_waitcnt lgkmcnt(1)
	v_pk_add_f32 v[104:105], v[76:77], v[108:109]
	v_pk_add_f32 v[76:77], v[76:77], v[108:109] neg_lo:[0,1] neg_hi:[0,1]
	v_mul_f32_e32 v106, 0x3f3504f3, v76
	v_pk_fma_f32 v[76:77], v[76:77], s[28:29], v[106:107] op_sel:[1,0,0] op_sel_hi:[1,1,0] neg_lo:[0,0,1] neg_hi:[0,0,1]
	v_pk_add_f32 v[106:107], v[78:79], v[110:111]
	v_pk_add_f32 v[78:79], v[78:79], v[110:111] neg_lo:[0,1] neg_hi:[0,1]
	v_pk_mul_f32 v[108:109], v[78:79], s[2:3] op_sel_hi:[0,1]
	v_pk_fma_f32 v[78:79], v[78:79], s[10:11], v[108:109] op_sel:[1,0,0] neg_lo:[0,0,1] neg_hi:[0,0,1]
	s_waitcnt lgkmcnt(0)
	v_pk_add_f32 v[108:109], v[80:81], v[112:113]
	v_pk_add_f32 v[80:81], v[80:81], v[112:113] neg_lo:[0,1] neg_hi:[0,1]
	v_pk_mul_f32 v[110:111], v[80:81], s[24:25] op_sel_hi:[0,1]
	v_pk_fma_f32 v[80:81], v[80:81], s[34:35], v[110:111] op_sel:[1,0,0] neg_lo:[0,0,1] neg_hi:[0,0,1]
	v_pk_add_f32 v[110:111], v[82:83], v[114:115]
	v_pk_add_f32 v[82:83], v[82:83], v[114:115] neg_lo:[0,1] neg_hi:[0,1]
	v_pk_mul_f32 v[112:113], v[82:83], s[6:7] op_sel_hi:[0,1]
	v_pk_fma_f32 v[82:83], v[82:83], s[8:9], v[112:113] op_sel:[1,0,0] neg_lo:[0,0,1] neg_hi:[0,0,1]
	v_pk_add_f32 v[112:113], v[116:117], v[18:19]
	v_pk_add_f32 v[18:19], v[116:117], v[18:19] neg_lo:[0,1] neg_hi:[0,1]
	v_pk_mul_f32 v[114:115], v[18:19], 0 op_sel_hi:[1,0]
	v_pk_add_f32 v[116:117], v[18:19], v[114:115] op_sel:[0,1] op_sel_hi:[1,0] neg_lo:[0,1] neg_hi:[0,1]
	v_pk_add_f32 v[18:19], v[18:19], v[114:115] op_sel:[0,1] op_sel_hi:[1,0]
	v_mov_b32_e32 v117, v19
	v_pk_add_f32 v[18:19], v[4:5], v[68:69]
	v_pk_add_f32 v[4:5], v[4:5], v[68:69] neg_lo:[0,1] neg_hi:[0,1]
	v_pk_mul_f32 v[68:69], v[4:5], s[84:85] op_sel_hi:[1,0]
	v_pk_fma_f32 v[114:115], v[4:5], s[16:17], v[68:69] op_sel:[0,0,1] op_sel_hi:[1,0,0]
	v_pk_fma_f32 v[4:5], v[4:5], s[16:17], v[68:69] op_sel:[0,0,1] op_sel_hi:[1,0,0] neg_lo:[0,0,1] neg_hi:[0,0,1]
	v_mov_b32_e32 v115, v5
	v_pk_add_f32 v[4:5], v[6:7], v[100:101]
	v_pk_add_f32 v[6:7], v[6:7], v[100:101] neg_lo:[0,1] neg_hi:[0,1]
	v_pk_mul_f32 v[68:69], v[6:7], s[18:19] op_sel_hi:[1,0]
	v_pk_fma_f32 v[100:101], v[6:7], s[18:19], v[68:69] op_sel:[0,0,1] op_sel_hi:[1,0,0]
	v_pk_fma_f32 v[6:7], v[6:7], s[18:19], v[68:69] op_sel_hi:[1,0,0] neg_lo:[0,0,1] neg_hi:[0,0,1]
	v_mov_b32_e32 v101, v7
	v_pk_add_f32 v[6:7], v[8:9], v[102:103]
	v_pk_add_f32 v[8:9], v[8:9], v[102:103] neg_lo:[0,1] neg_hi:[0,1]
	v_pk_mul_f32 v[68:69], v[8:9], s[16:17] op_sel_hi:[1,0]
	v_pk_fma_f32 v[102:103], v[8:9], s[84:85], v[68:69] op_sel:[0,0,1] op_sel_hi:[1,0,0]
	v_pk_fma_f32 v[8:9], v[8:9], s[84:85], v[68:69] op_sel:[0,0,1] op_sel_hi:[1,0,0] neg_lo:[0,0,1] neg_hi:[0,0,1]
	v_mov_b32_e32 v103, v9
	v_pk_add_f32 v[8:9], v[10:11], v[104:105]
	v_pk_add_f32 v[10:11], v[10:11], v[104:105] neg_lo:[0,1] neg_hi:[0,1]
	v_pk_fma_f32 v[68:69], v[10:11], 0, v[10:11] op_sel:[0,0,1] op_sel_hi:[1,0,0]
	v_pk_fma_f32 v[10:11], v[10:11], 0, v[10:11] op_sel:[0,0,1] op_sel_hi:[1,0,0] neg_lo:[0,0,1] neg_hi:[0,0,1]
	v_mov_b32_e32 v69, v11
	v_pk_add_f32 v[10:11], v[12:13], v[106:107]
	v_pk_add_f32 v[12:13], v[12:13], v[106:107] neg_lo:[0,1] neg_hi:[0,1]
	v_pk_mul_f32 v[104:105], v[12:13], s[84:85] op_sel_hi:[0,1]
	v_pk_fma_f32 v[12:13], v[12:13], s[30:31], v[104:105] op_sel:[1,0,0] neg_lo:[0,0,1] neg_hi:[0,0,1]
	v_pk_add_f32 v[104:105], v[14:15], v[108:109]
	v_pk_add_f32 v[14:15], v[14:15], v[108:109] neg_lo:[0,1] neg_hi:[0,1]
	v_mul_f32_e32 v106, 0x3f3504f3, v14
	v_pk_fma_f32 v[14:15], v[14:15], s[28:29], v[106:107] op_sel:[1,0,0] op_sel_hi:[1,1,0] neg_lo:[0,0,1] neg_hi:[0,0,1]
	v_pk_add_f32 v[106:107], v[16:17], v[110:111]
; template <int R, bool INV> DEV void dft_regs(cf (&v)[R]) {
; #pragma unroll
;     for (int s = R; s >= 2; s >>= 1) {
;         const int h = s >> 1;
; #pragma unroll
;         for (int b = 0; b < R; b += s) {
; #pragma unroll
;             for (int k = 0; k < h; ++k) {
;                 const cf a = v[b + k], c = v[b + k + h];
;                 v[b + k] = a + c;
;                 const cf d = a - c;
;                 const int m = k * (32 / s);
;                 const float wr = tw_cos(m), wi = INV ? tw_sin(m) : -tw_sin(m);
;                 v[b + k + h] = cf{d.x * wr - d.y * wi, d.x * wi + d.y * wr};
;             }
;         }
;     }
	v_pk_add_f32 v[16:17], v[16:17], v[110:111] neg_lo:[0,1] neg_hi:[0,1]
	v_pk_mul_f32 v[108:109], v[16:17], s[24:25] op_sel_hi:[0,1]
	v_pk_fma_f32 v[16:17], v[16:17], s[34:35], v[108:109] op_sel:[1,0,0] neg_lo:[0,0,1] neg_hi:[0,0,1]
	v_pk_add_f32 v[108:109], v[118:119], v[84:85]
	v_pk_add_f32 v[84:85], v[118:119], v[84:85] neg_lo:[0,1] neg_hi:[0,1]
	v_pk_mul_f32 v[110:111], v[84:85], 0 op_sel_hi:[1,0]
	v_pk_add_f32 v[118:119], v[84:85], v[110:111] op_sel:[0,1] op_sel_hi:[1,0] neg_lo:[0,1] neg_hi:[0,1]
	v_pk_add_f32 v[84:85], v[84:85], v[110:111] op_sel:[0,1] op_sel_hi:[1,0]
	v_mov_b32_e32 v119, v85
	v_pk_add_f32 v[84:85], v[86:87], v[70:71]
	v_pk_add_f32 v[70:71], v[86:87], v[70:71] neg_lo:[0,1] neg_hi:[0,1]
	v_pk_mul_f32 v[86:87], v[70:71], s[84:85] op_sel_hi:[1,0]
	v_pk_fma_f32 v[110:111], v[70:71], s[16:17], v[86:87] op_sel:[0,0,1] op_sel_hi:[1,0,0]
	v_pk_fma_f32 v[70:71], v[70:71], s[16:17], v[86:87] op_sel:[0,0,1] op_sel_hi:[1,0,0] neg_lo:[0,0,1] neg_hi:[0,0,1]
	v_mov_b32_e32 v111, v71
	v_pk_add_f32 v[70:71], v[88:89], v[72:73]
	v_pk_add_f32 v[72:73], v[88:89], v[72:73] neg_lo:[0,1] neg_hi:[0,1]
	v_pk_mul_f32 v[86:87], v[72:73], s[18:19] op_sel_hi:[1,0]
	v_pk_fma_f32 v[88:89], v[72:73], s[18:19], v[86:87] op_sel:[0,0,1] op_sel_hi:[1,0,0]
	v_pk_fma_f32 v[72:73], v[72:73], s[18:19], v[86:87] op_sel_hi:[1,0,0] neg_lo:[0,0,1] neg_hi:[0,0,1]
	v_mov_b32_e32 v89, v73
	v_pk_add_f32 v[72:73], v[90:91], v[74:75]
	v_pk_add_f32 v[74:75], v[90:91], v[74:75] neg_lo:[0,1] neg_hi:[0,1]
	v_pk_mul_f32 v[86:87], v[74:75], s[16:17] op_sel_hi:[1,0]
	v_pk_fma_f32 v[90:91], v[74:75], s[84:85], v[86:87] op_sel:[0,0,1] op_sel_hi:[1,0,0]
	v_pk_fma_f32 v[74:75], v[74:75], s[84:85], v[86:87] op_sel:[0,0,1] op_sel_hi:[1,0,0] neg_lo:[0,0,1] neg_hi:[0,0,1]
	v_mov_b32_e32 v91, v75
	v_pk_add_f32 v[74:75], v[92:93], v[76:77]
	v_pk_add_f32 v[76:77], v[92:93], v[76:77] neg_lo:[0,1] neg_hi:[0,1]
	v_pk_fma_f32 v[86:87], v[76:77], 0, v[76:77] op_sel:[0,0,1] op_sel_hi:[1,0,0]
	v_pk_fma_f32 v[76:77], v[76:77], 0, v[76:77] op_sel:[0,0,1] op_sel_hi:[1,0,0] neg_lo:[0,0,1] neg_hi:[0,0,1]
	v_mov_b32_e32 v87, v77
	v_pk_add_f32 v[76:77], v[94:95], v[78:79]
	v_pk_add_f32 v[78:79], v[94:95], v[78:79] neg_lo:[0,1] neg_hi:[0,1]
	v_pk_mul_f32 v[92:93], v[78:79], s[84:85] op_sel_hi:[0,1]
	v_pk_fma_f32 v[78:79], v[78:79], s[30:31], v[92:93] op_sel:[1,0,0] neg_lo:[0,0,1] neg_hi:[0,0,1]
	v_pk_add_f32 v[92:93], v[96:97], v[80:81]
	v_pk_add_f32 v[80:81], v[96:97], v[80:81] neg_lo:[0,1] neg_hi:[0,1]
	v_mul_f32_e32 v94, 0x3f3504f3, v80
	v_pk_fma_f32 v[80:81], v[80:81], s[28:29], v[94:95] op_sel:[1,0,0] op_sel_hi:[1,1,0] neg_lo:[0,0,1] neg_hi:[0,0,1]
	v_pk_add_f32 v[94:95], v[98:99], v[82:83]
	v_pk_add_f32 v[82:83], v[98:99], v[82:83] neg_lo:[0,1] neg_hi:[0,1]
	v_pk_mul_f32 v[96:97], v[82:83], s[24:25] op_sel_hi:[0,1]
	v_pk_fma_f32 v[82:83], v[82:83], s[34:35], v[96:97] op_sel:[1,0,0] neg_lo:[0,0,1] neg_hi:[0,0,1]
	v_pk_add_f32 v[96:97], v[112:113], v[8:9]
	v_pk_add_f32 v[8:9], v[112:113], v[8:9] neg_lo:[0,1] neg_hi:[0,1]
	v_pk_mul_f32 v[98:99], v[8:9], 0 op_sel_hi:[1,0]
	v_pk_add_f32 v[112:113], v[8:9], v[98:99] op_sel:[0,1] op_sel_hi:[1,0] neg_lo:[0,1] neg_hi:[0,1]
	v_pk_add_f32 v[8:9], v[8:9], v[98:99] op_sel:[0,1] op_sel_hi:[1,0]
	v_mov_b32_e32 v113, v9
	v_pk_add_f32 v[8:9], v[18:19], v[10:11]
	v_pk_add_f32 v[10:11], v[18:19], v[10:11] neg_lo:[0,1] neg_hi:[0,1]
	v_pk_mul_f32 v[18:19], v[10:11], s[18:19] op_sel_hi:[1,0]
	v_pk_fma_f32 v[98:99], v[10:11], s[18:19], v[18:19] op_sel:[0,0,1] op_sel_hi:[1,0,0]
	v_pk_fma_f32 v[10:11], v[10:11], s[18:19], v[18:19] op_sel_hi:[1,0,0] neg_lo:[0,0,1] neg_hi:[0,0,1]
	v_mov_b32_e32 v99, v11
	v_pk_add_f32 v[10:11], v[4:5], v[104:105]
	v_pk_add_f32 v[4:5], v[4:5], v[104:105] neg_lo:[0,1] neg_hi:[0,1]
	v_pk_fma_f32 v[18:19], v[4:5], 0, v[4:5] op_sel:[0,0,1] op_sel_hi:[1,0,0]
	v_pk_fma_f32 v[4:5], v[4:5], 0, v[4:5] op_sel:[0,0,1] op_sel_hi:[1,0,0] neg_lo:[0,0,1] neg_hi:[0,0,1]
	v_mov_b32_e32 v19, v5
	v_pk_add_f32 v[4:5], v[6:7], v[106:107]
	v_pk_add_f32 v[6:7], v[6:7], v[106:107] neg_lo:[0,1] neg_hi:[0,1]
	v_mul_f32_e32 v104, 0x3f3504f3, v6
	v_pk_fma_f32 v[6:7], v[6:7], s[28:29], v[104:105] op_sel:[1,0,0] op_sel_hi:[1,1,0] neg_lo:[0,0,1] neg_hi:[0,0,1]
	v_pk_add_f32 v[104:105], v[116:117], v[68:69]
	v_pk_add_f32 v[68:69], v[116:117], v[68:69] neg_lo:[0,1] neg_hi:[0,1]
	v_pk_mul_f32 v[106:107], v[68:69], 0 op_sel_hi:[1,0]
	v_pk_add_f32 v[116:117], v[68:69], v[106:107] op_sel:[0,1] op_sel_hi:[1,0] neg_lo:[0,1] neg_hi:[0,1]
	v_pk_add_f32 v[68:69], v[68:69], v[106:107] op_sel:[0,1] op_sel_hi:[1,0]
	v_mov_b32_e32 v117, v69
	v_pk_add_f32 v[68:69], v[114:115], v[12:13]
	v_pk_add_f32 v[12:13], v[114:115], v[12:13] neg_lo:[0,1] neg_hi:[0,1]
	v_pk_mul_f32 v[106:107], v[12:13], s[18:19] op_sel_hi:[1,0]
	v_pk_fma_f32 v[114:115], v[12:13], s[18:19], v[106:107] op_sel:[0,0,1] op_sel_hi:[1,0,0]
	v_pk_fma_f32 v[12:13], v[12:13], s[18:19], v[106:107] op_sel_hi:[1,0,0] neg_lo:[0,0,1] neg_hi:[0,0,1]
	v_mov_b32_e32 v115, v13
	v_pk_add_f32 v[12:13], v[100:101], v[14:15]
	v_pk_add_f32 v[14:15], v[100:101], v[14:15] neg_lo:[0,1] neg_hi:[0,1]
	v_pk_fma_f32 v[100:101], v[14:15], 0, v[14:15] op_sel:[0,0,1] op_sel_hi:[1,0,0]
	v_pk_fma_f32 v[14:15], v[14:15], 0, v[14:15] op_sel:[0,0,1] op_sel_hi:[1,0,0] neg_lo:[0,0,1] neg_hi:[0,0,1]
	v_mov_b32_e32 v101, v15
	v_pk_add_f32 v[14:15], v[102:103], v[16:17]
	v_pk_add_f32 v[16:17], v[102:103], v[16:17] neg_lo:[0,1] neg_hi:[0,1]
	v_mul_f32_e32 v102, 0x3f3504f3, v16
	v_pk_fma_f32 v[16:17], v[16:17], s[28:29], v[102:103] op_sel:[1,0,0] op_sel_hi:[1,1,0] neg_lo:[0,0,1] neg_hi:[0,0,1]
	v_pk_add_f32 v[102:103], v[108:109], v[74:75]
; template <int R, bool INV> DEV void dft_regs(cf (&v)[R]) {
; #pragma unroll
;     for (int s = R; s >= 2; s >>= 1) {
;         const int h = s >> 1;
; #pragma unroll
;         for (int b = 0; b < R; b += s) {
; #pragma unroll
;             for (int k = 0; k < h; ++k) {
;                 const cf a = v[b + k], c = v[b + k + h];
;                 v[b + k] = a + c;
;                 const cf d = a - c;
;                 const int m = k * (32 / s);
;                 const float wr = tw_cos(m), wi = INV ? tw_sin(m) : -tw_sin(m);
;                 v[b + k + h] = cf{d.x * wr - d.y * wi, d.x * wi + d.y * wr};
;             }
;         }
;     }
	v_pk_add_f32 v[74:75], v[108:109], v[74:75] neg_lo:[0,1] neg_hi:[0,1]
	v_pk_mul_f32 v[106:107], v[74:75], 0 op_sel_hi:[1,0]
	v_pk_add_f32 v[108:109], v[74:75], v[106:107] op_sel:[0,1] op_sel_hi:[1,0] neg_lo:[0,1] neg_hi:[0,1]
	v_pk_add_f32 v[74:75], v[74:75], v[106:107] op_sel:[0,1] op_sel_hi:[1,0]
	v_mov_b32_e32 v109, v75
	v_pk_add_f32 v[74:75], v[84:85], v[76:77]
	v_pk_add_f32 v[76:77], v[84:85], v[76:77] neg_lo:[0,1] neg_hi:[0,1]
	v_pk_mul_f32 v[84:85], v[76:77], s[18:19] op_sel_hi:[1,0]
	v_pk_fma_f32 v[106:107], v[76:77], s[18:19], v[84:85] op_sel:[0,0,1] op_sel_hi:[1,0,0]
	v_pk_fma_f32 v[76:77], v[76:77], s[18:19], v[84:85] op_sel_hi:[1,0,0] neg_lo:[0,0,1] neg_hi:[0,0,1]
	v_mov_b32_e32 v107, v77
	v_pk_add_f32 v[76:77], v[70:71], v[92:93]
	v_pk_add_f32 v[70:71], v[70:71], v[92:93] neg_lo:[0,1] neg_hi:[0,1]
	v_pk_fma_f32 v[84:85], v[70:71], 0, v[70:71] op_sel:[0,0,1] op_sel_hi:[1,0,0]
	v_pk_fma_f32 v[70:71], v[70:71], 0, v[70:71] op_sel:[0,0,1] op_sel_hi:[1,0,0] neg_lo:[0,0,1] neg_hi:[0,0,1]
	v_mov_b32_e32 v85, v71
	v_pk_add_f32 v[70:71], v[72:73], v[94:95]
	v_pk_add_f32 v[72:73], v[72:73], v[94:95] neg_lo:[0,1] neg_hi:[0,1]
	v_mul_f32_e32 v92, 0x3f3504f3, v72
	v_pk_fma_f32 v[72:73], v[72:73], s[28:29], v[92:93] op_sel:[1,0,0] op_sel_hi:[1,1,0] neg_lo:[0,0,1] neg_hi:[0,0,1]
	v_pk_add_f32 v[92:93], v[118:119], v[86:87]
	v_pk_add_f32 v[86:87], v[118:119], v[86:87] neg_lo:[0,1] neg_hi:[0,1]
	v_pk_mul_f32 v[94:95], v[86:87], 0 op_sel_hi:[1,0]
	v_pk_add_f32 v[118:119], v[86:87], v[94:95] op_sel:[0,1] op_sel_hi:[1,0] neg_lo:[0,1] neg_hi:[0,1]
	v_pk_add_f32 v[86:87], v[86:87], v[94:95] op_sel:[0,1] op_sel_hi:[1,0]
	v_mov_b32_e32 v119, v87
	v_pk_add_f32 v[86:87], v[110:111], v[78:79]
	v_pk_add_f32 v[78:79], v[110:111], v[78:79] neg_lo:[0,1] neg_hi:[0,1]
	v_pk_mul_f32 v[94:95], v[78:79], s[18:19] op_sel_hi:[1,0]
	v_pk_fma_f32 v[110:111], v[78:79], s[18:19], v[94:95] op_sel:[0,0,1] op_sel_hi:[1,0,0]
	v_pk_fma_f32 v[78:79], v[78:79], s[18:19], v[94:95] op_sel_hi:[1,0,0] neg_lo:[0,0,1] neg_hi:[0,0,1]
	v_mov_b32_e32 v111, v79
	v_pk_add_f32 v[78:79], v[88:89], v[80:81]
	v_pk_add_f32 v[80:81], v[88:89], v[80:81] neg_lo:[0,1] neg_hi:[0,1]
	v_pk_fma_f32 v[88:89], v[80:81], 0, v[80:81] op_sel:[0,0,1] op_sel_hi:[1,0,0]
	v_pk_fma_f32 v[80:81], v[80:81], 0, v[80:81] op_sel:[0,0,1] op_sel_hi:[1,0,0] neg_lo:[0,0,1] neg_hi:[0,0,1]
	v_mov_b32_e32 v89, v81
	v_pk_add_f32 v[80:81], v[90:91], v[82:83]
	v_pk_add_f32 v[82:83], v[90:91], v[82:83] neg_lo:[0,1] neg_hi:[0,1]
	v_mul_f32_e32 v90, 0x3f3504f3, v82
	v_pk_fma_f32 v[82:83], v[82:83], s[28:29], v[90:91] op_sel:[1,0,0] op_sel_hi:[1,1,0] neg_lo:[0,0,1] neg_hi:[0,0,1]
	v_pk_add_f32 v[90:91], v[96:97], v[10:11]
	v_pk_add_f32 v[10:11], v[96:97], v[10:11] neg_lo:[0,1] neg_hi:[0,1]
	v_pk_mul_f32 v[94:95], v[10:11], 0 op_sel_hi:[1,0]
	v_pk_add_f32 v[96:97], v[10:11], v[94:95] op_sel:[0,1] op_sel_hi:[1,0] neg_lo:[0,1] neg_hi:[0,1]
	v_pk_add_f32 v[10:11], v[10:11], v[94:95] op_sel:[0,1] op_sel_hi:[1,0]
	v_mov_b32_e32 v97, v11
	v_pk_add_f32 v[10:11], v[8:9], v[4:5]
	v_pk_add_f32 v[4:5], v[8:9], v[4:5] neg_lo:[0,1] neg_hi:[0,1]
	v_pk_fma_f32 v[8:9], v[4:5], 0, v[4:5] op_sel:[0,0,1] op_sel_hi:[1,0,0]
	v_pk_fma_f32 v[4:5], v[4:5], 0, v[4:5] op_sel:[0,0,1] op_sel_hi:[1,0,0] neg_lo:[0,0,1] neg_hi:[0,0,1]
	v_mov_b32_e32 v9, v5
	v_pk_add_f32 v[4:5], v[112:113], v[18:19]
	v_pk_add_f32 v[18:19], v[112:113], v[18:19] neg_lo:[0,1] neg_hi:[0,1]
	v_pk_mul_f32 v[94:95], v[18:19], 0 op_sel_hi:[1,0]
	v_pk_add_f32 v[112:113], v[18:19], v[94:95] op_sel:[0,1] op_sel_hi:[1,0] neg_lo:[0,1] neg_hi:[0,1]
	v_pk_add_f32 v[18:19], v[18:19], v[94:95] op_sel:[0,1] op_sel_hi:[1,0]
	v_mov_b32_e32 v113, v19
	v_pk_add_f32 v[18:19], v[98:99], v[6:7]
	v_pk_add_f32 v[6:7], v[98:99], v[6:7] neg_lo:[0,1] neg_hi:[0,1]
	v_pk_fma_f32 v[94:95], v[6:7], 0, v[6:7] op_sel:[0,0,1] op_sel_hi:[1,0,0]
	v_pk_fma_f32 v[6:7], v[6:7], 0, v[6:7] op_sel:[0,0,1] op_sel_hi:[1,0,0] neg_lo:[0,0,1] neg_hi:[0,0,1]
	v_mov_b32_e32 v95, v7
	v_pk_add_f32 v[6:7], v[104:105], v[12:13]
	v_pk_add_f32 v[12:13], v[104:105], v[12:13] neg_lo:[0,1] neg_hi:[0,1]
	v_pk_mul_f32 v[98:99], v[12:13], 0 op_sel_hi:[1,0]
	v_pk_add_f32 v[104:105], v[12:13], v[98:99] op_sel:[0,1] op_sel_hi:[1,0] neg_lo:[0,1] neg_hi:[0,1]
	v_pk_add_f32 v[12:13], v[12:13], v[98:99] op_sel:[0,1] op_sel_hi:[1,0]
	v_pk_add_f32 v[98:99], v[116:117], v[100:101] neg_lo:[0,1] neg_hi:[0,1]
	v_mov_b32_e32 v105, v13
	v_pk_add_f32 v[12:13], v[68:69], v[14:15]
	v_pk_add_f32 v[14:15], v[68:69], v[14:15] neg_lo:[0,1] neg_hi:[0,1]
	v_pk_fma_f32 v[68:69], v[14:15], 0, v[14:15] op_sel:[0,0,1] op_sel_hi:[1,0,0]
	v_pk_fma_f32 v[14:15], v[14:15], 0, v[14:15] op_sel:[0,0,1] op_sel_hi:[1,0,0] neg_lo:[0,0,1] neg_hi:[0,0,1]
	v_mov_b32_e32 v69, v15
	v_pk_add_f32 v[14:15], v[116:117], v[100:101]
	v_pk_mul_f32 v[100:101], v[98:99], 0 op_sel_hi:[1,0]
	v_pk_add_f32 v[116:117], v[98:99], v[100:101] op_sel:[0,1] op_sel_hi:[1,0] neg_lo:[0,1] neg_hi:[0,1]
	v_pk_add_f32 v[98:99], v[98:99], v[100:101] op_sel:[0,1] op_sel_hi:[1,0]
	v_mov_b32_e32 v117, v99
	v_pk_add_f32 v[98:99], v[114:115], v[16:17]
	v_pk_add_f32 v[16:17], v[114:115], v[16:17] neg_lo:[0,1] neg_hi:[0,1]
	v_pk_fma_f32 v[100:101], v[16:17], 0, v[16:17] op_sel:[0,0,1] op_sel_hi:[1,0,0]
	v_pk_fma_f32 v[16:17], v[16:17], 0, v[16:17] op_sel:[0,0,1] op_sel_hi:[1,0,0] neg_lo:[0,0,1] neg_hi:[0,0,1]
	v_mov_b32_e32 v101, v17
	v_pk_add_f32 v[16:17], v[102:103], v[76:77]
	v_pk_add_f32 v[76:77], v[102:103], v[76:77] neg_lo:[0,1] neg_hi:[0,1]
	v_pk_mul_f32 v[102:103], v[76:77], 0 op_sel_hi:[1,0]
	v_pk_add_f32 v[114:115], v[76:77], v[102:103] op_sel:[0,1] op_sel_hi:[1,0] neg_lo:[0,1] neg_hi:[0,1]
; template <int R, bool INV> DEV void dft_regs(cf (&v)[R]) {
; #pragma unroll
;     for (int s = R; s >= 2; s >>= 1) {
;         const int h = s >> 1;
; #pragma unroll
;         for (int b = 0; b < R; b += s) {
; #pragma unroll
;             for (int k = 0; k < h; ++k) {
;                 const cf a = v[b + k], c = v[b + k + h];
;                 v[b + k] = a + c;
;                 const cf d = a - c;
;                 const int m = k * (32 / s);
;                 const float wr = tw_cos(m), wi = INV ? tw_sin(m) : -tw_sin(m);
;                 v[b + k + h] = cf{d.x * wr - d.y * wi, d.x * wi + d.y * wr};
;             }
;         }
;     }
	v_pk_add_f32 v[76:77], v[76:77], v[102:103] op_sel:[0,1] op_sel_hi:[1,0]
	v_mov_b32_e32 v115, v77
	v_pk_add_f32 v[76:77], v[74:75], v[70:71]
	v_pk_add_f32 v[70:71], v[74:75], v[70:71] neg_lo:[0,1] neg_hi:[0,1]
	v_pk_fma_f32 v[74:75], v[70:71], 0, v[70:71] op_sel:[0,0,1] op_sel_hi:[1,0,0]
	v_pk_fma_f32 v[70:71], v[70:71], 0, v[70:71] op_sel:[0,0,1] op_sel_hi:[1,0,0] neg_lo:[0,0,1] neg_hi:[0,0,1]
	v_mov_b32_e32 v75, v71
	v_pk_add_f32 v[70:71], v[108:109], v[84:85]
	v_pk_add_f32 v[84:85], v[108:109], v[84:85] neg_lo:[0,1] neg_hi:[0,1]
	v_pk_mul_f32 v[102:103], v[84:85], 0 op_sel_hi:[1,0]
	v_pk_add_f32 v[108:109], v[84:85], v[102:103] op_sel:[0,1] op_sel_hi:[1,0] neg_lo:[0,1] neg_hi:[0,1]
	v_pk_add_f32 v[84:85], v[84:85], v[102:103] op_sel:[0,1] op_sel_hi:[1,0]
	v_mov_b32_e32 v109, v85
	v_pk_add_f32 v[84:85], v[106:107], v[72:73]
	v_pk_add_f32 v[72:73], v[106:107], v[72:73] neg_lo:[0,1] neg_hi:[0,1]
	v_pk_fma_f32 v[102:103], v[72:73], 0, v[72:73] op_sel:[0,0,1] op_sel_hi:[1,0,0]
	v_pk_fma_f32 v[72:73], v[72:73], 0, v[72:73] op_sel:[0,0,1] op_sel_hi:[1,0,0] neg_lo:[0,0,1] neg_hi:[0,0,1]
	v_mov_b32_e32 v103, v73
	v_pk_add_f32 v[72:73], v[92:93], v[78:79]
	v_pk_add_f32 v[78:79], v[92:93], v[78:79] neg_lo:[0,1] neg_hi:[0,1]
	v_pk_mul_f32 v[92:93], v[78:79], 0 op_sel_hi:[1,0]
	v_pk_add_f32 v[106:107], v[78:79], v[92:93] op_sel:[0,1] op_sel_hi:[1,0] neg_lo:[0,1] neg_hi:[0,1]
	v_pk_add_f32 v[78:79], v[78:79], v[92:93] op_sel:[0,1] op_sel_hi:[1,0]
	v_mov_b32_e32 v107, v79
	v_pk_add_f32 v[78:79], v[86:87], v[80:81]
	v_pk_add_f32 v[80:81], v[86:87], v[80:81] neg_lo:[0,1] neg_hi:[0,1]
	v_pk_fma_f32 v[86:87], v[80:81], 0, v[80:81] op_sel:[0,0,1] op_sel_hi:[1,0,0]
	v_pk_fma_f32 v[80:81], v[80:81], 0, v[80:81] op_sel:[0,0,1] op_sel_hi:[1,0,0] neg_lo:[0,0,1] neg_hi:[0,0,1]
	v_mov_b32_e32 v87, v81
	v_pk_add_f32 v[80:81], v[118:119], v[88:89]
	v_pk_add_f32 v[88:89], v[118:119], v[88:89] neg_lo:[0,1] neg_hi:[0,1]
	v_pk_mul_f32 v[92:93], v[88:89], 0 op_sel_hi:[1,0]
	v_pk_add_f32 v[118:119], v[88:89], v[92:93] op_sel:[0,1] op_sel_hi:[1,0] neg_lo:[0,1] neg_hi:[0,1]
	v_pk_add_f32 v[88:89], v[88:89], v[92:93] op_sel:[0,1] op_sel_hi:[1,0]
	v_mov_b32_e32 v119, v89
	v_pk_add_f32 v[88:89], v[110:111], v[82:83]
	v_pk_add_f32 v[82:83], v[110:111], v[82:83] neg_lo:[0,1] neg_hi:[0,1]
	v_pk_fma_f32 v[92:93], v[82:83], 0, v[82:83] op_sel:[0,0,1] op_sel_hi:[1,0,0]
	v_pk_fma_f32 v[82:83], v[82:83], 0, v[82:83] op_sel:[0,0,1] op_sel_hi:[1,0,0] neg_lo:[0,0,1] neg_hi:[0,0,1]
	v_mov_b32_e32 v93, v83
	v_pk_add_f32 v[82:83], v[90:91], v[10:11]
	v_pk_add_f32 v[10:11], v[90:91], v[10:11] neg_lo:[0,1] neg_hi:[0,1]
	v_pk_mul_f32 v[90:91], v[10:11], 0 op_sel_hi:[1,0]
	v_pk_add_f32 v[110:111], v[10:11], v[90:91] op_sel:[0,1] op_sel_hi:[1,0] neg_lo:[0,1] neg_hi:[0,1]
	v_pk_add_f32 v[10:11], v[10:11], v[90:91] op_sel:[0,1] op_sel_hi:[1,0]
	v_mov_b32_e32 v111, v11
	v_pk_add_f32 v[10:11], v[96:97], v[8:9]
	v_pk_add_f32 v[8:9], v[96:97], v[8:9] neg_lo:[0,1] neg_hi:[0,1]
	v_pk_mul_f32 v[90:91], v[8:9], 0 op_sel_hi:[1,0]
	v_pk_add_f32 v[96:97], v[8:9], v[90:91] op_sel:[0,1] op_sel_hi:[1,0] neg_lo:[0,1] neg_hi:[0,1]
	v_pk_add_f32 v[8:9], v[8:9], v[90:91] op_sel:[0,1] op_sel_hi:[1,0]
	v_mov_b32_e32 v97, v9
	v_pk_add_f32 v[8:9], v[4:5], v[18:19]
	v_pk_add_f32 v[4:5], v[4:5], v[18:19] neg_lo:[0,1] neg_hi:[0,1]
	v_pk_mul_f32 v[18:19], v[4:5], 0 op_sel_hi:[1,0]
	v_pk_add_f32 v[90:91], v[4:5], v[18:19] op_sel:[0,1] op_sel_hi:[1,0] neg_lo:[0,1] neg_hi:[0,1]
	v_pk_add_f32 v[4:5], v[4:5], v[18:19] op_sel:[0,1] op_sel_hi:[1,0]
	v_pk_add_f32 v[18:19], v[112:113], v[94:95] neg_lo:[0,1] neg_hi:[0,1]
	v_mov_b32_e32 v91, v5
	v_pk_add_f32 v[4:5], v[112:113], v[94:95]
	v_pk_mul_f32 v[94:95], v[18:19], 0 op_sel_hi:[1,0]
	v_pk_add_f32 v[112:113], v[18:19], v[94:95] op_sel:[0,1] op_sel_hi:[1,0] neg_lo:[0,1] neg_hi:[0,1]
	v_pk_add_f32 v[18:19], v[18:19], v[94:95] op_sel:[0,1] op_sel_hi:[1,0]
	v_mov_b32_e32 v113, v19
	v_pk_add_f32 v[18:19], v[6:7], v[12:13]
	v_pk_add_f32 v[6:7], v[6:7], v[12:13] neg_lo:[0,1] neg_hi:[0,1]
	v_pk_mul_f32 v[12:13], v[6:7], 0 op_sel_hi:[1,0]
	v_pk_add_f32 v[94:95], v[6:7], v[12:13] op_sel:[0,1] op_sel_hi:[1,0] neg_lo:[0,1] neg_hi:[0,1]
	v_pk_add_f32 v[6:7], v[6:7], v[12:13] op_sel:[0,1] op_sel_hi:[1,0]
	v_pk_add_f32 v[12:13], v[104:105], v[68:69] neg_lo:[0,1] neg_hi:[0,1]
	v_mov_b32_e32 v95, v7
	v_pk_add_f32 v[6:7], v[104:105], v[68:69]
	v_pk_mul_f32 v[68:69], v[12:13], 0 op_sel_hi:[1,0]
	v_pk_add_f32 v[104:105], v[12:13], v[68:69] op_sel:[0,1] op_sel_hi:[1,0] neg_lo:[0,1] neg_hi:[0,1]
	v_pk_add_f32 v[12:13], v[12:13], v[68:69] op_sel:[0,1] op_sel_hi:[1,0]
	v_mov_b32_e32 v105, v13
	v_pk_add_f32 v[12:13], v[14:15], v[98:99]
	v_pk_add_f32 v[14:15], v[14:15], v[98:99] neg_lo:[0,1] neg_hi:[0,1]
	v_pk_mul_f32 v[68:69], v[14:15], 0 op_sel_hi:[1,0]
	v_pk_add_f32 v[98:99], v[14:15], v[68:69] op_sel:[0,1] op_sel_hi:[1,0] neg_lo:[0,1] neg_hi:[0,1]
	v_pk_add_f32 v[14:15], v[14:15], v[68:69] op_sel:[0,1] op_sel_hi:[1,0]
	v_pk_add_f32 v[68:69], v[116:117], v[100:101] neg_lo:[0,1] neg_hi:[0,1]
	v_mov_b32_e32 v99, v15
	v_pk_add_f32 v[14:15], v[116:117], v[100:101]
	v_pk_mul_f32 v[100:101], v[68:69], 0 op_sel_hi:[1,0]
	v_pk_add_f32 v[116:117], v[68:69], v[100:101] op_sel:[0,1] op_sel_hi:[1,0] neg_lo:[0,1] neg_hi:[0,1]
	v_pk_add_f32 v[68:69], v[68:69], v[100:101] op_sel:[0,1] op_sel_hi:[1,0]
	v_mov_b32_e32 v117, v69
	v_pk_add_f32 v[68:69], v[16:17], v[76:77]
	v_pk_add_f32 v[16:17], v[16:17], v[76:77] neg_lo:[0,1] neg_hi:[0,1]
	v_pk_mul_f32 v[76:77], v[16:17], 0 op_sel_hi:[1,0]
	v_pk_add_f32 v[100:101], v[16:17], v[76:77] op_sel:[0,1] op_sel_hi:[1,0] neg_lo:[0,1] neg_hi:[0,1]
; #define SINCOSPI(x, s, c) do { const float hx_ = 0.5f * (x); *(s) = __builtin_amdgcn_sinf(hx_); *(c) = __builtin_amdgcn_cosf(hx_); } while (0)
; DEV void fft_f2(LAS cf* buf, int t8) {
;     ...
;     dft_regs<32, false>(v);
;     float sn, cs; SINCOSPI(-(float)(t8 & 15) * (2.0f / 512.0f), &sn, &cs);
;     const cf w = cf{cs, sn}; cf wp = cf{1.f, 0.f};
; #pragma unroll
;     for (int p = 0; p < 32; ++p) { pb[17 * p] = cmul(v[BR32[p]], wp); wp = cmul(wp, w); }
	v_pk_add_f32 v[16:17], v[16:17], v[76:77] op_sel:[0,1] op_sel_hi:[1,0]
	v_mov_b32_e32 v101, v17
	v_pk_add_f32 v[16:17], v[114:115], v[74:75]
	v_pk_add_f32 v[74:75], v[114:115], v[74:75] neg_lo:[0,1] neg_hi:[0,1]
	v_pk_mul_f32 v[76:77], v[74:75], 0 op_sel_hi:[1,0]
	v_pk_add_f32 v[114:115], v[74:75], v[76:77] op_sel:[0,1] op_sel_hi:[1,0] neg_lo:[0,1] neg_hi:[0,1]
	v_pk_add_f32 v[74:75], v[74:75], v[76:77] op_sel:[0,1] op_sel_hi:[1,0]
	v_mov_b32_e32 v115, v75
	v_pk_add_f32 v[74:75], v[70:71], v[84:85]
	v_pk_add_f32 v[70:71], v[70:71], v[84:85] neg_lo:[0,1] neg_hi:[0,1]
	v_pk_mul_f32 v[76:77], v[70:71], 0 op_sel_hi:[1,0]
	v_pk_add_f32 v[84:85], v[70:71], v[76:77] op_sel:[0,1] op_sel_hi:[1,0] neg_lo:[0,1] neg_hi:[0,1]
	v_pk_add_f32 v[70:71], v[70:71], v[76:77] op_sel:[0,1] op_sel_hi:[1,0]
	v_pk_add_f32 v[76:77], v[108:109], v[102:103] neg_lo:[0,1] neg_hi:[0,1]
	v_mov_b32_e32 v85, v71
	v_pk_add_f32 v[70:71], v[108:109], v[102:103]
	v_pk_mul_f32 v[102:103], v[76:77], 0 op_sel_hi:[1,0]
	v_pk_add_f32 v[108:109], v[76:77], v[102:103] op_sel:[0,1] op_sel_hi:[1,0] neg_lo:[0,1] neg_hi:[0,1]
	v_pk_add_f32 v[76:77], v[76:77], v[102:103] op_sel:[0,1] op_sel_hi:[1,0]
	v_mov_b32_e32 v109, v77
	v_pk_add_f32 v[76:77], v[72:73], v[78:79]
	v_pk_add_f32 v[72:73], v[72:73], v[78:79] neg_lo:[0,1] neg_hi:[0,1]
	v_pk_mul_f32 v[78:79], v[72:73], 0 op_sel_hi:[1,0]
	v_pk_add_f32 v[102:103], v[72:73], v[78:79] op_sel:[0,1] op_sel_hi:[1,0] neg_lo:[0,1] neg_hi:[0,1]
	v_pk_add_f32 v[72:73], v[72:73], v[78:79] op_sel:[0,1] op_sel_hi:[1,0]
	v_pk_add_f32 v[78:79], v[106:107], v[86:87] neg_lo:[0,1] neg_hi:[0,1]
	v_mov_b32_e32 v103, v73
	v_pk_add_f32 v[72:73], v[106:107], v[86:87]
	v_pk_mul_f32 v[86:87], v[78:79], 0 op_sel_hi:[1,0]
	v_pk_add_f32 v[106:107], v[78:79], v[86:87] op_sel:[0,1] op_sel_hi:[1,0] neg_lo:[0,1] neg_hi:[0,1]
	v_pk_add_f32 v[78:79], v[78:79], v[86:87] op_sel:[0,1] op_sel_hi:[1,0]
	v_mov_b32_e32 v107, v79
	v_pk_add_f32 v[78:79], v[80:81], v[88:89]
	v_pk_add_f32 v[80:81], v[80:81], v[88:89] neg_lo:[0,1] neg_hi:[0,1]
	v_pk_mul_f32 v[86:87], v[80:81], 0 op_sel_hi:[1,0]
	v_pk_add_f32 v[88:89], v[80:81], v[86:87] op_sel:[0,1] op_sel_hi:[1,0] neg_lo:[0,1] neg_hi:[0,1]
	v_pk_add_f32 v[80:81], v[80:81], v[86:87] op_sel:[0,1] op_sel_hi:[1,0]
	v_pk_add_f32 v[86:87], v[118:119], v[92:93] neg_lo:[0,1] neg_hi:[0,1]
	v_mov_b32_e32 v89, v81
	v_pk_add_f32 v[80:81], v[118:119], v[92:93]
	v_pk_mul_f32 v[92:93], v[86:87], 0 op_sel_hi:[1,0]
	v_pk_add_f32 v[118:119], v[86:87], v[92:93] op_sel:[0,1] op_sel_hi:[1,0] neg_lo:[0,1] neg_hi:[0,1]
	v_pk_add_f32 v[86:87], v[86:87], v[92:93] op_sel:[0,1] op_sel_hi:[1,0]
	v_pk_mul_f32 v[92:93], v[82:83], v[66:67] op_sel:[1,1] op_sel_hi:[1,0] neg_lo:[1,0]
	v_pk_fma_f32 v[82:83], v[82:83], v[66:67], v[92:93] op_sel_hi:[0,1,1]
	s_nop 0
	v_mov_b32_e32 v119, v87
	v_sin_f32_e32 v87, v3
	v_cos_f32_e32 v86, v3
	v_pk_mul_f32 v[92:93], v[66:67], v[86:87] op_sel:[1,1] op_sel_hi:[1,0] neg_lo:[1,0]
	v_pk_fma_f32 v[120:121], v[66:67], v[86:87], v[92:93] op_sel_hi:[0,1,1]
	v_pk_mul_f32 v[92:93], v[68:69], v[120:121] op_sel:[1,1] op_sel_hi:[1,0] neg_lo:[1,0]
	v_pk_fma_f32 v[68:69], v[68:69], v[120:121], v[92:93] op_sel_hi:[0,1,1]
	ds_write2_b64 v2, v[82:83], v[68:69] offset1:17
	v_pk_mul_f32 v[68:69], v[120:121], v[86:87] op_sel:[1,1] op_sel_hi:[1,0] neg_lo:[1,0]
	v_pk_fma_f32 v[82:83], v[120:121], v[86:87], v[68:69] op_sel_hi:[0,1,1]
	v_pk_mul_f32 v[68:69], v[18:19], v[82:83] op_sel:[1,1] op_sel_hi:[1,0] neg_lo:[1,0]
	v_pk_fma_f32 v[18:19], v[18:19], v[82:83], v[68:69] op_sel_hi:[0,1,1]
	s_nop 0
	v_pk_mul_f32 v[68:69], v[82:83], v[86:87] op_sel:[1,1] op_sel_hi:[1,0] neg_lo:[1,0]
	v_pk_fma_f32 v[82:83], v[82:83], v[86:87], v[68:69] op_sel_hi:[0,1,1]
	v_pk_mul_f32 v[92:93], v[76:77], v[82:83] op_sel:[1,1] op_sel_hi:[1,0] neg_lo:[1,0]
	v_pk_fma_f32 v[68:69], v[76:77], v[82:83], v[92:93] op_sel_hi:[0,1,1]
	ds_write2_b64 v2, v[18:19], v[68:69] offset0:34 offset1:51
	v_pk_mul_f32 v[18:19], v[82:83], v[86:87] op_sel:[1,1] op_sel_hi:[1,0] neg_lo:[1,0]
	v_pk_fma_f32 v[68:69], v[82:83], v[86:87], v[18:19] op_sel_hi:[0,1,1]
	v_pk_mul_f32 v[18:19], v[8:9], v[68:69] op_sel:[1,1] op_sel_hi:[1,0] neg_lo:[1,0]
	v_pk_fma_f32 v[8:9], v[8:9], v[68:69], v[18:19] op_sel_hi:[0,1,1]
	s_nop 0
	v_pk_mul_f32 v[18:19], v[68:69], v[86:87] op_sel:[1,1] op_sel_hi:[1,0] neg_lo:[1,0]
	v_pk_fma_f32 v[68:69], v[68:69], v[86:87], v[18:19] op_sel_hi:[0,1,1]
	v_pk_mul_f32 v[76:77], v[74:75], v[68:69] op_sel:[1,1] op_sel_hi:[1,0] neg_lo:[1,0]
	v_pk_fma_f32 v[18:19], v[74:75], v[68:69], v[76:77] op_sel_hi:[0,1,1]
	ds_write2_b64 v2, v[8:9], v[18:19] offset0:68 offset1:85
	v_pk_mul_f32 v[8:9], v[68:69], v[86:87] op_sel:[1,1] op_sel_hi:[1,0] neg_lo:[1,0]
	v_pk_fma_f32 v[18:19], v[68:69], v[86:87], v[8:9] op_sel_hi:[0,1,1]
	v_pk_mul_f32 v[68:69], v[12:13], v[18:19] op_sel:[1,1] op_sel_hi:[1,0] neg_lo:[1,0]
	v_pk_fma_f32 v[8:9], v[12:13], v[18:19], v[68:69] op_sel_hi:[0,1,1]
	v_pk_mul_f32 v[12:13], v[18:19], v[86:87] op_sel:[1,1] op_sel_hi:[1,0] neg_lo:[1,0]
	v_pk_fma_f32 v[18:19], v[18:19], v[86:87], v[12:13] op_sel_hi:[0,1,1]
	v_pk_mul_f32 v[68:69], v[78:79], v[18:19] op_sel:[1,1] op_sel_hi:[1,0] neg_lo:[1,0]
	v_pk_fma_f32 v[12:13], v[78:79], v[18:19], v[68:69] op_sel_hi:[0,1,1]
	ds_write2_b64 v2, v[8:9], v[12:13] offset0:102 offset1:119
	v_pk_mul_f32 v[8:9], v[18:19], v[86:87] op_sel:[1,1] op_sel_hi:[1,0] neg_lo:[1,0]
	v_pk_fma_f32 v[12:13], v[18:19], v[86:87], v[8:9] op_sel_hi:[0,1,1]
	v_pk_mul_f32 v[18:19], v[10:11], v[12:13] op_sel:[1,1] op_sel_hi:[1,0] neg_lo:[1,0]
	v_pk_fma_f32 v[8:9], v[10:11], v[12:13], v[18:19] op_sel_hi:[0,1,1]
	v_pk_mul_f32 v[10:11], v[12:13], v[86:87] op_sel:[1,1] op_sel_hi:[1,0] neg_lo:[1,0]
; DEV void fft_f2(LAS cf* buf, int t8) {
;     ...
;     const cf w = cf{cs, sn}; cf wp = cf{1.f, 0.f};
; #pragma unroll
;     for (int p = 0; p < 32; ++p) { pb[17 * p] = cmul(v[BR32[p]], wp); wp = cmul(wp, w); }
	v_pk_fma_f32 v[12:13], v[12:13], v[86:87], v[10:11] op_sel_hi:[0,1,1]
	v_pk_mul_f32 v[18:19], v[16:17], v[12:13] op_sel:[1,1] op_sel_hi:[1,0] neg_lo:[1,0]
	v_pk_fma_f32 v[10:11], v[16:17], v[12:13], v[18:19] op_sel_hi:[0,1,1]
	ds_write2_b64 v2, v[8:9], v[10:11] offset0:136 offset1:153
	v_pk_mul_f32 v[8:9], v[12:13], v[86:87] op_sel:[1,1] op_sel_hi:[1,0] neg_lo:[1,0]
	v_pk_fma_f32 v[10:11], v[12:13], v[86:87], v[8:9] op_sel_hi:[0,1,1]
	v_pk_mul_f32 v[8:9], v[6:7], v[10:11] op_sel:[1,1] op_sel_hi:[1,0] neg_lo:[1,0]
	v_pk_fma_f32 v[6:7], v[6:7], v[10:11], v[8:9] op_sel_hi:[0,1,1]
	s_nop 0
	v_pk_mul_f32 v[8:9], v[10:11], v[86:87] op_sel:[1,1] op_sel_hi:[1,0] neg_lo:[1,0]
	v_pk_fma_f32 v[10:11], v[10:11], v[86:87], v[8:9] op_sel_hi:[0,1,1]
	v_pk_mul_f32 v[12:13], v[72:73], v[10:11] op_sel:[1,1] op_sel_hi:[1,0] neg_lo:[1,0]
	v_pk_fma_f32 v[8:9], v[72:73], v[10:11], v[12:13] op_sel_hi:[0,1,1]
	ds_write2_b64 v2, v[6:7], v[8:9] offset0:170 offset1:187
	v_pk_mul_f32 v[6:7], v[10:11], v[86:87] op_sel:[1,1] op_sel_hi:[1,0] neg_lo:[1,0]
	v_pk_fma_f32 v[8:9], v[10:11], v[86:87], v[6:7] op_sel_hi:[0,1,1]
	v_pk_mul_f32 v[6:7], v[4:5], v[8:9] op_sel:[1,1] op_sel_hi:[1,0] neg_lo:[1,0]
	v_pk_fma_f32 v[4:5], v[4:5], v[8:9], v[6:7] op_sel_hi:[0,1,1]
	s_nop 0
	v_pk_mul_f32 v[6:7], v[8:9], v[86:87] op_sel:[1,1] op_sel_hi:[1,0] neg_lo:[1,0]
	v_pk_fma_f32 v[8:9], v[8:9], v[86:87], v[6:7] op_sel_hi:[0,1,1]
	v_pk_mul_f32 v[10:11], v[70:71], v[8:9] op_sel:[1,1] op_sel_hi:[1,0] neg_lo:[1,0]
	v_pk_fma_f32 v[6:7], v[70:71], v[8:9], v[10:11] op_sel_hi:[0,1,1]
	ds_write2_b64 v2, v[4:5], v[6:7] offset0:204 offset1:221
	v_pk_mul_f32 v[4:5], v[8:9], v[86:87] op_sel:[1,1] op_sel_hi:[1,0] neg_lo:[1,0]
	v_pk_fma_f32 v[6:7], v[8:9], v[86:87], v[4:5] op_sel_hi:[0,1,1]
	v_pk_mul_f32 v[8:9], v[14:15], v[6:7] op_sel:[1,1] op_sel_hi:[1,0] neg_lo:[1,0]
	v_pk_fma_f32 v[4:5], v[14:15], v[6:7], v[8:9] op_sel_hi:[0,1,1]
	s_nop 0
	v_pk_mul_f32 v[8:9], v[6:7], v[86:87] op_sel:[1,1] op_sel_hi:[1,0] neg_lo:[1,0]
	v_pk_fma_f32 v[6:7], v[6:7], v[86:87], v[8:9] op_sel_hi:[0,1,1]
	v_pk_mul_f32 v[10:11], v[80:81], v[6:7] op_sel:[1,1] op_sel_hi:[1,0] neg_lo:[1,0]
	v_pk_fma_f32 v[8:9], v[80:81], v[6:7], v[10:11] op_sel_hi:[0,1,1]
	ds_write2_b64 v2, v[4:5], v[8:9] offset0:238 offset1:255
	v_pk_mul_f32 v[2:3], v[6:7], v[86:87] op_sel:[1,1] op_sel_hi:[1,0] neg_lo:[1,0]
	v_pk_fma_f32 v[4:5], v[6:7], v[86:87], v[2:3] op_sel_hi:[0,1,1]
	v_pk_mul_f32 v[6:7], v[110:111], v[4:5] op_sel:[1,1] op_sel_hi:[1,0] neg_lo:[1,0]
	v_pk_fma_f32 v[2:3], v[110:111], v[4:5], v[6:7] op_sel_hi:[0,1,1]
	s_nop 0
	v_pk_mul_f32 v[6:7], v[4:5], v[86:87] op_sel:[1,1] op_sel_hi:[1,0] neg_lo:[1,0]
	v_pk_fma_f32 v[4:5], v[4:5], v[86:87], v[6:7] op_sel_hi:[0,1,1]
	v_pk_mul_f32 v[8:9], v[100:101], v[4:5] op_sel:[1,1] op_sel_hi:[1,0] neg_lo:[1,0]
	v_pk_fma_f32 v[6:7], v[100:101], v[4:5], v[8:9] op_sel_hi:[0,1,1]
	ds_write2_b64 v0, v[2:3], v[6:7] offset0:16 offset1:33
	v_pk_mul_f32 v[2:3], v[4:5], v[86:87] op_sel:[1,1] op_sel_hi:[1,0] neg_lo:[1,0]
	v_pk_fma_f32 v[4:5], v[4:5], v[86:87], v[2:3] op_sel_hi:[0,1,1]
	v_pk_mul_f32 v[6:7], v[94:95], v[4:5] op_sel:[1,1] op_sel_hi:[1,0] neg_lo:[1,0]
	v_pk_fma_f32 v[2:3], v[94:95], v[4:5], v[6:7] op_sel_hi:[0,1,1]
	s_nop 0
	v_pk_mul_f32 v[6:7], v[4:5], v[86:87] op_sel:[1,1] op_sel_hi:[1,0] neg_lo:[1,0]
	v_pk_fma_f32 v[4:5], v[4:5], v[86:87], v[6:7] op_sel_hi:[0,1,1]
	v_pk_mul_f32 v[8:9], v[102:103], v[4:5] op_sel:[1,1] op_sel_hi:[1,0] neg_lo:[1,0]
	v_pk_fma_f32 v[6:7], v[102:103], v[4:5], v[8:9] op_sel_hi:[0,1,1]
	ds_write2_b64 v0, v[2:3], v[6:7] offset0:50 offset1:67
	v_pk_mul_f32 v[2:3], v[4:5], v[86:87] op_sel:[1,1] op_sel_hi:[1,0] neg_lo:[1,0]
	v_pk_fma_f32 v[4:5], v[4:5], v[86:87], v[2:3] op_sel_hi:[0,1,1]
	v_pk_mul_f32 v[6:7], v[90:91], v[4:5] op_sel:[1,1] op_sel_hi:[1,0] neg_lo:[1,0]
	v_pk_fma_f32 v[2:3], v[90:91], v[4:5], v[6:7] op_sel_hi:[0,1,1]
	s_nop 0
	v_pk_mul_f32 v[6:7], v[4:5], v[86:87] op_sel:[1,1] op_sel_hi:[1,0] neg_lo:[1,0]
	v_pk_fma_f32 v[4:5], v[4:5], v[86:87], v[6:7] op_sel_hi:[0,1,1]
	v_pk_mul_f32 v[8:9], v[84:85], v[4:5] op_sel:[1,1] op_sel_hi:[1,0] neg_lo:[1,0]
	v_pk_fma_f32 v[6:7], v[84:85], v[4:5], v[8:9] op_sel_hi:[0,1,1]
	ds_write2_b64 v0, v[2:3], v[6:7] offset0:84 offset1:101
	v_pk_mul_f32 v[2:3], v[4:5], v[86:87] op_sel:[1,1] op_sel_hi:[1,0] neg_lo:[1,0]
	v_pk_fma_f32 v[4:5], v[4:5], v[86:87], v[2:3] op_sel_hi:[0,1,1]
	v_pk_mul_f32 v[6:7], v[98:99], v[4:5] op_sel:[1,1] op_sel_hi:[1,0] neg_lo:[1,0]
	v_pk_fma_f32 v[2:3], v[98:99], v[4:5], v[6:7] op_sel_hi:[0,1,1]
	s_nop 0
	v_pk_mul_f32 v[6:7], v[4:5], v[86:87] op_sel:[1,1] op_sel_hi:[1,0] neg_lo:[1,0]
	v_pk_fma_f32 v[4:5], v[4:5], v[86:87], v[6:7] op_sel_hi:[0,1,1]
	v_pk_mul_f32 v[8:9], v[88:89], v[4:5] op_sel:[1,1] op_sel_hi:[1,0] neg_lo:[1,0]
	v_pk_fma_f32 v[6:7], v[88:89], v[4:5], v[8:9] op_sel_hi:[0,1,1]
	ds_write2_b64 v0, v[2:3], v[6:7] offset0:118 offset1:135
	v_pk_mul_f32 v[2:3], v[4:5], v[86:87] op_sel:[1,1] op_sel_hi:[1,0] neg_lo:[1,0]
	v_pk_fma_f32 v[4:5], v[4:5], v[86:87], v[2:3] op_sel_hi:[0,1,1]
	v_pk_mul_f32 v[6:7], v[96:97], v[4:5] op_sel:[1,1] op_sel_hi:[1,0] neg_lo:[1,0]
	v_pk_fma_f32 v[2:3], v[96:97], v[4:5], v[6:7] op_sel_hi:[0,1,1]
	s_nop 0
	v_pk_mul_f32 v[6:7], v[4:5], v[86:87] op_sel:[1,1] op_sel_hi:[1,0] neg_lo:[1,0]
	v_pk_fma_f32 v[4:5], v[4:5], v[86:87], v[6:7] op_sel_hi:[0,1,1]
	v_pk_mul_f32 v[8:9], v[114:115], v[4:5] op_sel:[1,1] op_sel_hi:[1,0] neg_lo:[1,0]
	v_pk_fma_f32 v[6:7], v[114:115], v[4:5], v[8:9] op_sel_hi:[0,1,1]
	ds_write2_b64 v0, v[2:3], v[6:7] offset0:152 offset1:169
	v_pk_mul_f32 v[2:3], v[4:5], v[86:87] op_sel:[1,1] op_sel_hi:[1,0] neg_lo:[1,0]
; #define LAS __attribute__((address_space(3)))
; DEV void fft_midx2(LAS cf* buf0, LAS cf* buf1, const unsigned* Kp, int blk) {
;     const int base = 16 * blk;
;     LAS cf* p0 = buf0 + 17 * blk; LAS cf* p1 = buf1 + 17 * blk;
;     cf v[16], u[16];
; #pragma unroll
;     for (int q = 0; q < 16; ++q) { v[q] = p0[q]; u[q] = p1[q]; }
;     dft_regs<16, false>(v); dft_regs<16, false>(u);
	v_pk_fma_f32 v[4:5], v[4:5], v[86:87], v[2:3] op_sel_hi:[0,1,1]
	v_pk_mul_f32 v[6:7], v[104:105], v[4:5] op_sel:[1,1] op_sel_hi:[1,0] neg_lo:[1,0]
	v_pk_fma_f32 v[2:3], v[104:105], v[4:5], v[6:7] op_sel_hi:[0,1,1]
	s_nop 0
	v_pk_mul_f32 v[6:7], v[4:5], v[86:87] op_sel:[1,1] op_sel_hi:[1,0] neg_lo:[1,0]
	v_pk_fma_f32 v[4:5], v[4:5], v[86:87], v[6:7] op_sel_hi:[0,1,1]
	v_pk_mul_f32 v[8:9], v[106:107], v[4:5] op_sel:[1,1] op_sel_hi:[1,0] neg_lo:[1,0]
	v_pk_fma_f32 v[6:7], v[106:107], v[4:5], v[8:9] op_sel_hi:[0,1,1]
	ds_write2_b64 v0, v[2:3], v[6:7] offset0:186 offset1:203
	v_pk_mul_f32 v[2:3], v[4:5], v[86:87] op_sel:[1,1] op_sel_hi:[1,0] neg_lo:[1,0]
	v_pk_fma_f32 v[4:5], v[4:5], v[86:87], v[2:3] op_sel_hi:[0,1,1]
	v_pk_mul_f32 v[6:7], v[112:113], v[4:5] op_sel:[1,1] op_sel_hi:[1,0] neg_lo:[1,0]
	v_pk_fma_f32 v[2:3], v[112:113], v[4:5], v[6:7] op_sel_hi:[0,1,1]
	s_nop 0
	v_pk_mul_f32 v[6:7], v[4:5], v[86:87] op_sel:[1,1] op_sel_hi:[1,0] neg_lo:[1,0]
	v_pk_fma_f32 v[4:5], v[4:5], v[86:87], v[6:7] op_sel_hi:[0,1,1]
	v_pk_mul_f32 v[8:9], v[108:109], v[4:5] op_sel:[1,1] op_sel_hi:[1,0] neg_lo:[1,0]
	v_pk_fma_f32 v[6:7], v[108:109], v[4:5], v[8:9] op_sel_hi:[0,1,1]
	ds_write2_b64 v0, v[2:3], v[6:7] offset0:220 offset1:237
	v_pk_mul_f32 v[2:3], v[4:5], v[86:87] op_sel:[1,1] op_sel_hi:[1,0] neg_lo:[1,0]
	v_pk_fma_f32 v[4:5], v[4:5], v[86:87], v[2:3] op_sel_hi:[0,1,1]
	v_pk_mul_f32 v[6:7], v[116:117], v[4:5] op_sel:[1,1] op_sel_hi:[1,0] neg_lo:[1,0]
	v_pk_fma_f32 v[2:3], v[116:117], v[4:5], v[6:7] op_sel_hi:[0,1,1]
	s_nop 0
	v_pk_mul_f32 v[6:7], v[4:5], v[86:87] op_sel:[1,1] op_sel_hi:[1,0] neg_lo:[1,0]
	v_pk_fma_f32 v[4:5], v[4:5], v[86:87], v[6:7] op_sel_hi:[0,1,1]
	v_pk_mul_f32 v[6:7], v[118:119], v[4:5] op_sel:[1,1] op_sel_hi:[1,0] neg_lo:[1,0]
	v_pk_fma_f32 v[4:5], v[118:119], v[4:5], v[6:7] op_sel_hi:[0,1,1]
	ds_write2_b64 v1, v[2:3], v[4:5] offset0:126 offset1:143
	s_waitcnt lgkmcnt(0)
	s_barrier
	ds_read2_b64 v[68:71], v161 offset1:1
	ds_read2_b64 v[8:11], v162 offset1:1
	ds_read2_b64 v[72:75], v161 offset0:2 offset1:3
	ds_read2_b64 v[12:15], v162 offset0:2 offset1:3
	ds_read2_b64 v[76:79], v161 offset0:4 offset1:5
	ds_read2_b64 v[0:3], v162 offset0:4 offset1:5
	ds_read2_b64 v[80:83], v161 offset0:6 offset1:7
	ds_read2_b64 v[4:7], v162 offset0:6 offset1:7
	ds_read2_b64 v[84:87], v161 offset0:8 offset1:9
	ds_read2_b64 v[100:103], v162 offset0:8 offset1:9
	ds_read2_b64 v[88:91], v161 offset0:10 offset1:11
	ds_read2_b64 v[104:107], v162 offset0:10 offset1:11
	ds_read2_b64 v[92:95], v161 offset0:12 offset1:13
	ds_read2_b64 v[16:19], v162 offset0:12 offset1:13
	ds_read2_b64 v[96:99], v161 offset0:14 offset1:15
	ds_read2_b64 v[108:111], v162 offset0:14 offset1:15
	s_waitcnt lgkmcnt(7)
	v_pk_add_f32 v[112:113], v[68:69], v[84:85]
	v_pk_add_f32 v[68:69], v[68:69], v[84:85] neg_lo:[0,1] neg_hi:[0,1]
	v_pk_mul_f32 v[84:85], v[68:69], 0 op_sel_hi:[1,0]
	v_pk_add_f32 v[114:115], v[68:69], v[84:85] op_sel:[0,1] op_sel_hi:[1,0] neg_lo:[0,1] neg_hi:[0,1]
	v_pk_add_f32 v[68:69], v[68:69], v[84:85] op_sel:[0,1] op_sel_hi:[1,0]
	v_mov_b32_e32 v115, v69
	v_pk_add_f32 v[68:69], v[70:71], v[86:87]
	v_pk_add_f32 v[70:71], v[70:71], v[86:87] neg_lo:[0,1] neg_hi:[0,1]
	v_pk_mul_f32 v[84:85], v[70:71], s[84:85] op_sel_hi:[1,0]
	v_pk_fma_f32 v[86:87], v[70:71], s[16:17], v[84:85] op_sel:[0,0,1] op_sel_hi:[1,0,0]
	v_pk_fma_f32 v[70:71], v[70:71], s[16:17], v[84:85] op_sel:[0,0,1] op_sel_hi:[1,0,0] neg_lo:[0,0,1] neg_hi:[0,0,1]
	v_mov_b32_e32 v87, v71
	s_waitcnt lgkmcnt(5)
	v_pk_add_f32 v[70:71], v[72:73], v[88:89]
	v_pk_add_f32 v[72:73], v[72:73], v[88:89] neg_lo:[0,1] neg_hi:[0,1]
	v_pk_mul_f32 v[84:85], v[72:73], s[18:19] op_sel_hi:[1,0]
	v_pk_fma_f32 v[88:89], v[72:73], s[18:19], v[84:85] op_sel:[0,0,1] op_sel_hi:[1,0,0]
	v_pk_fma_f32 v[72:73], v[72:73], s[18:19], v[84:85] op_sel_hi:[1,0,0] neg_lo:[0,0,1] neg_hi:[0,0,1]
	v_pk_add_f32 v[84:85], v[74:75], v[90:91]
	v_pk_add_f32 v[74:75], v[74:75], v[90:91] neg_lo:[0,1] neg_hi:[0,1]
	v_mov_b32_e32 v89, v73
	v_pk_mul_f32 v[90:91], v[74:75], s[16:17] op_sel_hi:[1,0]
	v_pk_fma_f32 v[116:117], v[74:75], s[84:85], v[90:91] op_sel:[0,0,1] op_sel_hi:[1,0,0]
	v_pk_fma_f32 v[74:75], v[74:75], s[84:85], v[90:91] op_sel:[0,0,1] op_sel_hi:[1,0,0] neg_lo:[0,0,1] neg_hi:[0,0,1]
	v_mov_b32_e32 v117, v75
	s_waitcnt lgkmcnt(3)
	v_pk_add_f32 v[74:75], v[76:77], v[92:93]
	v_pk_add_f32 v[76:77], v[76:77], v[92:93] neg_lo:[0,1] neg_hi:[0,1]
	v_pk_fma_f32 v[90:91], v[76:77], 0, v[76:77] op_sel:[0,0,1] op_sel_hi:[1,0,0]
	v_pk_fma_f32 v[76:77], v[76:77], 0, v[76:77] op_sel:[0,0,1] op_sel_hi:[1,0,0] neg_lo:[0,0,1] neg_hi:[0,0,1]
	v_mov_b32_e32 v91, v77
	v_pk_add_f32 v[76:77], v[78:79], v[94:95]
	v_pk_add_f32 v[78:79], v[78:79], v[94:95] neg_lo:[0,1] neg_hi:[0,1]
	s_waitcnt lgkmcnt(1)
; template <int R, bool INV> DEV void dft_regs(cf (&v)[R]) {
; #pragma unroll
;     for (int s = R; s >= 2; s >>= 1) {
;         const int h = s >> 1;
; #pragma unroll
;         for (int b = 0; b < R; b += s) {
; #pragma unroll
;             for (int k = 0; k < h; ++k) {
;                 const cf a = v[b + k], c = v[b + k + h];
;                 v[b + k] = a + c;
;                 const cf d = a - c;
;                 const int m = k * (32 / s);
;                 const float wr = tw_cos(m), wi = INV ? tw_sin(m) : -tw_sin(m);
;                 v[b + k + h] = cf{d.x * wr - d.y * wi, d.x * wi + d.y * wr};
;             }
;         }
;     }
; DEV void fft_midx2(LAS cf* buf0, LAS cf* buf1, const unsigned* Kp, int blk) {
;     ...
;     for (int q = 0; q < 16; ++q) { v[q] = p0[q]; u[q] = p1[q]; }
;     dft_regs<16, false>(v); dft_regs<16, false>(u);
	v_pk_add_f32 v[94:95], v[82:83], v[98:99]
	v_pk_mul_f32 v[92:93], v[78:79], s[84:85] op_sel_hi:[0,1]
	v_pk_add_f32 v[82:83], v[82:83], v[98:99] neg_lo:[0,1] neg_hi:[0,1]
	v_pk_fma_f32 v[78:79], v[78:79], s[30:31], v[92:93] op_sel:[1,0,0] neg_lo:[0,0,1] neg_hi:[0,0,1]
	v_pk_add_f32 v[92:93], v[80:81], v[96:97]
	v_pk_add_f32 v[80:81], v[80:81], v[96:97] neg_lo:[0,1] neg_hi:[0,1]
	v_pk_mul_f32 v[96:97], v[82:83], s[24:25] op_sel_hi:[0,1]
	v_pk_fma_f32 v[82:83], v[82:83], s[34:35], v[96:97] op_sel:[1,0,0] neg_lo:[0,0,1] neg_hi:[0,0,1]
	v_pk_add_f32 v[96:97], v[112:113], v[74:75]
	v_pk_add_f32 v[74:75], v[112:113], v[74:75] neg_lo:[0,1] neg_hi:[0,1]
	v_mul_f32_e32 v72, 0x3f3504f3, v80
	v_pk_mul_f32 v[98:99], v[74:75], 0 op_sel_hi:[1,0]
	v_pk_fma_f32 v[80:81], v[80:81], s[28:29], v[72:73] op_sel:[1,0,0] op_sel_hi:[1,1,0] neg_lo:[0,0,1] neg_hi:[0,0,1]
	v_pk_add_f32 v[112:113], v[74:75], v[98:99] op_sel:[0,1] op_sel_hi:[1,0] neg_lo:[0,1] neg_hi:[0,1]
	v_pk_add_f32 v[74:75], v[74:75], v[98:99] op_sel:[0,1] op_sel_hi:[1,0]
	v_pk_add_f32 v[72:73], v[88:89], v[80:81]
	v_mov_b32_e32 v113, v75
	v_pk_add_f32 v[74:75], v[68:69], v[76:77]
	v_pk_add_f32 v[68:69], v[68:69], v[76:77] neg_lo:[0,1] neg_hi:[0,1]
	v_pk_mul_f32 v[76:77], v[68:69], s[18:19] op_sel_hi:[1,0]
	v_pk_fma_f32 v[98:99], v[68:69], s[18:19], v[76:77] op_sel:[0,0,1] op_sel_hi:[1,0,0]
	v_pk_fma_f32 v[68:69], v[68:69], s[18:19], v[76:77] op_sel_hi:[1,0,0] neg_lo:[0,0,1] neg_hi:[0,0,1]
	v_pk_add_f32 v[76:77], v[70:71], v[92:93]
	v_pk_add_f32 v[70:71], v[70:71], v[92:93] neg_lo:[0,1] neg_hi:[0,1]
	v_mov_b32_e32 v99, v69
	v_pk_fma_f32 v[92:93], v[70:71], 0, v[70:71] op_sel:[0,0,1] op_sel_hi:[1,0,0]
	v_pk_fma_f32 v[70:71], v[70:71], 0, v[70:71] op_sel:[0,0,1] op_sel_hi:[1,0,0] neg_lo:[0,0,1] neg_hi:[0,0,1]
	v_mov_b32_e32 v93, v71
	v_pk_add_f32 v[70:71], v[84:85], v[94:95]
	v_pk_add_f32 v[84:85], v[84:85], v[94:95] neg_lo:[0,1] neg_hi:[0,1]
	v_pk_add_f32 v[94:95], v[114:115], v[90:91]
	v_pk_add_f32 v[90:91], v[114:115], v[90:91] neg_lo:[0,1] neg_hi:[0,1]
	v_mul_f32_e32 v68, 0x3f3504f3, v84
	v_pk_mul_f32 v[114:115], v[90:91], 0 op_sel_hi:[1,0]
	v_pk_fma_f32 v[84:85], v[84:85], s[28:29], v[68:69] op_sel:[1,0,0] op_sel_hi:[1,1,0] neg_lo:[0,0,1] neg_hi:[0,0,1]
	v_pk_add_f32 v[118:119], v[90:91], v[114:115] op_sel:[0,1] op_sel_hi:[1,0] neg_lo:[0,1] neg_hi:[0,1]
	v_pk_add_f32 v[90:91], v[90:91], v[114:115] op_sel:[0,1] op_sel_hi:[1,0]
	v_mov_b32_e32 v119, v91
	v_pk_add_f32 v[90:91], v[86:87], v[78:79]
	v_pk_add_f32 v[78:79], v[86:87], v[78:79] neg_lo:[0,1] neg_hi:[0,1]
	v_pk_mul_f32 v[86:87], v[78:79], s[18:19] op_sel_hi:[1,0]
	v_pk_fma_f32 v[114:115], v[78:79], s[18:19], v[86:87] op_sel:[0,0,1] op_sel_hi:[1,0,0]
	v_pk_fma_f32 v[78:79], v[78:79], s[18:19], v[86:87] op_sel_hi:[1,0,0] neg_lo:[0,0,1] neg_hi:[0,0,1]
	v_mov_b32_e32 v115, v79
	v_pk_add_f32 v[78:79], v[88:89], v[80:81] neg_lo:[0,1] neg_hi:[0,1]
	v_pk_add_f32 v[88:89], v[96:97], v[76:77]
	v_pk_add_f32 v[76:77], v[96:97], v[76:77] neg_lo:[0,1] neg_hi:[0,1]
	v_pk_fma_f32 v[80:81], v[78:79], 0, v[78:79] op_sel:[0,0,1] op_sel_hi:[1,0,0]
	v_pk_mul_f32 v[86:87], v[76:77], 0 op_sel_hi:[1,0]
	v_pk_fma_f32 v[78:79], v[78:79], 0, v[78:79] op_sel:[0,0,1] op_sel_hi:[1,0,0] neg_lo:[0,0,1] neg_hi:[0,0,1]
	v_pk_add_f32 v[96:97], v[76:77], v[86:87] op_sel:[0,1] op_sel_hi:[1,0] neg_lo:[0,1] neg_hi:[0,1]
	v_pk_add_f32 v[76:77], v[76:77], v[86:87] op_sel:[0,1] op_sel_hi:[1,0]
	v_mov_b32_e32 v81, v79
	v_mov_b32_e32 v97, v77
	v_pk_add_f32 v[76:77], v[74:75], v[70:71]
	v_pk_add_f32 v[70:71], v[74:75], v[70:71] neg_lo:[0,1] neg_hi:[0,1]
	v_pk_add_f32 v[78:79], v[116:117], v[82:83]
	v_pk_fma_f32 v[74:75], v[70:71], 0, v[70:71] op_sel:[0,0,1] op_sel_hi:[1,0,0]
	v_pk_fma_f32 v[70:71], v[70:71], 0, v[70:71] op_sel:[0,0,1] op_sel_hi:[1,0,0] neg_lo:[0,0,1] neg_hi:[0,0,1]
	v_pk_add_f32 v[82:83], v[116:117], v[82:83] neg_lo:[0,1] neg_hi:[0,1]
	v_mov_b32_e32 v75, v71
	v_pk_add_f32 v[70:71], v[112:113], v[92:93] neg_lo:[0,1] neg_hi:[0,1]
	v_pk_add_f32 v[116:117], v[112:113], v[92:93]
	v_pk_mul_f32 v[86:87], v[70:71], 0 op_sel_hi:[1,0]
	v_mul_f32_e32 v68, 0x3f3504f3, v82
	v_pk_add_f32 v[92:93], v[70:71], v[86:87] op_sel:[0,1] op_sel_hi:[1,0] neg_lo:[0,1] neg_hi:[0,1]
	v_pk_add_f32 v[70:71], v[70:71], v[86:87] op_sel:[0,1] op_sel_hi:[1,0]
	v_pk_fma_f32 v[82:83], v[82:83], s[28:29], v[68:69] op_sel:[1,0,0] op_sel_hi:[1,1,0] neg_lo:[0,0,1] neg_hi:[0,0,1]
	v_mov_b32_e32 v93, v71
	v_pk_add_f32 v[70:71], v[98:99], v[84:85] neg_lo:[0,1] neg_hi:[0,1]
	v_pk_add_f32 v[68:69], v[98:99], v[84:85]
	v_pk_fma_f32 v[98:99], v[70:71], 0, v[70:71] op_sel:[0,0,1] op_sel_hi:[1,0,0]
	v_pk_fma_f32 v[70:71], v[70:71], 0, v[70:71] op_sel:[0,0,1] op_sel_hi:[1,0,0] neg_lo:[0,0,1] neg_hi:[0,0,1]
	v_pk_add_f32 v[112:113], v[94:95], v[72:73]
	v_mov_b32_e32 v99, v71
	v_pk_add_f32 v[70:71], v[94:95], v[72:73] neg_lo:[0,1] neg_hi:[0,1]
	v_pk_add_f32 v[122:123], v[118:119], v[80:81]
	v_pk_mul_f32 v[72:73], v[70:71], 0 op_sel_hi:[1,0]
	v_pk_add_f32 v[124:125], v[114:115], v[82:83]
	v_pk_add_f32 v[120:121], v[70:71], v[72:73] op_sel:[0,1] op_sel_hi:[1,0] neg_lo:[0,1] neg_hi:[0,1]
	v_pk_add_f32 v[70:71], v[70:71], v[72:73] op_sel:[0,1] op_sel_hi:[1,0]
	v_pk_add_f32 v[72:73], v[90:91], v[78:79]
	v_mov_b32_e32 v121, v71
	v_pk_add_f32 v[70:71], v[90:91], v[78:79] neg_lo:[0,1] neg_hi:[0,1]
	v_pk_add_f32 v[86:87], v[88:89], v[76:77]
	v_pk_fma_f32 v[78:79], v[70:71], 0, v[70:71] op_sel:[0,0,1] op_sel_hi:[1,0,0]
	v_pk_fma_f32 v[70:71], v[70:71], 0, v[70:71] op_sel:[0,0,1] op_sel_hi:[1,0,0] neg_lo:[0,0,1] neg_hi:[0,0,1]
	v_pk_add_f32 v[94:95], v[112:113], v[72:73]
	v_mov_b32_e32 v79, v71
; template <int R, bool INV> DEV void dft_regs(cf (&v)[R]) {
; #pragma unroll
;     for (int s = R; s >= 2; s >>= 1) {
;         const int h = s >> 1;
; #pragma unroll
;         for (int b = 0; b < R; b += s) {
; #pragma unroll
;             for (int k = 0; k < h; ++k) {
;                 const cf a = v[b + k], c = v[b + k + h];
;                 v[b + k] = a + c;
;                 const cf d = a - c;
;                 const int m = k * (32 / s);
;                 const float wr = tw_cos(m), wi = INV ? tw_sin(m) : -tw_sin(m);
;                 v[b + k + h] = cf{d.x * wr - d.y * wi, d.x * wi + d.y * wr};
;             }
;         }
;     }
; DEV void fft_midx2(LAS cf* buf0, LAS cf* buf1, const unsigned* Kp, int blk) {
;     ...
;     for (int q = 0; q < 16; ++q) { v[q] = p0[q]; u[q] = p1[q]; }
;     dft_regs<16, false>(v); dft_regs<16, false>(u);
	v_pk_add_f32 v[70:71], v[118:119], v[80:81] neg_lo:[0,1] neg_hi:[0,1]
	v_pk_add_f32 v[72:73], v[112:113], v[72:73] neg_lo:[0,1] neg_hi:[0,1]
	v_pk_mul_f32 v[80:81], v[70:71], 0 op_sel_hi:[1,0]
	v_pk_add_f32 v[84:85], v[92:93], v[98:99]
	v_pk_add_f32 v[118:119], v[70:71], v[80:81] op_sel:[0,1] op_sel_hi:[1,0] neg_lo:[0,1] neg_hi:[0,1]
	v_pk_add_f32 v[70:71], v[70:71], v[80:81] op_sel:[0,1] op_sel_hi:[1,0]
	v_pk_add_f32 v[112:113], v[8:9], v[100:101]
	v_mov_b32_e32 v119, v71
	v_pk_add_f32 v[70:71], v[114:115], v[82:83] neg_lo:[0,1] neg_hi:[0,1]
	v_pk_add_f32 v[82:83], v[96:97], v[74:75]
	v_pk_fma_f32 v[114:115], v[70:71], 0, v[70:71] op_sel:[0,0,1] op_sel_hi:[1,0,0]
	v_pk_fma_f32 v[70:71], v[70:71], 0, v[70:71] op_sel:[0,0,1] op_sel_hi:[1,0,0] neg_lo:[0,0,1] neg_hi:[0,0,1]
	v_pk_add_f32 v[74:75], v[96:97], v[74:75] neg_lo:[0,1] neg_hi:[0,1]
	v_mov_b32_e32 v115, v71
	v_pk_add_f32 v[70:71], v[88:89], v[76:77] neg_lo:[0,1] neg_hi:[0,1]
	v_pk_add_f32 v[88:89], v[116:117], v[68:69]
	v_pk_mul_f32 v[80:81], v[70:71], 0 op_sel_hi:[1,0]
	v_pk_add_f32 v[68:69], v[116:117], v[68:69] neg_lo:[0,1] neg_hi:[0,1]
	v_pk_add_f32 v[76:77], v[70:71], v[80:81] op_sel:[0,1] op_sel_hi:[1,0] neg_lo:[0,1] neg_hi:[0,1]
	v_pk_add_f32 v[70:71], v[70:71], v[80:81] op_sel:[0,1] op_sel_hi:[1,0]
	v_pk_mul_f32 v[80:81], v[74:75], 0 op_sel_hi:[1,0]
	v_mov_b32_e32 v77, v71
	v_pk_add_f32 v[70:71], v[74:75], v[80:81] op_sel:[0,1] op_sel_hi:[1,0] neg_lo:[0,1] neg_hi:[0,1]
	v_pk_add_f32 v[74:75], v[74:75], v[80:81] op_sel:[0,1] op_sel_hi:[1,0]
	v_pk_mul_f32 v[80:81], v[68:69], 0 op_sel_hi:[1,0]
	v_mov_b32_e32 v71, v75
	v_pk_add_f32 v[74:75], v[68:69], v[80:81] op_sel:[0,1] op_sel_hi:[1,0] neg_lo:[0,1] neg_hi:[0,1]
	v_pk_add_f32 v[68:69], v[68:69], v[80:81] op_sel:[0,1] op_sel_hi:[1,0]
	v_pk_add_f32 v[80:81], v[92:93], v[98:99] neg_lo:[0,1] neg_hi:[0,1]
	v_mov_b32_e32 v75, v69
	v_pk_mul_f32 v[90:91], v[80:81], 0 op_sel_hi:[1,0]
	v_pk_add_f32 v[8:9], v[8:9], v[100:101] neg_lo:[0,1] neg_hi:[0,1]
	v_pk_add_f32 v[68:69], v[80:81], v[90:91] op_sel:[0,1] op_sel_hi:[1,0] neg_lo:[0,1] neg_hi:[0,1]
	v_pk_add_f32 v[80:81], v[80:81], v[90:91] op_sel:[0,1] op_sel_hi:[1,0]
	v_pk_mul_f32 v[90:91], v[72:73], 0 op_sel_hi:[1,0]
	v_mov_b32_e32 v69, v81
	v_pk_add_f32 v[80:81], v[72:73], v[90:91] op_sel:[0,1] op_sel_hi:[1,0] neg_lo:[0,1] neg_hi:[0,1]
	v_pk_add_f32 v[72:73], v[72:73], v[90:91] op_sel:[0,1] op_sel_hi:[1,0]
	v_pk_add_f32 v[90:91], v[120:121], v[78:79]
	v_pk_add_f32 v[78:79], v[120:121], v[78:79] neg_lo:[0,1] neg_hi:[0,1]
	v_mov_b32_e32 v81, v73
	v_pk_mul_f32 v[92:93], v[78:79], 0 op_sel_hi:[1,0]
	v_pk_mul_f32 v[100:101], v[8:9], 0 op_sel_hi:[1,0]
	v_pk_add_f32 v[72:73], v[78:79], v[92:93] op_sel:[0,1] op_sel_hi:[1,0] neg_lo:[0,1] neg_hi:[0,1]
	v_pk_add_f32 v[78:79], v[78:79], v[92:93] op_sel:[0,1] op_sel_hi:[1,0]
	v_pk_add_f32 v[92:93], v[122:123], v[124:125] neg_lo:[0,1] neg_hi:[0,1]
	v_mov_b32_e32 v73, v79
	v_pk_mul_f32 v[98:99], v[92:93], 0 op_sel_hi:[1,0]
	v_pk_add_f32 v[96:97], v[122:123], v[124:125]
	v_pk_add_f32 v[78:79], v[92:93], v[98:99] op_sel:[0,1] op_sel_hi:[1,0] neg_lo:[0,1] neg_hi:[0,1]
	v_pk_add_f32 v[92:93], v[92:93], v[98:99] op_sel:[0,1] op_sel_hi:[1,0]
	v_pk_add_f32 v[98:99], v[118:119], v[114:115] neg_lo:[0,1] neg_hi:[0,1]
	v_mov_b32_e32 v79, v93
	v_pk_add_f32 v[92:93], v[118:119], v[114:115]
	v_pk_add_f32 v[114:115], v[8:9], v[100:101] op_sel:[0,1] op_sel_hi:[1,0] neg_lo:[0,1] neg_hi:[0,1]
	v_pk_add_f32 v[8:9], v[8:9], v[100:101] op_sel:[0,1] op_sel_hi:[1,0]
	v_mov_b32_e32 v115, v9
	v_pk_add_f32 v[8:9], v[10:11], v[102:103]
	v_pk_add_f32 v[10:11], v[10:11], v[102:103] neg_lo:[0,1] neg_hi:[0,1]
	v_pk_mul_f32 v[100:101], v[10:11], s[84:85] op_sel_hi:[1,0]
	v_pk_fma_f32 v[102:103], v[10:11], s[16:17], v[100:101] op_sel:[0,0,1] op_sel_hi:[1,0,0]
	v_pk_fma_f32 v[10:11], v[10:11], s[16:17], v[100:101] op_sel:[0,0,1] op_sel_hi:[1,0,0] neg_lo:[0,0,1] neg_hi:[0,0,1]
	v_mov_b32_e32 v103, v11
	v_pk_add_f32 v[10:11], v[12:13], v[104:105]
	v_pk_add_f32 v[12:13], v[12:13], v[104:105] neg_lo:[0,1] neg_hi:[0,1]
	v_pk_mul_f32 v[100:101], v[12:13], s[18:19] op_sel_hi:[1,0]
	v_pk_fma_f32 v[104:105], v[12:13], s[18:19], v[100:101] op_sel:[0,0,1] op_sel_hi:[1,0,0]
	v_pk_fma_f32 v[12:13], v[12:13], s[18:19], v[100:101] op_sel_hi:[1,0,0] neg_lo:[0,0,1] neg_hi:[0,0,1]
	v_mov_b32_e32 v105, v13
	v_pk_add_f32 v[12:13], v[14:15], v[106:107]
	v_pk_add_f32 v[14:15], v[14:15], v[106:107] neg_lo:[0,1] neg_hi:[0,1]
	v_pk_mul_f32 v[100:101], v[14:15], s[16:17] op_sel_hi:[1,0]
	v_pk_fma_f32 v[106:107], v[14:15], s[84:85], v[100:101] op_sel:[0,0,1] op_sel_hi:[1,0,0]
	v_pk_fma_f32 v[14:15], v[14:15], s[84:85], v[100:101] op_sel:[0,0,1] op_sel_hi:[1,0,0] neg_lo:[0,0,1] neg_hi:[0,0,1]
	v_mov_b32_e32 v107, v15
	v_pk_add_f32 v[14:15], v[0:1], v[16:17]
	v_pk_add_f32 v[0:1], v[0:1], v[16:17] neg_lo:[0,1] neg_hi:[0,1]
	v_pk_fma_f32 v[16:17], v[0:1], 0, v[0:1] op_sel:[0,0,1] op_sel_hi:[1,0,0]
	v_pk_fma_f32 v[0:1], v[0:1], 0, v[0:1] op_sel:[0,0,1] op_sel_hi:[1,0,0] neg_lo:[0,0,1] neg_hi:[0,0,1]
	v_mov_b32_e32 v17, v1
	v_pk_add_f32 v[0:1], v[2:3], v[18:19]
	v_pk_add_f32 v[2:3], v[2:3], v[18:19] neg_lo:[0,1] neg_hi:[0,1]
	v_pk_mul_f32 v[18:19], v[2:3], s[84:85] op_sel_hi:[0,1]
	v_pk_fma_f32 v[2:3], v[2:3], s[30:31], v[18:19] op_sel:[1,0,0] neg_lo:[0,0,1] neg_hi:[0,0,1]
	s_waitcnt lgkmcnt(0)
; template <int R, bool INV> DEV void dft_regs(cf (&v)[R]) {
; #pragma unroll
;     for (int s = R; s >= 2; s >>= 1) {
;         const int h = s >> 1;
; #pragma unroll
;         for (int b = 0; b < R; b += s) {
; #pragma unroll
;             for (int k = 0; k < h; ++k) {
;                 const cf a = v[b + k], c = v[b + k + h];
;                 v[b + k] = a + c;
;                 const cf d = a - c;
;                 const int m = k * (32 / s);
;                 const float wr = tw_cos(m), wi = INV ? tw_sin(m) : -tw_sin(m);
;                 v[b + k + h] = cf{d.x * wr - d.y * wi, d.x * wi + d.y * wr};
;             }
;         }
;     }
; DEV void fft_midx2(LAS cf* buf0, LAS cf* buf1, const unsigned* Kp, int blk) {
;     ...
;     for (int q = 0; q < 16; ++q) { v[q] = p0[q]; u[q] = p1[q]; }
;     dft_regs<16, false>(v); dft_regs<16, false>(u);
	v_pk_add_f32 v[18:19], v[4:5], v[108:109]
	v_pk_add_f32 v[4:5], v[4:5], v[108:109] neg_lo:[0,1] neg_hi:[0,1]
	v_mul_f32_e32 v100, 0x3f3504f3, v4
	v_pk_fma_f32 v[4:5], v[4:5], s[28:29], v[100:101] op_sel:[1,0,0] op_sel_hi:[1,1,0] neg_lo:[0,0,1] neg_hi:[0,0,1]
	v_pk_add_f32 v[100:101], v[6:7], v[110:111]
	v_pk_add_f32 v[6:7], v[6:7], v[110:111] neg_lo:[0,1] neg_hi:[0,1]
	v_pk_mul_f32 v[108:109], v[6:7], s[24:25] op_sel_hi:[0,1]
	v_pk_fma_f32 v[6:7], v[6:7], s[34:35], v[108:109] op_sel:[1,0,0] neg_lo:[0,0,1] neg_hi:[0,0,1]
	v_pk_add_f32 v[108:109], v[112:113], v[14:15]
	v_pk_add_f32 v[14:15], v[112:113], v[14:15] neg_lo:[0,1] neg_hi:[0,1]
	v_pk_mul_f32 v[110:111], v[14:15], 0 op_sel_hi:[1,0]
	v_pk_add_f32 v[112:113], v[14:15], v[110:111] op_sel:[0,1] op_sel_hi:[1,0] neg_lo:[0,1] neg_hi:[0,1]
	v_pk_add_f32 v[14:15], v[14:15], v[110:111] op_sel:[0,1] op_sel_hi:[1,0]
	v_mov_b32_e32 v113, v15
	v_pk_add_f32 v[14:15], v[8:9], v[0:1]
	v_pk_add_f32 v[0:1], v[8:9], v[0:1] neg_lo:[0,1] neg_hi:[0,1]
	v_pk_mul_f32 v[8:9], v[0:1], s[18:19] op_sel_hi:[1,0]
	v_pk_fma_f32 v[110:111], v[0:1], s[18:19], v[8:9] op_sel:[0,0,1] op_sel_hi:[1,0,0]
	v_pk_fma_f32 v[0:1], v[0:1], s[18:19], v[8:9] op_sel_hi:[1,0,0] neg_lo:[0,0,1] neg_hi:[0,0,1]
	v_pk_add_f32 v[8:9], v[10:11], v[18:19] neg_lo:[0,1] neg_hi:[0,1]
	v_mov_b32_e32 v111, v1
	v_pk_add_f32 v[0:1], v[10:11], v[18:19]
	v_pk_fma_f32 v[10:11], v[8:9], 0, v[8:9] op_sel:[0,0,1] op_sel_hi:[1,0,0]
	v_pk_fma_f32 v[8:9], v[8:9], 0, v[8:9] op_sel:[0,0,1] op_sel_hi:[1,0,0] neg_lo:[0,0,1] neg_hi:[0,0,1]
	v_mov_b32_e32 v11, v9
	v_pk_add_f32 v[8:9], v[12:13], v[100:101]
	v_pk_add_f32 v[12:13], v[12:13], v[100:101] neg_lo:[0,1] neg_hi:[0,1]
	v_mul_f32_e32 v18, 0x3f3504f3, v12
	v_pk_fma_f32 v[12:13], v[12:13], s[28:29], v[18:19] op_sel:[1,0,0] op_sel_hi:[1,1,0] neg_lo:[0,0,1] neg_hi:[0,0,1]
	v_pk_add_f32 v[18:19], v[114:115], v[16:17]
	v_pk_add_f32 v[16:17], v[114:115], v[16:17] neg_lo:[0,1] neg_hi:[0,1]
	v_pk_mul_f32 v[100:101], v[16:17], 0 op_sel_hi:[1,0]
	v_pk_add_f32 v[114:115], v[16:17], v[100:101] op_sel:[0,1] op_sel_hi:[1,0] neg_lo:[0,1] neg_hi:[0,1]
	v_pk_add_f32 v[16:17], v[16:17], v[100:101] op_sel:[0,1] op_sel_hi:[1,0]
	v_mov_b32_e32 v115, v17
	v_pk_add_f32 v[16:17], v[102:103], v[2:3]
	v_pk_add_f32 v[2:3], v[102:103], v[2:3] neg_lo:[0,1] neg_hi:[0,1]
	v_pk_mul_f32 v[100:101], v[2:3], s[18:19] op_sel_hi:[1,0]
	v_pk_fma_f32 v[102:103], v[2:3], s[18:19], v[100:101] op_sel:[0,0,1] op_sel_hi:[1,0,0]
	v_pk_fma_f32 v[2:3], v[2:3], s[18:19], v[100:101] op_sel_hi:[1,0,0] neg_lo:[0,0,1] neg_hi:[0,0,1]
	v_mov_b32_e32 v103, v3
	v_pk_add_f32 v[2:3], v[104:105], v[4:5]
	v_pk_add_f32 v[4:5], v[104:105], v[4:5] neg_lo:[0,1] neg_hi:[0,1]
	v_pk_fma_f32 v[100:101], v[4:5], 0, v[4:5] op_sel:[0,0,1] op_sel_hi:[1,0,0]
	v_pk_fma_f32 v[4:5], v[4:5], 0, v[4:5] op_sel:[0,0,1] op_sel_hi:[1,0,0] neg_lo:[0,0,1] neg_hi:[0,0,1]
	v_mov_b32_e32 v101, v5
	v_pk_add_f32 v[4:5], v[106:107], v[6:7]
	v_pk_add_f32 v[6:7], v[106:107], v[6:7] neg_lo:[0,1] neg_hi:[0,1]
	v_mul_f32_e32 v104, 0x3f3504f3, v6
	v_pk_fma_f32 v[6:7], v[6:7], s[28:29], v[104:105] op_sel:[1,0,0] op_sel_hi:[1,1,0] neg_lo:[0,0,1] neg_hi:[0,0,1]
	v_pk_add_f32 v[104:105], v[108:109], v[0:1]
	v_pk_add_f32 v[0:1], v[108:109], v[0:1] neg_lo:[0,1] neg_hi:[0,1]
	v_pk_add_f32 v[166:167], v[102:103], v[6:7]
	v_pk_mul_f32 v[106:107], v[0:1], 0 op_sel_hi:[1,0]
	v_pk_add_f32 v[6:7], v[102:103], v[6:7] neg_lo:[0,1] neg_hi:[0,1]
	v_pk_add_f32 v[108:109], v[0:1], v[106:107] op_sel:[0,1] op_sel_hi:[1,0] neg_lo:[0,1] neg_hi:[0,1]
	v_pk_add_f32 v[0:1], v[0:1], v[106:107] op_sel:[0,1] op_sel_hi:[1,0]
	v_pk_fma_f32 v[168:169], v[6:7], 0, v[6:7] op_sel:[0,0,1] op_sel_hi:[1,0,0]
	v_mov_b32_e32 v109, v1
	v_pk_add_f32 v[0:1], v[14:15], v[8:9]
	v_pk_add_f32 v[8:9], v[14:15], v[8:9] neg_lo:[0,1] neg_hi:[0,1]
	v_pk_fma_f32 v[6:7], v[6:7], 0, v[6:7] op_sel:[0,0,1] op_sel_hi:[1,0,0] neg_lo:[0,0,1] neg_hi:[0,0,1]
	v_pk_fma_f32 v[14:15], v[8:9], 0, v[8:9] op_sel:[0,0,1] op_sel_hi:[1,0,0]
	v_pk_fma_f32 v[8:9], v[8:9], 0, v[8:9] op_sel:[0,0,1] op_sel_hi:[1,0,0] neg_lo:[0,0,1] neg_hi:[0,0,1]
	v_pk_add_f32 v[122:123], v[104:105], v[0:1]
	v_mov_b32_e32 v15, v9
	v_pk_add_f32 v[8:9], v[112:113], v[10:11]
	v_pk_add_f32 v[10:11], v[112:113], v[10:11] neg_lo:[0,1] neg_hi:[0,1]
	v_pk_add_f32 v[0:1], v[104:105], v[0:1] neg_lo:[0,1] neg_hi:[0,1]
	v_pk_mul_f32 v[106:107], v[10:11], 0 op_sel_hi:[1,0]
	v_mov_b32_e32 v169, v7
	v_pk_add_f32 v[116:117], v[10:11], v[106:107] op_sel:[0,1] op_sel_hi:[1,0] neg_lo:[0,1] neg_hi:[0,1]
	v_pk_add_f32 v[10:11], v[10:11], v[106:107] op_sel:[0,1] op_sel_hi:[1,0]
	v_pk_mul_f32 v[6:7], v[0:1], 0 op_sel_hi:[1,0]
	v_mov_b32_e32 v117, v11
	v_pk_add_f32 v[10:11], v[110:111], v[12:13]
	v_pk_add_f32 v[12:13], v[110:111], v[12:13] neg_lo:[0,1] neg_hi:[0,1]
	v_pk_add_f32 v[106:107], v[0:1], v[6:7] op_sel:[0,1] op_sel_hi:[1,0] neg_lo:[0,1] neg_hi:[0,1]
	v_pk_fma_f32 v[110:111], v[12:13], 0, v[12:13] op_sel:[0,0,1] op_sel_hi:[1,0,0]
	v_pk_fma_f32 v[12:13], v[12:13], 0, v[12:13] op_sel:[0,0,1] op_sel_hi:[1,0,0] neg_lo:[0,0,1] neg_hi:[0,0,1]
	v_pk_add_f32 v[0:1], v[0:1], v[6:7] op_sel:[0,1] op_sel_hi:[1,0]
	v_mov_b32_e32 v111, v13
	v_pk_add_f32 v[12:13], v[18:19], v[2:3]
	v_pk_add_f32 v[2:3], v[18:19], v[2:3] neg_lo:[0,1] neg_hi:[0,1]
	v_mov_b32_e32 v107, v1
	v_pk_mul_f32 v[18:19], v[2:3], 0 op_sel_hi:[1,0]
	v_pk_add_f32 v[0:1], v[108:109], v[14:15] neg_lo:[0,1] neg_hi:[0,1]
	v_pk_add_f32 v[124:125], v[2:3], v[18:19] op_sel:[0,1] op_sel_hi:[1,0] neg_lo:[0,1] neg_hi:[0,1]
	v_pk_add_f32 v[2:3], v[2:3], v[18:19] op_sel:[0,1] op_sel_hi:[1,0]
	v_pk_mul_f32 v[6:7], v[0:1], 0 op_sel_hi:[1,0]
	v_mov_b32_e32 v125, v3
; DEV cf kunpack(unsigned w) { return cf{U2F(w << 16), U2F(w & 0xffff0000u)}; }
; DEV void fft_midx2(LAS cf* buf0, LAS cf* buf1, const unsigned* Kp, int blk) {
;     ...
;     dft_regs<16, false>(v); dft_regs<16, false>(u);
;     cf w[16], x[16];
;     u32x4 kw[4];
; #pragma unroll
;     for (int j = 0; j < 4; ++j) kw[j] = *(const u32x4*)(Kp + base + 4 * j);
; #pragma unroll
;     for (int p = 0; p < 16; ++p) { const cf k = kunpack(kw[p >> 2][p & 3]); w[p] = cmul(v[BR16[p]], k); x[p] = cmul(u[BR16[p]], k); }
	v_pk_add_f32 v[2:3], v[16:17], v[4:5]
	v_pk_add_f32 v[4:5], v[16:17], v[4:5] neg_lo:[0,1] neg_hi:[0,1]
	v_pk_add_f32 v[16:17], v[114:115], v[100:101] neg_lo:[0,1] neg_hi:[0,1]
	v_pk_fma_f32 v[164:165], v[4:5], 0, v[4:5] op_sel:[0,0,1] op_sel_hi:[1,0,0]
	v_pk_fma_f32 v[4:5], v[4:5], 0, v[4:5] op_sel:[0,0,1] op_sel_hi:[1,0,0] neg_lo:[0,0,1] neg_hi:[0,0,1]
	v_pk_mul_f32 v[18:19], v[16:17], 0 op_sel_hi:[1,0]
	v_mov_b32_e32 v165, v5
	v_pk_add_f32 v[4:5], v[114:115], v[100:101]
	v_pk_add_f32 v[100:101], v[16:17], v[18:19] op_sel:[0,1] op_sel_hi:[1,0] neg_lo:[0,1] neg_hi:[0,1]
	v_pk_add_f32 v[16:17], v[16:17], v[18:19] op_sel:[0,1] op_sel_hi:[1,0]
	v_pk_add_f32 v[18:19], v[0:1], v[6:7] op_sel:[0,1] op_sel_hi:[1,0] neg_lo:[0,1] neg_hi:[0,1]
	v_pk_add_f32 v[0:1], v[0:1], v[6:7] op_sel:[0,1] op_sel_hi:[1,0]
	v_mov_b32_e32 v101, v17
	v_mov_b32_e32 v19, v1
	v_pk_add_f32 v[0:1], v[8:9], v[10:11] neg_lo:[0,1] neg_hi:[0,1]
	v_pk_add_f32 v[126:127], v[12:13], v[2:3]
	v_pk_mul_f32 v[6:7], v[0:1], 0 op_sel_hi:[1,0]
	v_pk_add_f32 v[112:113], v[116:117], v[110:111]
	v_pk_add_f32 v[104:105], v[0:1], v[6:7] op_sel:[0,1] op_sel_hi:[1,0] neg_lo:[0,1] neg_hi:[0,1]
	v_pk_add_f32 v[0:1], v[0:1], v[6:7] op_sel:[0,1] op_sel_hi:[1,0]
	v_pk_add_f32 v[114:115], v[108:109], v[14:15]
	v_mov_b32_e32 v105, v1
	v_pk_add_f32 v[0:1], v[116:117], v[110:111] neg_lo:[0,1] neg_hi:[0,1]
	v_pk_add_f32 v[116:117], v[100:101], v[168:169]
	v_pk_mul_f32 v[6:7], v[0:1], 0 op_sel_hi:[1,0]
	v_pk_add_f32 v[120:121], v[8:9], v[10:11]
	v_pk_add_f32 v[16:17], v[0:1], v[6:7] op_sel:[0,1] op_sel_hi:[1,0] neg_lo:[0,1] neg_hi:[0,1]
	v_pk_add_f32 v[0:1], v[0:1], v[6:7] op_sel:[0,1] op_sel_hi:[1,0]
	v_pk_add_f32 v[118:119], v[124:125], v[164:165]
	v_mov_b32_e32 v17, v1
	v_pk_add_f32 v[0:1], v[12:13], v[2:3] neg_lo:[0,1] neg_hi:[0,1]
	v_pk_mul_f32 v[2:3], v[0:1], 0 op_sel_hi:[1,0]
	s_mov_b32 s28, s95
	v_pk_add_f32 v[110:111], v[0:1], v[2:3] op_sel:[0,1] op_sel_hi:[1,0] neg_lo:[0,1] neg_hi:[0,1]
	v_pk_add_f32 v[0:1], v[0:1], v[2:3] op_sel:[0,1] op_sel_hi:[1,0]
	s_mov_b32 s29, s94
	v_mov_b32_e32 v111, v1
	v_pk_add_f32 v[0:1], v[124:125], v[164:165] neg_lo:[0,1] neg_hi:[0,1]
	v_pk_add_f32 v[124:125], v[4:5], v[166:167]
	v_pk_mul_f32 v[2:3], v[0:1], 0 op_sel_hi:[1,0]
	v_pk_mul_f32 v[164:165], v[98:99], 0 op_sel_hi:[1,0]
	v_pk_add_f32 v[102:103], v[0:1], v[2:3] op_sel:[0,1] op_sel_hi:[1,0] neg_lo:[0,1] neg_hi:[0,1]
	v_pk_add_f32 v[0:1], v[0:1], v[2:3] op_sel:[0,1] op_sel_hi:[1,0]
	v_mov_b32_e32 v103, v1
	v_pk_add_f32 v[0:1], v[4:5], v[166:167] neg_lo:[0,1] neg_hi:[0,1]
	v_pk_add_f32 v[166:167], v[98:99], v[164:165] op_sel:[0,1] op_sel_hi:[1,0] neg_lo:[0,1] neg_hi:[0,1]
	v_pk_mul_f32 v[2:3], v[0:1], 0 op_sel_hi:[1,0]
	v_pk_add_f32 v[98:99], v[98:99], v[164:165] op_sel:[0,1] op_sel_hi:[1,0]
	v_pk_add_f32 v[108:109], v[0:1], v[2:3] op_sel:[0,1] op_sel_hi:[1,0] neg_lo:[0,1] neg_hi:[0,1]
	v_pk_add_f32 v[0:1], v[0:1], v[2:3] op_sel:[0,1] op_sel_hi:[1,0]
	v_mov_b32_e32 v167, v99
	v_mov_b32_e32 v109, v1
	v_pk_add_f32 v[0:1], v[100:101], v[168:169] neg_lo:[0,1] neg_hi:[0,1]
	v_pk_mul_f32 v[2:3], v[0:1], 0 op_sel_hi:[1,0]
	v_pk_add_f32 v[100:101], v[0:1], v[2:3] op_sel:[0,1] op_sel_hi:[1,0] neg_lo:[0,1] neg_hi:[0,1]
	v_pk_add_f32 v[0:1], v[0:1], v[2:3] op_sel:[0,1] op_sel_hi:[1,0]
	v_mov_b32_e32 v101, v1
	s_nop 0
	s_waitcnt vmcnt(0)
	v_lshlrev_b32_e32 v98, 16, v182
	v_and_b32_e32 v99, 0xffff0000, v182
	v_lshlrev_b32_e32 v12, 16, v183
	v_and_b32_e32 v13, 0xffff0000, v183
	v_pk_mul_f32 v[168:169], v[86:87], v[98:99] op_sel:[1,1] op_sel_hi:[1,0] neg_lo:[1,0]
	v_pk_fma_f32 v[164:165], v[86:87], v[98:99], v[168:169] op_sel_hi:[0,1,1]
	s_nop 0
	v_pk_mul_f32 v[168:169], v[122:123], v[98:99] op_sel:[1,1] op_sel_hi:[1,0] neg_lo:[1,0]
	v_pk_fma_f32 v[86:87], v[122:123], v[98:99], v[168:169] op_sel_hi:[0,1,1]
	v_pk_mul_f32 v[98:99], v[94:95], v[12:13] op_sel:[1,1] op_sel_hi:[1,0] neg_lo:[1,0]
	v_pk_fma_f32 v[94:95], v[94:95], v[12:13], v[98:99] op_sel_hi:[0,1,1]
	s_nop 0
	v_pk_mul_f32 v[98:99], v[126:127], v[12:13] op_sel:[1,1] op_sel_hi:[1,0] neg_lo:[1,0]
	v_pk_fma_f32 v[12:13], v[126:127], v[12:13], v[98:99] op_sel_hi:[0,1,1]
	s_nop 0
	v_lshlrev_b32_e32 v98, 16, v184
	v_and_b32_e32 v99, 0xffff0000, v184
	v_lshlrev_b32_e32 v14, 16, v185
	v_and_b32_e32 v15, 0xffff0000, v185
	v_pk_mul_f32 v[126:127], v[88:89], v[98:99] op_sel:[1,1] op_sel_hi:[1,0] neg_lo:[1,0]
	v_pk_fma_f32 v[122:123], v[88:89], v[98:99], v[126:127] op_sel_hi:[0,1,1]
	s_nop 0
	v_pk_mul_f32 v[126:127], v[120:121], v[98:99] op_sel:[1,1] op_sel_hi:[1,0] neg_lo:[1,0]
	v_pk_fma_f32 v[88:89], v[120:121], v[98:99], v[126:127] op_sel_hi:[0,1,1]
	v_pk_mul_f32 v[98:99], v[96:97], v[14:15] op_sel:[1,1] op_sel_hi:[1,0] neg_lo:[1,0]
	v_pk_fma_f32 v[96:97], v[96:97], v[14:15], v[98:99] op_sel_hi:[0,1,1]
	s_nop 0
	v_pk_mul_f32 v[98:99], v[124:125], v[14:15] op_sel:[1,1] op_sel_hi:[1,0] neg_lo:[1,0]
	v_pk_fma_f32 v[14:15], v[124:125], v[14:15], v[98:99] op_sel_hi:[0,1,1]
	s_nop 0
	v_lshlrev_b32_e32 v98, 16, v178
	v_and_b32_e32 v99, 0xffff0000, v178
	v_lshlrev_b32_e32 v8, 16, v179
	v_and_b32_e32 v9, 0xffff0000, v179
	v_pk_mul_f32 v[124:125], v[82:83], v[98:99] op_sel:[1,1] op_sel_hi:[1,0] neg_lo:[1,0]
	v_pk_fma_f32 v[120:121], v[82:83], v[98:99], v[124:125] op_sel_hi:[0,1,1]
	s_nop 0
	v_pk_mul_f32 v[124:125], v[114:115], v[98:99] op_sel:[1,1] op_sel_hi:[1,0] neg_lo:[1,0]
	v_pk_fma_f32 v[82:83], v[114:115], v[98:99], v[124:125] op_sel_hi:[0,1,1]
	v_pk_mul_f32 v[98:99], v[90:91], v[8:9] op_sel:[1,1] op_sel_hi:[1,0] neg_lo:[1,0]
	v_pk_fma_f32 v[90:91], v[90:91], v[8:9], v[98:99] op_sel_hi:[0,1,1]
	s_nop 0
	v_pk_mul_f32 v[98:99], v[118:119], v[8:9] op_sel:[1,1] op_sel_hi:[1,0] neg_lo:[1,0]
; DEV cf kunpack(unsigned w) { return cf{U2F(w << 16), U2F(w & 0xffff0000u)}; }
; DEV void fft_midx2(LAS cf* buf0, LAS cf* buf1, const unsigned* Kp, int blk) {
;     ...
;     for (int p = 0; p < 16; ++p) { const cf k = kunpack(kw[p >> 2][p & 3]); w[p] = cmul(v[BR16[p]], k); x[p] = cmul(u[BR16[p]], k); }
;     dft_regs<16, true>(w); dft_regs<16, true>(x);
	v_pk_fma_f32 v[8:9], v[118:119], v[8:9], v[98:99] op_sel_hi:[0,1,1]
	s_nop 0
	v_lshlrev_b32_e32 v98, 16, v180
	v_and_b32_e32 v99, 0xffff0000, v180
	v_lshlrev_b32_e32 v10, 16, v181
	v_and_b32_e32 v11, 0xffff0000, v181
	v_pk_mul_f32 v[118:119], v[84:85], v[98:99] op_sel:[1,1] op_sel_hi:[1,0] neg_lo:[1,0]
	v_pk_fma_f32 v[114:115], v[84:85], v[98:99], v[118:119] op_sel_hi:[0,1,1]
	s_nop 0
	v_pk_mul_f32 v[118:119], v[112:113], v[98:99] op_sel:[1,1] op_sel_hi:[1,0] neg_lo:[1,0]
	v_pk_fma_f32 v[84:85], v[112:113], v[98:99], v[118:119] op_sel_hi:[0,1,1]
	v_pk_mul_f32 v[98:99], v[92:93], v[10:11] op_sel:[1,1] op_sel_hi:[1,0] neg_lo:[1,0]
	v_pk_fma_f32 v[92:93], v[92:93], v[10:11], v[98:99] op_sel_hi:[0,1,1]
	s_nop 0
	v_pk_mul_f32 v[98:99], v[116:117], v[10:11] op_sel:[1,1] op_sel_hi:[1,0] neg_lo:[1,0]
	v_pk_fma_f32 v[10:11], v[116:117], v[10:11], v[98:99] op_sel_hi:[0,1,1]
	s_nop 0
	v_lshlrev_b32_e32 v98, 16, v174
	v_and_b32_e32 v99, 0xffff0000, v174
	v_pk_mul_f32 v[112:113], v[76:77], v[98:99] op_sel:[1,1] op_sel_hi:[1,0] neg_lo:[1,0]
	v_pk_fma_f32 v[76:77], v[76:77], v[98:99], v[112:113] op_sel_hi:[0,1,1]
	v_lshlrev_b32_e32 v4, 16, v175
	v_pk_mul_f32 v[112:113], v[106:107], v[98:99] op_sel:[1,1] op_sel_hi:[1,0] neg_lo:[1,0]
	v_pk_fma_f32 v[98:99], v[106:107], v[98:99], v[112:113] op_sel_hi:[0,1,1]
	v_and_b32_e32 v5, 0xffff0000, v175
	v_pk_mul_f32 v[106:107], v[80:81], v[4:5] op_sel:[1,1] op_sel_hi:[1,0] neg_lo:[1,0]
	v_pk_fma_f32 v[80:81], v[80:81], v[4:5], v[106:107] op_sel_hi:[0,1,1]
	s_nop 0
	v_pk_mul_f32 v[112:113], v[110:111], v[4:5] op_sel:[1,1] op_sel_hi:[1,0] neg_lo:[1,0]
	v_pk_fma_f32 v[106:107], v[110:111], v[4:5], v[112:113] op_sel_hi:[0,1,1]
	v_lshlrev_b32_e32 v4, 16, v176
	v_and_b32_e32 v5, 0xffff0000, v176
	v_pk_mul_f32 v[110:111], v[74:75], v[4:5] op_sel:[1,1] op_sel_hi:[1,0] neg_lo:[1,0]
	v_pk_fma_f32 v[74:75], v[74:75], v[4:5], v[110:111] op_sel_hi:[0,1,1]
	s_nop 0
	v_pk_mul_f32 v[110:111], v[104:105], v[4:5] op_sel:[1,1] op_sel_hi:[1,0] neg_lo:[1,0]
	v_pk_fma_f32 v[104:105], v[104:105], v[4:5], v[110:111] op_sel_hi:[0,1,1]
	v_lshlrev_b32_e32 v4, 16, v177
	v_and_b32_e32 v5, 0xffff0000, v177
	v_pk_mul_f32 v[110:111], v[78:79], v[4:5] op_sel:[1,1] op_sel_hi:[1,0] neg_lo:[1,0]
	v_pk_fma_f32 v[6:7], v[78:79], v[4:5], v[110:111] op_sel_hi:[0,1,1]
	v_pk_mul_f32 v[78:79], v[108:109], v[4:5] op_sel:[1,1] op_sel_hi:[1,0] neg_lo:[1,0]
	v_pk_fma_f32 v[108:109], v[108:109], v[4:5], v[78:79] op_sel_hi:[0,1,1]
	v_lshlrev_b32_e32 v4, 16, v170
	v_and_b32_e32 v5, 0xffff0000, v170
	v_lshlrev_b32_e32 v0, 16, v171
	v_and_b32_e32 v1, 0xffff0000, v171
	v_pk_mul_f32 v[78:79], v[70:71], v[4:5] op_sel:[1,1] op_sel_hi:[1,0] neg_lo:[1,0]
	v_pk_fma_f32 v[70:71], v[70:71], v[4:5], v[78:79] op_sel_hi:[0,1,1]
	s_nop 0
	v_pk_mul_f32 v[78:79], v[18:19], v[4:5] op_sel:[1,1] op_sel_hi:[1,0] neg_lo:[1,0]
	v_pk_fma_f32 v[110:111], v[18:19], v[4:5], v[78:79] op_sel_hi:[0,1,1]
	v_pk_mul_f32 v[18:19], v[72:73], v[0:1] op_sel:[1,1] op_sel_hi:[1,0] neg_lo:[1,0]
	v_pk_fma_f32 v[4:5], v[72:73], v[0:1], v[18:19] op_sel_hi:[0,1,1]
	s_nop 0
	v_pk_mul_f32 v[18:19], v[102:103], v[0:1] op_sel:[1,1] op_sel_hi:[1,0] neg_lo:[1,0]
	v_pk_fma_f32 v[102:103], v[102:103], v[0:1], v[18:19] op_sel_hi:[0,1,1]
	v_lshlrev_b32_e32 v0, 16, v172
	v_and_b32_e32 v1, 0xffff0000, v172
	v_pk_mul_f32 v[72:73], v[68:69], v[0:1] op_sel:[1,1] op_sel_hi:[1,0] neg_lo:[1,0]
	v_pk_fma_f32 v[18:19], v[68:69], v[0:1], v[72:73] op_sel_hi:[0,1,1]
	v_pk_mul_f32 v[68:69], v[16:17], v[0:1] op_sel:[1,1] op_sel_hi:[1,0] neg_lo:[1,0]
	v_pk_fma_f32 v[112:113], v[16:17], v[0:1], v[68:69] op_sel_hi:[0,1,1]
	v_lshlrev_b32_e32 v0, 16, v173
	v_and_b32_e32 v1, 0xffff0000, v173
	v_pk_mul_f32 v[16:17], v[166:167], v[0:1] op_sel:[1,1] op_sel_hi:[1,0] neg_lo:[1,0]
	v_pk_fma_f32 v[2:3], v[166:167], v[0:1], v[16:17] op_sel_hi:[0,1,1]
	s_nop 0
	v_pk_mul_f32 v[16:17], v[100:101], v[0:1] op_sel:[1,1] op_sel_hi:[1,0] neg_lo:[1,0]
	v_pk_fma_f32 v[100:101], v[100:101], v[0:1], v[16:17] op_sel_hi:[0,1,1]
	v_pk_add_f32 v[0:1], v[164:165], v[76:77]
	v_pk_add_f32 v[16:17], v[164:165], v[76:77] neg_lo:[0,1] neg_hi:[0,1]
	v_pk_mul_f32 v[68:69], v[16:17], 0 op_sel_hi:[1,0]
	v_pk_add_f32 v[72:73], v[16:17], v[68:69] op_sel:[0,1] op_sel_hi:[1,0]
	v_pk_add_f32 v[16:17], v[16:17], v[68:69] op_sel:[0,1] op_sel_hi:[1,0] neg_lo:[0,1] neg_hi:[0,1]
	v_pk_add_f32 v[68:69], v[94:95], v[80:81] neg_lo:[0,1] neg_hi:[0,1]
	v_mov_b32_e32 v73, v17
	v_pk_mul_f32 v[76:77], v[68:69], s[84:85] op_sel_hi:[1,0]
	v_pk_add_f32 v[16:17], v[94:95], v[80:81]
	v_pk_fma_f32 v[78:79], v[68:69], s[16:17], v[76:77] op_sel:[0,0,1] op_sel_hi:[1,0,0] neg_lo:[0,0,1] neg_hi:[0,0,1]
	v_pk_fma_f32 v[68:69], v[68:69], s[16:17], v[76:77] op_sel:[0,0,1] op_sel_hi:[1,0,0]
	v_mov_b32_e32 v79, v69
	v_pk_add_f32 v[68:69], v[122:123], v[74:75]
	v_pk_add_f32 v[74:75], v[122:123], v[74:75] neg_lo:[0,1] neg_hi:[0,1]
	v_pk_mul_f32 v[76:77], v[74:75], s[18:19] op_sel_hi:[1,0]
	v_pk_fma_f32 v[80:81], v[74:75], s[18:19], v[76:77] op_sel:[0,0,1] op_sel_hi:[1,0,0] neg_lo:[0,0,1] neg_hi:[0,0,1]
	v_pk_fma_f32 v[74:75], v[74:75], s[18:19], v[76:77] op_sel_hi:[1,0,0]
	v_mov_b32_e32 v81, v75
	v_pk_add_f32 v[74:75], v[96:97], v[6:7]
	v_pk_add_f32 v[6:7], v[96:97], v[6:7] neg_lo:[0,1] neg_hi:[0,1]
	v_pk_mul_f32 v[76:77], v[6:7], s[16:17] op_sel_hi:[1,0]
	v_pk_fma_f32 v[94:95], v[6:7], s[84:85], v[76:77] op_sel:[0,0,1] op_sel_hi:[1,0,0] neg_lo:[0,0,1] neg_hi:[0,0,1]
	v_pk_fma_f32 v[6:7], v[6:7], s[84:85], v[76:77] op_sel:[0,0,1] op_sel_hi:[1,0,0]
	v_mov_b32_e32 v95, v7
	v_pk_add_f32 v[6:7], v[120:121], v[70:71]
	v_pk_add_f32 v[70:71], v[120:121], v[70:71] neg_lo:[0,1] neg_hi:[0,1]
; template <int R, bool INV> DEV void dft_regs(cf (&v)[R]) {
; #pragma unroll
;     for (int s = R; s >= 2; s >>= 1) {
;         const int h = s >> 1;
; #pragma unroll
;         for (int b = 0; b < R; b += s) {
; #pragma unroll
;             for (int k = 0; k < h; ++k) {
;                 const cf a = v[b + k], c = v[b + k + h];
;                 v[b + k] = a + c;
;                 const cf d = a - c;
;                 const int m = k * (32 / s);
;                 const float wr = tw_cos(m), wi = INV ? tw_sin(m) : -tw_sin(m);
;                 v[b + k + h] = cf{d.x * wr - d.y * wi, d.x * wi + d.y * wr};
;             }
;         }
;     }
; DEV void fft_midx2(LAS cf* buf0, LAS cf* buf1, const unsigned* Kp, int blk) {
;     ...
;     dft_regs<16, true>(w); dft_regs<16, true>(x);
	v_pk_fma_f32 v[76:77], v[70:71], 0, v[70:71] op_sel:[0,0,1] op_sel_hi:[1,0,0] neg_lo:[0,0,1] neg_hi:[0,0,1]
	v_pk_fma_f32 v[70:71], v[70:71], 0, v[70:71] op_sel:[0,0,1] op_sel_hi:[1,0,0]
	v_mov_b32_e32 v77, v71
	v_pk_add_f32 v[70:71], v[90:91], v[4:5]
	v_pk_add_f32 v[4:5], v[90:91], v[4:5] neg_lo:[0,1] neg_hi:[0,1]
	v_pk_mul_f32 v[90:91], v[4:5], s[24:25] op_sel:[1,0]
	v_pk_fma_f32 v[4:5], v[4:5], s[0:1], v[90:91] op_sel_hi:[0,1,1] neg_lo:[0,0,1] neg_hi:[0,0,1]
	v_pk_add_f32 v[90:91], v[114:115], v[18:19]
	v_pk_add_f32 v[18:19], v[114:115], v[18:19] neg_lo:[0,1] neg_hi:[0,1]
	v_mul_f32_e32 v96, 0x3f3504f3, v19
	v_pk_fma_f32 v[18:19], v[18:19], s[96:97], v[96:97] op_sel_hi:[0,1,0] neg_lo:[0,0,1] neg_hi:[0,0,1]
	v_pk_add_f32 v[96:97], v[92:93], v[2:3]
	v_pk_add_f32 v[2:3], v[92:93], v[2:3] neg_lo:[0,1] neg_hi:[0,1]
	v_pk_mul_f32 v[92:93], v[2:3], s[84:85] op_sel:[1,0]
	v_pk_fma_f32 v[2:3], v[2:3], s[88:89], v[92:93] op_sel_hi:[0,1,1] neg_lo:[0,0,1] neg_hi:[0,0,1]
	v_pk_add_f32 v[92:93], v[0:1], v[6:7]
	v_pk_add_f32 v[0:1], v[0:1], v[6:7] neg_lo:[0,1] neg_hi:[0,1]
	v_pk_mul_f32 v[6:7], v[0:1], 0 op_sel_hi:[1,0]
	v_pk_add_f32 v[114:115], v[0:1], v[6:7] op_sel:[0,1] op_sel_hi:[1,0]
	v_pk_add_f32 v[0:1], v[0:1], v[6:7] op_sel:[0,1] op_sel_hi:[1,0] neg_lo:[0,1] neg_hi:[0,1]
	v_pk_add_f32 v[6:7], v[16:17], v[70:71] neg_lo:[0,1] neg_hi:[0,1]
	v_mov_b32_e32 v115, v1
	v_pk_add_f32 v[0:1], v[16:17], v[70:71]
	v_pk_mul_f32 v[16:17], v[6:7], s[18:19] op_sel_hi:[1,0]
	v_pk_fma_f32 v[70:71], v[6:7], s[18:19], v[16:17] op_sel:[0,0,1] op_sel_hi:[1,0,0] neg_lo:[0,0,1] neg_hi:[0,0,1]
	v_pk_fma_f32 v[6:7], v[6:7], s[18:19], v[16:17] op_sel_hi:[1,0,0]
	v_pk_add_f32 v[16:17], v[68:69], v[90:91] neg_lo:[0,1] neg_hi:[0,1]
	v_mov_b32_e32 v71, v7
	v_pk_add_f32 v[6:7], v[68:69], v[90:91]
	v_pk_fma_f32 v[68:69], v[16:17], 0, v[16:17] op_sel:[0,0,1] op_sel_hi:[1,0,0] neg_lo:[0,0,1] neg_hi:[0,0,1]
	v_pk_fma_f32 v[16:17], v[16:17], 0, v[16:17] op_sel:[0,0,1] op_sel_hi:[1,0,0]
	v_mov_b32_e32 v69, v17
	v_pk_add_f32 v[16:17], v[74:75], v[96:97]
	v_pk_add_f32 v[74:75], v[74:75], v[96:97] neg_lo:[0,1] neg_hi:[0,1]
	v_mul_f32_e32 v90, 0x3f3504f3, v75
	v_pk_fma_f32 v[74:75], v[74:75], s[96:97], v[90:91] op_sel_hi:[0,1,0] neg_lo:[0,0,1] neg_hi:[0,0,1]
	v_pk_add_f32 v[90:91], v[72:73], v[76:77]
	v_pk_add_f32 v[72:73], v[72:73], v[76:77] neg_lo:[0,1] neg_hi:[0,1]
	v_pk_mul_f32 v[76:77], v[72:73], 0 op_sel_hi:[1,0]
	v_pk_add_f32 v[96:97], v[72:73], v[76:77] op_sel:[0,1] op_sel_hi:[1,0]
	v_pk_add_f32 v[72:73], v[72:73], v[76:77] op_sel:[0,1] op_sel_hi:[1,0] neg_lo:[0,1] neg_hi:[0,1]
	v_mov_b32_e32 v97, v73
	v_pk_add_f32 v[72:73], v[78:79], v[4:5]
	v_pk_add_f32 v[4:5], v[78:79], v[4:5] neg_lo:[0,1] neg_hi:[0,1]
	v_pk_mul_f32 v[76:77], v[4:5], s[18:19] op_sel_hi:[1,0]
	v_pk_fma_f32 v[78:79], v[4:5], s[18:19], v[76:77] op_sel:[0,0,1] op_sel_hi:[1,0,0] neg_lo:[0,0,1] neg_hi:[0,0,1]
	v_pk_fma_f32 v[4:5], v[4:5], s[18:19], v[76:77] op_sel_hi:[1,0,0]
	v_mov_b32_e32 v79, v5
	v_pk_add_f32 v[4:5], v[80:81], v[18:19]
	v_pk_add_f32 v[18:19], v[80:81], v[18:19] neg_lo:[0,1] neg_hi:[0,1]
	v_pk_add_f32 v[116:117], v[90:91], v[4:5]
	v_pk_fma_f32 v[76:77], v[18:19], 0, v[18:19] op_sel:[0,0,1] op_sel_hi:[1,0,0] neg_lo:[0,0,1] neg_hi:[0,0,1]
	v_pk_fma_f32 v[18:19], v[18:19], 0, v[18:19] op_sel:[0,0,1] op_sel_hi:[1,0,0]
	v_pk_add_f32 v[4:5], v[90:91], v[4:5] neg_lo:[0,1] neg_hi:[0,1]
	v_mov_b32_e32 v77, v19
	v_pk_add_f32 v[18:19], v[94:95], v[2:3]
	v_pk_add_f32 v[2:3], v[94:95], v[2:3] neg_lo:[0,1] neg_hi:[0,1]
	v_pk_add_f32 v[118:119], v[72:73], v[18:19]
	v_mul_f32_e32 v80, 0x3f3504f3, v3
	v_pk_fma_f32 v[2:3], v[2:3], s[96:97], v[80:81] op_sel_hi:[0,1,0] neg_lo:[0,0,1] neg_hi:[0,0,1]
	v_pk_add_f32 v[80:81], v[92:93], v[6:7]
	v_pk_add_f32 v[6:7], v[92:93], v[6:7] neg_lo:[0,1] neg_hi:[0,1]
	v_pk_add_f32 v[122:123], v[78:79], v[2:3]
	v_pk_mul_f32 v[92:93], v[6:7], 0 op_sel_hi:[1,0]
	v_pk_add_f32 v[2:3], v[78:79], v[2:3] neg_lo:[0,1] neg_hi:[0,1]
	v_pk_add_f32 v[94:95], v[6:7], v[92:93] op_sel:[0,1] op_sel_hi:[1,0]
	v_pk_add_f32 v[6:7], v[6:7], v[92:93] op_sel:[0,1] op_sel_hi:[1,0] neg_lo:[0,1] neg_hi:[0,1]
	v_pk_fma_f32 v[78:79], v[2:3], 0, v[2:3] op_sel:[0,0,1] op_sel_hi:[1,0,0] neg_lo:[0,0,1] neg_hi:[0,0,1]
	v_mov_b32_e32 v95, v7
	v_pk_add_f32 v[6:7], v[0:1], v[16:17]
	v_pk_add_f32 v[0:1], v[0:1], v[16:17] neg_lo:[0,1] neg_hi:[0,1]
	v_pk_fma_f32 v[2:3], v[2:3], 0, v[2:3] op_sel:[0,0,1] op_sel_hi:[1,0,0]
	v_pk_fma_f32 v[16:17], v[0:1], 0, v[0:1] op_sel:[0,0,1] op_sel_hi:[1,0,0] neg_lo:[0,0,1] neg_hi:[0,0,1]
	v_pk_fma_f32 v[0:1], v[0:1], 0, v[0:1] op_sel:[0,0,1] op_sel_hi:[1,0,0]
	v_pk_add_f32 v[120:121], v[96:97], v[76:77]
	v_mov_b32_e32 v17, v1
	v_pk_add_f32 v[0:1], v[114:115], v[68:69]
	v_pk_add_f32 v[68:69], v[114:115], v[68:69] neg_lo:[0,1] neg_hi:[0,1]
	v_mov_b32_e32 v79, v3
	v_pk_mul_f32 v[92:93], v[68:69], 0 op_sel_hi:[1,0]
	v_pk_add_f32 v[2:3], v[80:81], v[6:7] neg_lo:[0,1] neg_hi:[0,1]
	v_pk_add_f32 v[114:115], v[68:69], v[92:93] op_sel:[0,1] op_sel_hi:[1,0]
	v_pk_add_f32 v[68:69], v[68:69], v[92:93] op_sel:[0,1] op_sel_hi:[1,0] neg_lo:[0,1] neg_hi:[0,1]
	v_pk_add_f32 v[92:93], v[70:71], v[74:75]
	v_mov_b32_e32 v115, v69
	v_pk_add_f32 v[68:69], v[70:71], v[74:75] neg_lo:[0,1] neg_hi:[0,1]
	v_pk_add_f32 v[124:125], v[80:81], v[6:7]
	v_pk_fma_f32 v[74:75], v[68:69], 0, v[68:69] op_sel:[0,0,1] op_sel_hi:[1,0,0] neg_lo:[0,0,1] neg_hi:[0,0,1]
	v_pk_fma_f32 v[68:69], v[68:69], 0, v[68:69] op_sel:[0,0,1] op_sel_hi:[1,0,0]
	v_pk_add_f32 v[80:81], v[94:95], v[16:17]
	v_mov_b32_e32 v75, v69
	v_pk_mul_f32 v[68:69], v[4:5], 0 op_sel_hi:[1,0]
	v_pk_add_f32 v[90:91], v[4:5], v[68:69] op_sel:[0,1] op_sel_hi:[1,0]
; DEV void fft_midx2(LAS cf* buf0, LAS cf* buf1, const unsigned* Kp, int blk) {
;     ...
;     dft_regs<16, true>(w); dft_regs<16, true>(x);
	v_pk_add_f32 v[4:5], v[4:5], v[68:69] op_sel:[0,1] op_sel_hi:[1,0] neg_lo:[0,1] neg_hi:[0,1]
	v_mov_b32_e32 v91, v5
	v_pk_add_f32 v[4:5], v[72:73], v[18:19] neg_lo:[0,1] neg_hi:[0,1]
	v_pk_fma_f32 v[72:73], v[4:5], 0, v[4:5] op_sel:[0,0,1] op_sel_hi:[1,0,0] neg_lo:[0,0,1] neg_hi:[0,0,1]
	v_pk_fma_f32 v[4:5], v[4:5], 0, v[4:5] op_sel:[0,0,1] op_sel_hi:[1,0,0]
	v_mov_b32_e32 v73, v5
	v_pk_add_f32 v[4:5], v[96:97], v[76:77] neg_lo:[0,1] neg_hi:[0,1]
	v_pk_add_f32 v[126:127], v[90:91], v[72:73]
	v_pk_mul_f32 v[18:19], v[4:5], 0 op_sel_hi:[1,0]
	v_pk_add_f32 v[72:73], v[90:91], v[72:73] neg_lo:[0,1] neg_hi:[0,1]
	v_pk_add_f32 v[96:97], v[4:5], v[18:19] op_sel:[0,1] op_sel_hi:[1,0]
	v_pk_add_f32 v[4:5], v[4:5], v[18:19] op_sel:[0,1] op_sel_hi:[1,0] neg_lo:[0,1] neg_hi:[0,1]
	v_pk_add_f32 v[90:91], v[120:121], v[122:123]
	v_mov_b32_e32 v97, v5
	v_pk_mul_f32 v[4:5], v[2:3], 0 op_sel_hi:[1,0]
	v_pk_add_f32 v[164:165], v[96:97], v[78:79]
	v_pk_add_f32 v[18:19], v[2:3], v[4:5] op_sel:[0,1] op_sel_hi:[1,0]
	v_pk_add_f32 v[68:69], v[2:3], v[4:5] op_sel:[0,1] op_sel_hi:[1,0] neg_lo:[0,1] neg_hi:[0,1]
	v_pk_add_f32 v[4:5], v[94:95], v[16:17] neg_lo:[0,1] neg_hi:[0,1]
	v_pk_add_f32 v[94:95], v[0:1], v[92:93]
	v_pk_mul_f32 v[6:7], v[4:5], 0 op_sel_hi:[1,0]
	v_pk_add_f32 v[0:1], v[0:1], v[92:93] neg_lo:[0,1] neg_hi:[0,1]
	v_pk_add_f32 v[2:3], v[4:5], v[6:7] op_sel:[0,1] op_sel_hi:[1,0]
	v_pk_add_f32 v[4:5], v[4:5], v[6:7] op_sel:[0,1] op_sel_hi:[1,0] neg_lo:[0,1] neg_hi:[0,1]
	v_pk_mul_f32 v[6:7], v[0:1], 0 op_sel_hi:[1,0]
	v_pk_add_f32 v[92:93], v[114:115], v[74:75]
	v_pk_add_f32 v[16:17], v[0:1], v[6:7] op_sel:[0,1] op_sel_hi:[1,0]
	v_pk_add_f32 v[70:71], v[0:1], v[6:7] op_sel:[0,1] op_sel_hi:[1,0] neg_lo:[0,1] neg_hi:[0,1]
	v_pk_add_f32 v[6:7], v[114:115], v[74:75] neg_lo:[0,1] neg_hi:[0,1]
	v_pk_add_f32 v[114:115], v[116:117], v[118:119]
	v_pk_mul_f32 v[74:75], v[6:7], 0 op_sel_hi:[1,0]
	v_pk_add_f32 v[78:79], v[96:97], v[78:79] neg_lo:[0,1] neg_hi:[0,1]
	v_pk_add_f32 v[0:1], v[6:7], v[74:75] op_sel:[0,1] op_sel_hi:[1,0]
	v_pk_add_f32 v[6:7], v[6:7], v[74:75] op_sel:[0,1] op_sel_hi:[1,0] neg_lo:[0,1] neg_hi:[0,1]
	v_pk_add_f32 v[74:75], v[116:117], v[118:119] neg_lo:[0,1] neg_hi:[0,1]
	v_pk_mul_f32 v[96:97], v[78:79], 0 op_sel_hi:[1,0]
	v_pk_mul_f32 v[76:77], v[74:75], 0 op_sel_hi:[1,0]
	v_mov_b32_e32 v1, v7
	v_pk_add_f32 v[116:117], v[74:75], v[76:77] op_sel:[0,1] op_sel_hi:[1,0]
	v_pk_add_f32 v[118:119], v[74:75], v[76:77] op_sel:[0,1] op_sel_hi:[1,0] neg_lo:[0,1] neg_hi:[0,1]
	v_pk_mul_f32 v[76:77], v[72:73], 0 op_sel_hi:[1,0]
	v_mov_b32_e32 v19, v69
	v_pk_add_f32 v[74:75], v[72:73], v[76:77] op_sel:[0,1] op_sel_hi:[1,0]
	v_pk_add_f32 v[76:77], v[72:73], v[76:77] op_sel:[0,1] op_sel_hi:[1,0] neg_lo:[0,1] neg_hi:[0,1]
	v_pk_add_f32 v[72:73], v[120:121], v[122:123] neg_lo:[0,1] neg_hi:[0,1]
	v_mov_b32_e32 v117, v119
	v_pk_mul_f32 v[120:121], v[72:73], 0 op_sel_hi:[1,0]
	v_mov_b32_e32 v17, v71
	v_pk_add_f32 v[122:123], v[72:73], v[120:121] op_sel:[0,1] op_sel_hi:[1,0]
	v_pk_add_f32 v[120:121], v[72:73], v[120:121] op_sel:[0,1] op_sel_hi:[1,0] neg_lo:[0,1] neg_hi:[0,1]
	v_pk_add_f32 v[72:73], v[78:79], v[96:97] op_sel:[0,1] op_sel_hi:[1,0]
	v_pk_add_f32 v[78:79], v[78:79], v[96:97] op_sel:[0,1] op_sel_hi:[1,0] neg_lo:[0,1] neg_hi:[0,1]
	v_pk_add_f32 v[96:97], v[86:87], v[98:99]
	v_pk_add_f32 v[86:87], v[86:87], v[98:99] neg_lo:[0,1] neg_hi:[0,1]
	v_mov_b32_e32 v73, v79
	v_pk_mul_f32 v[98:99], v[86:87], 0 op_sel_hi:[1,0]
	v_mov_b32_e32 v123, v121
	v_pk_add_f32 v[166:167], v[86:87], v[98:99] op_sel:[0,1] op_sel_hi:[1,0]
	v_pk_add_f32 v[86:87], v[86:87], v[98:99] op_sel:[0,1] op_sel_hi:[1,0] neg_lo:[0,1] neg_hi:[0,1]
	v_mov_b32_e32 v3, v5
	v_mov_b32_e32 v167, v87
	v_pk_add_f32 v[86:87], v[12:13], v[106:107]
	v_pk_add_f32 v[12:13], v[12:13], v[106:107] neg_lo:[0,1] neg_hi:[0,1]
	v_mov_b32_e32 v75, v77
	v_pk_mul_f32 v[98:99], v[12:13], s[84:85] op_sel_hi:[1,0]
	v_pk_fma_f32 v[106:107], v[12:13], s[16:17], v[98:99] op_sel:[0,0,1] op_sel_hi:[1,0,0] neg_lo:[0,0,1] neg_hi:[0,0,1]
	v_pk_fma_f32 v[12:13], v[12:13], s[16:17], v[98:99] op_sel:[0,0,1] op_sel_hi:[1,0,0]
	v_mov_b32_e32 v107, v13
	v_pk_add_f32 v[12:13], v[88:89], v[104:105]
	v_pk_add_f32 v[88:89], v[88:89], v[104:105] neg_lo:[0,1] neg_hi:[0,1]
	v_pk_mul_f32 v[98:99], v[88:89], s[18:19] op_sel_hi:[1,0]
	v_pk_fma_f32 v[104:105], v[88:89], s[18:19], v[98:99] op_sel:[0,0,1] op_sel_hi:[1,0,0] neg_lo:[0,0,1] neg_hi:[0,0,1]
	v_pk_fma_f32 v[88:89], v[88:89], s[18:19], v[98:99] op_sel_hi:[1,0,0]
	v_mov_b32_e32 v105, v89
	v_pk_add_f32 v[88:89], v[14:15], v[108:109]
	v_pk_add_f32 v[14:15], v[14:15], v[108:109] neg_lo:[0,1] neg_hi:[0,1]
	v_pk_mul_f32 v[98:99], v[14:15], s[16:17] op_sel_hi:[1,0]
	v_pk_fma_f32 v[108:109], v[14:15], s[84:85], v[98:99] op_sel:[0,0,1] op_sel_hi:[1,0,0] neg_lo:[0,0,1] neg_hi:[0,0,1]
	v_pk_fma_f32 v[14:15], v[14:15], s[84:85], v[98:99] op_sel:[0,0,1] op_sel_hi:[1,0,0]
	v_mov_b32_e32 v109, v15
	v_pk_add_f32 v[14:15], v[82:83], v[110:111]
	v_pk_add_f32 v[82:83], v[82:83], v[110:111] neg_lo:[0,1] neg_hi:[0,1]
	v_pk_add_f32 v[110:111], v[10:11], v[100:101]
	v_pk_add_f32 v[10:11], v[10:11], v[100:101] neg_lo:[0,1] neg_hi:[0,1]
	v_pk_fma_f32 v[98:99], v[82:83], 0, v[82:83] op_sel:[0,0,1] op_sel_hi:[1,0,0] neg_lo:[0,0,1] neg_hi:[0,0,1]
	v_pk_fma_f32 v[82:83], v[82:83], 0, v[82:83] op_sel:[0,0,1] op_sel_hi:[1,0,0]
	v_pk_mul_f32 v[100:101], v[10:11], s[84:85] op_sel:[1,0]
	v_mov_b32_e32 v99, v83
	v_pk_add_f32 v[82:83], v[8:9], v[102:103]
	v_pk_add_f32 v[8:9], v[8:9], v[102:103] neg_lo:[0,1] neg_hi:[0,1]
	v_pk_fma_f32 v[10:11], v[10:11], s[88:89], v[100:101] op_sel_hi:[0,1,1] neg_lo:[0,0,1] neg_hi:[0,0,1]
; DEV void fft_midx2(LAS cf* buf0, LAS cf* buf1, const unsigned* Kp, int blk) {
;     ...
;     dft_regs<16, true>(w); dft_regs<16, true>(x);
	v_pk_add_f32 v[100:101], v[96:97], v[14:15]
	v_pk_add_f32 v[14:15], v[96:97], v[14:15] neg_lo:[0,1] neg_hi:[0,1]
	v_pk_mul_f32 v[102:103], v[8:9], s[24:25] op_sel:[1,0]
	v_pk_mul_f32 v[96:97], v[14:15], 0 op_sel_hi:[1,0]
	v_pk_fma_f32 v[8:9], v[8:9], s[0:1], v[102:103] op_sel_hi:[0,1,1] neg_lo:[0,0,1] neg_hi:[0,0,1]
	v_pk_add_f32 v[102:103], v[84:85], v[112:113]
	v_pk_add_f32 v[84:85], v[84:85], v[112:113] neg_lo:[0,1] neg_hi:[0,1]
	v_pk_add_f32 v[112:113], v[14:15], v[96:97] op_sel:[0,1] op_sel_hi:[1,0]
	v_pk_add_f32 v[14:15], v[14:15], v[96:97] op_sel:[0,1] op_sel_hi:[1,0] neg_lo:[0,1] neg_hi:[0,1]
	v_mul_f32_e32 v4, 0x3f3504f3, v85
	v_mov_b32_e32 v113, v15
	v_pk_add_f32 v[14:15], v[86:87], v[82:83]
	v_pk_add_f32 v[82:83], v[86:87], v[82:83] neg_lo:[0,1] neg_hi:[0,1]
	v_pk_fma_f32 v[84:85], v[84:85], s[96:97], v[4:5] op_sel_hi:[0,1,0] neg_lo:[0,0,1] neg_hi:[0,0,1]
	v_pk_mul_f32 v[86:87], v[82:83], s[18:19] op_sel_hi:[1,0]
	v_pk_fma_f32 v[96:97], v[82:83], s[18:19], v[86:87] op_sel:[0,0,1] op_sel_hi:[1,0,0] neg_lo:[0,0,1] neg_hi:[0,0,1]
	v_pk_fma_f32 v[82:83], v[82:83], s[18:19], v[86:87] op_sel_hi:[1,0,0]
	v_mov_b32_e32 v97, v83
	v_pk_add_f32 v[82:83], v[12:13], v[102:103]
	v_pk_add_f32 v[12:13], v[12:13], v[102:103] neg_lo:[0,1] neg_hi:[0,1]
	v_pk_add_f32 v[102:103], v[166:167], v[98:99]
	v_pk_fma_f32 v[86:87], v[12:13], 0, v[12:13] op_sel:[0,0,1] op_sel_hi:[1,0,0] neg_lo:[0,0,1] neg_hi:[0,0,1]
	v_pk_fma_f32 v[12:13], v[12:13], 0, v[12:13] op_sel:[0,0,1] op_sel_hi:[1,0,0]
	v_pk_add_f32 v[98:99], v[166:167], v[98:99] neg_lo:[0,1] neg_hi:[0,1]
	v_mov_b32_e32 v87, v13
	v_pk_add_f32 v[12:13], v[88:89], v[110:111]
	v_pk_add_f32 v[88:89], v[88:89], v[110:111] neg_lo:[0,1] neg_hi:[0,1]
	v_pk_mul_f32 v[110:111], v[98:99], 0 op_sel_hi:[1,0]
	v_mul_f32_e32 v4, 0x3f3504f3, v89
	v_pk_add_f32 v[166:167], v[98:99], v[110:111] op_sel:[0,1] op_sel_hi:[1,0]
	v_pk_add_f32 v[98:99], v[98:99], v[110:111] op_sel:[0,1] op_sel_hi:[1,0] neg_lo:[0,1] neg_hi:[0,1]
	v_pk_fma_f32 v[88:89], v[88:89], s[96:97], v[4:5] op_sel_hi:[0,1,0] neg_lo:[0,0,1] neg_hi:[0,0,1]
	v_mov_b32_e32 v167, v99
	v_pk_add_f32 v[98:99], v[106:107], v[8:9]
	v_pk_add_f32 v[8:9], v[106:107], v[8:9] neg_lo:[0,1] neg_hi:[0,1]
	v_pk_mul_f32 v[106:107], v[8:9], s[18:19] op_sel_hi:[1,0]
	v_pk_fma_f32 v[110:111], v[8:9], s[18:19], v[106:107] op_sel:[0,0,1] op_sel_hi:[1,0,0] neg_lo:[0,0,1] neg_hi:[0,0,1]
	v_pk_fma_f32 v[8:9], v[8:9], s[18:19], v[106:107] op_sel_hi:[1,0,0]
	v_pk_add_f32 v[106:107], v[100:101], v[82:83]
	v_mov_b32_e32 v111, v9
	v_pk_add_f32 v[8:9], v[104:105], v[84:85]
	v_pk_add_f32 v[84:85], v[104:105], v[84:85] neg_lo:[0,1] neg_hi:[0,1]
	v_pk_add_f32 v[82:83], v[100:101], v[82:83] neg_lo:[0,1] neg_hi:[0,1]
	v_pk_fma_f32 v[104:105], v[84:85], 0, v[84:85] op_sel:[0,0,1] op_sel_hi:[1,0,0] neg_lo:[0,0,1] neg_hi:[0,0,1]
	v_pk_fma_f32 v[84:85], v[84:85], 0, v[84:85] op_sel:[0,0,1] op_sel_hi:[1,0,0]
	v_pk_mul_f32 v[100:101], v[82:83], 0 op_sel_hi:[1,0]
	v_mov_b32_e32 v105, v85
	v_pk_add_f32 v[84:85], v[108:109], v[10:11]
	v_pk_add_f32 v[10:11], v[108:109], v[10:11] neg_lo:[0,1] neg_hi:[0,1]
	v_pk_add_f32 v[108:109], v[82:83], v[100:101] op_sel:[0,1] op_sel_hi:[1,0]
	v_pk_add_f32 v[82:83], v[82:83], v[100:101] op_sel:[0,1] op_sel_hi:[1,0] neg_lo:[0,1] neg_hi:[0,1]
	v_mul_f32_e32 v4, 0x3f3504f3, v11
	v_mov_b32_e32 v109, v83
	v_pk_add_f32 v[82:83], v[14:15], v[12:13]
	v_pk_add_f32 v[12:13], v[14:15], v[12:13] neg_lo:[0,1] neg_hi:[0,1]
	v_pk_fma_f32 v[10:11], v[10:11], s[96:97], v[4:5] op_sel_hi:[0,1,0] neg_lo:[0,0,1] neg_hi:[0,0,1]
	v_pk_fma_f32 v[14:15], v[12:13], 0, v[12:13] op_sel:[0,0,1] op_sel_hi:[1,0,0] neg_lo:[0,0,1] neg_hi:[0,0,1]
	v_pk_fma_f32 v[12:13], v[12:13], 0, v[12:13] op_sel:[0,0,1] op_sel_hi:[1,0,0]
	v_mov_b32_e32 v15, v13
	v_pk_add_f32 v[12:13], v[112:113], v[86:87]
	v_pk_add_f32 v[86:87], v[112:113], v[86:87] neg_lo:[0,1] neg_hi:[0,1]
	v_pk_mul_f32 v[100:101], v[86:87], 0 op_sel_hi:[1,0]
	v_pk_add_f32 v[112:113], v[86:87], v[100:101] op_sel:[0,1] op_sel_hi:[1,0]
	v_pk_add_f32 v[86:87], v[86:87], v[100:101] op_sel:[0,1] op_sel_hi:[1,0] neg_lo:[0,1] neg_hi:[0,1]
	v_mov_b32_e32 v113, v87
	v_pk_add_f32 v[86:87], v[96:97], v[88:89]
	v_pk_add_f32 v[88:89], v[96:97], v[88:89] neg_lo:[0,1] neg_hi:[0,1]
	v_pk_fma_f32 v[96:97], v[88:89], 0, v[88:89] op_sel:[0,0,1] op_sel_hi:[1,0,0] neg_lo:[0,0,1] neg_hi:[0,0,1]
	v_pk_fma_f32 v[88:89], v[88:89], 0, v[88:89] op_sel:[0,0,1] op_sel_hi:[1,0,0]
	v_mov_b32_e32 v97, v89
	v_pk_add_f32 v[88:89], v[102:103], v[8:9]
	v_pk_add_f32 v[8:9], v[102:103], v[8:9] neg_lo:[0,1] neg_hi:[0,1]
	v_pk_mul_f32 v[100:101], v[8:9], 0 op_sel_hi:[1,0]
	v_pk_add_f32 v[102:103], v[8:9], v[100:101] op_sel:[0,1] op_sel_hi:[1,0]
	v_pk_add_f32 v[8:9], v[8:9], v[100:101] op_sel:[0,1] op_sel_hi:[1,0] neg_lo:[0,1] neg_hi:[0,1]
	v_pk_add_f32 v[100:101], v[166:167], v[104:105] neg_lo:[0,1] neg_hi:[0,1]
	v_mov_b32_e32 v103, v9
	v_pk_add_f32 v[8:9], v[98:99], v[84:85]
	v_pk_add_f32 v[84:85], v[98:99], v[84:85] neg_lo:[0,1] neg_hi:[0,1]
	v_pk_fma_f32 v[98:99], v[84:85], 0, v[84:85] op_sel:[0,0,1] op_sel_hi:[1,0,0] neg_lo:[0,0,1] neg_hi:[0,0,1]
	v_pk_fma_f32 v[84:85], v[84:85], 0, v[84:85] op_sel:[0,0,1] op_sel_hi:[1,0,0]
	v_mov_b32_e32 v99, v85
	v_pk_add_f32 v[84:85], v[166:167], v[104:105]
	v_pk_mul_f32 v[104:105], v[100:101], 0 op_sel_hi:[1,0]
	v_pk_add_f32 v[166:167], v[100:101], v[104:105] op_sel:[0,1] op_sel_hi:[1,0]
	v_pk_add_f32 v[100:101], v[100:101], v[104:105] op_sel:[0,1] op_sel_hi:[1,0] neg_lo:[0,1] neg_hi:[0,1]
	v_mov_b32_e32 v167, v101
	v_pk_add_f32 v[100:101], v[110:111], v[10:11]
	v_pk_add_f32 v[10:11], v[110:111], v[10:11] neg_lo:[0,1] neg_hi:[0,1]
; #define LAS __attribute__((address_space(3)))
; #define SINCOSPI(x, s, c) do { const float hx_ = 0.5f * (x); *(s) = __builtin_amdgcn_sinf(hx_); *(c) = __builtin_amdgcn_cosf(hx_); } while (0)
; #define OPAQUE_I(x) asm volatile("" : "+v"(x))
; DEV void fft_midx2(LAS cf* buf0, LAS cf* buf1, const unsigned* Kp, int blk) {
;     ...
;     dft_regs<16, true>(w); dft_regs<16, true>(x);
; #pragma unroll
;     for (int q = 0; q < 16; ++q) { p0[q] = w[BR16[q]]; p1[q] = x[BR16[q]]; }
; }
; DEV void fft_i2(LAS cf* buf, int t8) {
;     OPAQUE_I(t8);
;     LAS cf* pb = buf + (t8 >> 4) * 544 + (t8 & 15);
;     float sn, cs; SINCOSPI(-(float)(t8 & 15) * (2.0f / 512.0f), &sn, &cs);
;     const cf w = cf{cs, sn}; cf wp = cf{1.f, 0.f};
;     cf v[32];
; #pragma unroll
;     for (int p = 0; p < 32; ++p) { v[p] = cmulc(pb[17 * p], wp); wp = cmul(wp, w); }
; DEV void hyena_issue_rows(const bf16_t* UT, int s, int c, u32x4 (&r)[4], int tid) {
; #pragma unroll
;     for (int b = 0; b < 4; ++b) r[b] = *(const u32x4*)(UT + ((size_t)(b * 3072 + s * 1024 + c)) * 4096 + tid * 8);
; }
	v_pk_fma_f32 v[104:105], v[10:11], 0, v[10:11] op_sel:[0,0,1] op_sel_hi:[1,0,0] neg_lo:[0,0,1] neg_hi:[0,0,1]
	v_pk_fma_f32 v[10:11], v[10:11], 0, v[10:11] op_sel:[0,0,1] op_sel_hi:[1,0,0]
	v_mov_b32_e32 v105, v11
	v_pk_add_f32 v[10:11], v[106:107], v[82:83]
	v_pk_add_f32 v[82:83], v[106:107], v[82:83] neg_lo:[0,1] neg_hi:[0,1]
	v_pk_mul_f32 v[106:107], v[82:83], 0 op_sel_hi:[1,0]
	v_pk_add_f32 v[110:111], v[82:83], v[106:107] op_sel:[0,1] op_sel_hi:[1,0]
	v_pk_add_f32 v[82:83], v[82:83], v[106:107] op_sel:[0,1] op_sel_hi:[1,0] neg_lo:[0,1] neg_hi:[0,1]
	v_pk_add_f32 v[106:107], v[108:109], v[14:15]
	v_pk_add_f32 v[14:15], v[108:109], v[14:15] neg_lo:[0,1] neg_hi:[0,1]
	v_mov_b32_e32 v111, v83
	v_pk_mul_f32 v[108:109], v[14:15], 0 op_sel_hi:[1,0]
	v_pk_add_f32 v[168:169], v[14:15], v[108:109] op_sel:[0,1] op_sel_hi:[1,0]
	v_pk_add_f32 v[14:15], v[14:15], v[108:109] op_sel:[0,1] op_sel_hi:[1,0] neg_lo:[0,1] neg_hi:[0,1]
	v_pk_add_f32 v[108:109], v[12:13], v[86:87]
	v_pk_add_f32 v[12:13], v[12:13], v[86:87] neg_lo:[0,1] neg_hi:[0,1]
	v_mov_b32_e32 v169, v15
	v_pk_mul_f32 v[86:87], v[12:13], 0 op_sel_hi:[1,0]
	v_pk_add_f32 v[170:171], v[12:13], v[86:87] op_sel:[0,1] op_sel_hi:[1,0]
	v_pk_add_f32 v[12:13], v[12:13], v[86:87] op_sel:[0,1] op_sel_hi:[1,0] neg_lo:[0,1] neg_hi:[0,1]
	v_pk_add_f32 v[86:87], v[112:113], v[96:97]
	v_pk_add_f32 v[96:97], v[112:113], v[96:97] neg_lo:[0,1] neg_hi:[0,1]
	v_mov_b32_e32 v171, v13
	v_pk_mul_f32 v[112:113], v[96:97], 0 op_sel_hi:[1,0]
	v_pk_add_f32 v[172:173], v[96:97], v[112:113] op_sel:[0,1] op_sel_hi:[1,0]
	v_pk_add_f32 v[96:97], v[96:97], v[112:113] op_sel:[0,1] op_sel_hi:[1,0] neg_lo:[0,1] neg_hi:[0,1]
	v_pk_add_f32 v[112:113], v[88:89], v[8:9]
	v_pk_add_f32 v[8:9], v[88:89], v[8:9] neg_lo:[0,1] neg_hi:[0,1]
	v_mov_b32_e32 v173, v97
	v_pk_mul_f32 v[88:89], v[8:9], 0 op_sel_hi:[1,0]
	v_pk_add_f32 v[174:175], v[8:9], v[88:89] op_sel:[0,1] op_sel_hi:[1,0]
	v_pk_add_f32 v[8:9], v[8:9], v[88:89] op_sel:[0,1] op_sel_hi:[1,0] neg_lo:[0,1] neg_hi:[0,1]
	v_pk_add_f32 v[88:89], v[102:103], v[98:99]
	v_pk_add_f32 v[98:99], v[102:103], v[98:99] neg_lo:[0,1] neg_hi:[0,1]
	v_mov_b32_e32 v175, v9
	v_pk_mul_f32 v[102:103], v[98:99], 0 op_sel_hi:[1,0]
	v_pk_add_f32 v[176:177], v[98:99], v[102:103] op_sel:[0,1] op_sel_hi:[1,0]
	v_pk_add_f32 v[98:99], v[98:99], v[102:103] op_sel:[0,1] op_sel_hi:[1,0] neg_lo:[0,1] neg_hi:[0,1]
	v_pk_add_f32 v[102:103], v[84:85], v[100:101]
	v_pk_add_f32 v[84:85], v[84:85], v[100:101] neg_lo:[0,1] neg_hi:[0,1]
	v_mov_b32_e32 v177, v99
	v_pk_mul_f32 v[100:101], v[84:85], 0 op_sel_hi:[1,0]
	v_pk_add_f32 v[178:179], v[84:85], v[100:101] op_sel:[0,1] op_sel_hi:[1,0]
	v_pk_add_f32 v[84:85], v[84:85], v[100:101] op_sel:[0,1] op_sel_hi:[1,0] neg_lo:[0,1] neg_hi:[0,1]
	v_pk_add_f32 v[100:101], v[166:167], v[104:105]
	v_pk_add_f32 v[104:105], v[166:167], v[104:105] neg_lo:[0,1] neg_hi:[0,1]
	ds_write2_b64 v161, v[124:125], v[114:115] offset1:1
	ds_write2_b64 v162, v[10:11], v[112:113] offset1:1
	ds_write2_b64 v161, v[94:95], v[90:91] offset0:2 offset1:3
	ds_write2_b64 v162, v[108:109], v[102:103] offset0:2 offset1:3
	ds_write2_b64 v161, v[80:81], v[126:127] offset0:4 offset1:5
	ds_write2_b64 v162, v[106:107], v[88:89] offset0:4 offset1:5
	ds_write2_b64 v161, v[92:93], v[164:165] offset0:6 offset1:7
	ds_write2_b64 v162, v[86:87], v[100:101] offset0:6 offset1:7
	v_pk_mul_f32 v[166:167], v[104:105], 0 op_sel_hi:[1,0]
	v_mov_b32_e32 v179, v85
	v_pk_add_f32 v[180:181], v[104:105], v[166:167] op_sel:[0,1] op_sel_hi:[1,0]
	v_pk_add_f32 v[104:105], v[104:105], v[166:167] op_sel:[0,1] op_sel_hi:[1,0] neg_lo:[0,1] neg_hi:[0,1]
	ds_write2_b64 v161, v[0:1], v[72:73] offset0:14 offset1:15
	v_mov_b32_e32 v181, v105
	v_mov_b32_e32 v0, v160
	ds_write2_b64 v161, v[18:19], v[116:117] offset0:8 offset1:9
	ds_write2_b64 v162, v[110:111], v[174:175] offset0:8 offset1:9
	ds_write2_b64 v161, v[16:17], v[122:123] offset0:10 offset1:11
	ds_write2_b64 v162, v[170:171], v[178:179] offset0:10 offset1:11
	ds_write2_b64 v161, v[2:3], v[74:75] offset0:12 offset1:13
	ds_write2_b64 v162, v[168:169], v[176:177] offset0:12 offset1:13
	ds_write2_b64 v162, v[172:173], v[180:181] offset0:14 offset1:15
	s_waitcnt lgkmcnt(0)
	s_barrier
	s_lshl_b32 s100, s19, 10
	s_add_i32 s100, s79, s100
	s_ashr_i32 s101, s100, 31
	s_lshl_b64 s[100:101], s[100:101], 13
	v_lshl_add_u64 v[218:219], v[56:57], 0, s[100:101]
	global_load_dwordx4 v[222:225], v[218:219], off
	s_add_u32 s100, s100, 0x1800000
	s_addc_u32 s101, s101, 0
	v_lshl_add_u64 v[220:221], v[56:57], 0, s[100:101]
	global_load_dwordx4 v[226:229], v[220:221], off
	s_add_u32 s100, s100, 0x1800000
	s_addc_u32 s101, s101, 0
	v_lshl_add_u64 v[218:219], v[56:57], 0, s[100:101]
	global_load_dwordx4 v[236:239], v[218:219], off
	s_add_u32 s100, s100, 0x1800000
	s_addc_u32 s101, s101, 0
	v_lshl_add_u64 v[220:221], v[56:57], 0, s[100:101]
	global_load_dwordx4 v[240:243], v[220:221], off
	s_nop 0
	v_lshrrev_b32_e32 v1, 4, v0
	v_and_b32_e32 v0, 15, v0
	v_mul_lo_u32 v1, v1, s15
	v_lshlrev_b32_e32 v2, 3, v0
	v_cvt_f32_ubyte0_e32 v0, v0
	v_add3_u32 v86, v159, v1, v2
	v_mul_f32_e32 v0, 0xbb800000, v0
	v_mul_f32_e32 v0, 0.5, v0
	v_add_u32_e32 v232, 0x800, v86
	v_add_u32_e32 v233, 0xc00, v86
	ds_read2_b64 v[166:169], v86 offset1:17
	ds_read2_b64 v[170:173], v86 offset0:34 offset1:51
	ds_read2_b64 v[174:177], v86 offset0:68 offset1:85
	ds_read2_b64 v[178:181], v86 offset0:102 offset1:119
	ds_read2_b64 v[182:185], v86 offset0:136 offset1:153
	ds_read2_b64 v[186:189], v86 offset0:170 offset1:187
	ds_read2_b64 v[190:193], v86 offset0:204 offset1:221
	ds_read2_b64 v[194:197], v86 offset0:238 offset1:255
	ds_read2_b64 v[198:201], v232 offset0:16 offset1:33
	ds_read2_b64 v[202:205], v232 offset0:50 offset1:67
	ds_read2_b64 v[208:211], v232 offset0:84 offset1:101
	ds_read2_b64 v[214:217], v232 offset0:118 offset1:135
	ds_read2_b64 v[218:221], v232 offset0:152 offset1:169
	v_sin_f32_e32 v1, v0
	v_cos_f32_e32 v0, v0
	s_waitcnt lgkmcnt(12)
; #define LAS __attribute__((address_space(3)))
; #define SINCOSPI(x, s, c) do { const float hx_ = 0.5f * (x); *(s) = __builtin_amdgcn_sinf(hx_); *(c) = __builtin_amdgcn_cosf(hx_); } while (0)
; #define OPAQUE_I(x) asm volatile("" : "+v"(x))
; DEV void fft_i2(LAS cf* buf, int t8) {
;     OPAQUE_I(t8);
;     LAS cf* pb = buf + (t8 >> 4) * 544 + (t8 & 15);
;     float sn, cs; SINCOSPI(-(float)(t8 & 15) * (2.0f / 512.0f), &sn, &cs);
;     const cf w = cf{cs, sn}; cf wp = cf{1.f, 0.f};
;     cf v[32];
; #pragma unroll
;     for (int p = 0; p < 32; ++p) { v[p] = cmulc(pb[17 * p], wp); wp = cmul(wp, w); }
	v_pk_mul_f32 v[2:3], v[166:167], v[66:67] op_sel:[1,1] op_sel_hi:[1,0]
	v_pk_fma_f32 v[4:5], v[166:167], v[66:67], v[2:3] op_sel_hi:[0,1,1] neg_hi:[1,0,0]
	v_add_u32_e32 v87, 0x800, v86
	v_pk_mul_f32 v[2:3], v[66:67], v[0:1] op_sel:[1,1] op_sel_hi:[1,0] neg_lo:[1,0]
	v_pk_fma_f32 v[8:9], v[66:67], v[0:1], v[2:3] op_sel_hi:[0,1,1]
	v_pk_mul_f32 v[10:11], v[168:169], v[8:9] op_sel:[1,1] op_sel_hi:[1,0]
	v_pk_fma_f32 v[2:3], v[168:169], v[8:9], v[10:11] op_sel_hi:[0,1,1] neg_hi:[1,0,0]
	v_pk_mul_f32 v[6:7], v[8:9], v[0:1] op_sel:[1,1] op_sel_hi:[1,0] neg_lo:[1,0]
	v_pk_fma_f32 v[12:13], v[8:9], v[0:1], v[6:7] op_sel_hi:[0,1,1]
	ds_read2_b64 v[166:169], v232 offset0:186 offset1:203
	s_waitcnt lgkmcnt(12)
	v_pk_mul_f32 v[14:15], v[170:171], v[12:13] op_sel:[1,1] op_sel_hi:[1,0]
	v_pk_fma_f32 v[10:11], v[170:171], v[12:13], v[14:15] op_sel_hi:[0,1,1] neg_hi:[1,0,0]
	v_pk_mul_f32 v[6:7], v[12:13], v[0:1] op_sel:[1,1] op_sel_hi:[1,0] neg_lo:[1,0]
	v_pk_fma_f32 v[12:13], v[12:13], v[0:1], v[6:7] op_sel_hi:[0,1,1]
	v_pk_mul_f32 v[14:15], v[172:173], v[12:13] op_sel:[1,1] op_sel_hi:[1,0]
	v_pk_fma_f32 v[6:7], v[172:173], v[12:13], v[14:15] op_sel_hi:[0,1,1] neg_hi:[1,0,0]
	v_pk_mul_f32 v[8:9], v[12:13], v[0:1] op_sel:[1,1] op_sel_hi:[1,0] neg_lo:[1,0]
	v_pk_fma_f32 v[16:17], v[12:13], v[0:1], v[8:9] op_sel_hi:[0,1,1]
	ds_read2_b64 v[170:173], v232 offset0:220 offset1:237
	s_waitcnt lgkmcnt(12)
	v_pk_mul_f32 v[8:9], v[174:175], v[16:17] op_sel:[1,1] op_sel_hi:[1,0]
	v_pk_fma_f32 v[12:13], v[174:175], v[16:17], v[8:9] op_sel_hi:[0,1,1] neg_hi:[1,0,0]
	s_nop 0
	v_pk_mul_f32 v[8:9], v[16:17], v[0:1] op_sel:[1,1] op_sel_hi:[1,0] neg_lo:[1,0]
	v_pk_fma_f32 v[16:17], v[16:17], v[0:1], v[8:9] op_sel_hi:[0,1,1]
	v_pk_mul_f32 v[18:19], v[176:177], v[16:17] op_sel:[1,1] op_sel_hi:[1,0]
	v_pk_fma_f32 v[8:9], v[176:177], v[16:17], v[18:19] op_sel_hi:[0,1,1] neg_hi:[1,0,0]
	v_pk_mul_f32 v[14:15], v[16:17], v[0:1] op_sel:[1,1] op_sel_hi:[1,0] neg_lo:[1,0]
	v_pk_fma_f32 v[68:69], v[16:17], v[0:1], v[14:15] op_sel_hi:[0,1,1]
	ds_read2_b64 v[174:177], v233 offset0:126 offset1:143
	s_waitcnt lgkmcnt(12)
	v_pk_mul_f32 v[14:15], v[178:179], v[68:69] op_sel:[1,1] op_sel_hi:[1,0]
	v_pk_fma_f32 v[16:17], v[178:179], v[68:69], v[14:15] op_sel_hi:[0,1,1] neg_hi:[1,0,0]
	s_nop 0
	v_pk_mul_f32 v[14:15], v[68:69], v[0:1] op_sel:[1,1] op_sel_hi:[1,0] neg_lo:[1,0]
	v_pk_fma_f32 v[68:69], v[68:69], v[0:1], v[14:15] op_sel_hi:[0,1,1]
	v_pk_mul_f32 v[70:71], v[180:181], v[68:69] op_sel:[1,1] op_sel_hi:[1,0]
	v_pk_fma_f32 v[14:15], v[180:181], v[68:69], v[70:71] op_sel_hi:[0,1,1] neg_hi:[1,0,0]
	v_pk_mul_f32 v[18:19], v[68:69], v[0:1] op_sel:[1,1] op_sel_hi:[1,0] neg_lo:[1,0]
	v_pk_fma_f32 v[72:73], v[68:69], v[0:1], v[18:19] op_sel_hi:[0,1,1]
	s_waitcnt lgkmcnt(11)
	v_pk_mul_f32 v[18:19], v[182:183], v[72:73] op_sel:[1,1] op_sel_hi:[1,0]
	v_pk_fma_f32 v[68:69], v[182:183], v[72:73], v[18:19] op_sel_hi:[0,1,1] neg_hi:[1,0,0]
	s_nop 0
	v_pk_mul_f32 v[18:19], v[72:73], v[0:1] op_sel:[1,1] op_sel_hi:[1,0] neg_lo:[1,0]
	v_pk_fma_f32 v[72:73], v[72:73], v[0:1], v[18:19] op_sel_hi:[0,1,1]
	v_pk_mul_f32 v[74:75], v[184:185], v[72:73] op_sel:[1,1] op_sel_hi:[1,0]
	v_pk_fma_f32 v[18:19], v[184:185], v[72:73], v[74:75] op_sel_hi:[0,1,1] neg_hi:[1,0,0]
	v_pk_mul_f32 v[70:71], v[72:73], v[0:1] op_sel:[1,1] op_sel_hi:[1,0] neg_lo:[1,0]
	v_pk_fma_f32 v[76:77], v[72:73], v[0:1], v[70:71] op_sel_hi:[0,1,1]
	s_waitcnt lgkmcnt(10)
	v_pk_mul_f32 v[70:71], v[186:187], v[76:77] op_sel:[1,1] op_sel_hi:[1,0]
	v_pk_fma_f32 v[72:73], v[186:187], v[76:77], v[70:71] op_sel_hi:[0,1,1] neg_hi:[1,0,0]
	s_nop 0
	v_pk_mul_f32 v[70:71], v[76:77], v[0:1] op_sel:[1,1] op_sel_hi:[1,0] neg_lo:[1,0]
	v_pk_fma_f32 v[76:77], v[76:77], v[0:1], v[70:71] op_sel_hi:[0,1,1]
	v_pk_mul_f32 v[78:79], v[188:189], v[76:77] op_sel:[1,1] op_sel_hi:[1,0]
	v_pk_fma_f32 v[70:71], v[188:189], v[76:77], v[78:79] op_sel_hi:[0,1,1] neg_hi:[1,0,0]
	v_pk_mul_f32 v[74:75], v[76:77], v[0:1] op_sel:[1,1] op_sel_hi:[1,0] neg_lo:[1,0]
	v_pk_fma_f32 v[80:81], v[76:77], v[0:1], v[74:75] op_sel_hi:[0,1,1]
	s_waitcnt lgkmcnt(9)
	v_pk_mul_f32 v[74:75], v[190:191], v[80:81] op_sel:[1,1] op_sel_hi:[1,0]
	v_pk_fma_f32 v[76:77], v[190:191], v[80:81], v[74:75] op_sel_hi:[0,1,1] neg_hi:[1,0,0]
	s_nop 0
	v_pk_mul_f32 v[74:75], v[80:81], v[0:1] op_sel:[1,1] op_sel_hi:[1,0] neg_lo:[1,0]
	v_pk_fma_f32 v[80:81], v[80:81], v[0:1], v[74:75] op_sel_hi:[0,1,1]
	v_pk_mul_f32 v[82:83], v[192:193], v[80:81] op_sel:[1,1] op_sel_hi:[1,0]
	v_pk_fma_f32 v[74:75], v[192:193], v[80:81], v[82:83] op_sel_hi:[0,1,1] neg_hi:[1,0,0]
	v_pk_mul_f32 v[78:79], v[80:81], v[0:1] op_sel:[1,1] op_sel_hi:[1,0] neg_lo:[1,0]
	v_pk_fma_f32 v[84:85], v[80:81], v[0:1], v[78:79] op_sel_hi:[0,1,1]
	s_waitcnt lgkmcnt(8)
	v_pk_mul_f32 v[78:79], v[194:195], v[84:85] op_sel:[1,1] op_sel_hi:[1,0]
	v_pk_fma_f32 v[80:81], v[194:195], v[84:85], v[78:79] op_sel_hi:[0,1,1] neg_hi:[1,0,0]
	s_nop 0
	v_pk_mul_f32 v[78:79], v[84:85], v[0:1] op_sel:[1,1] op_sel_hi:[1,0] neg_lo:[1,0]
	v_pk_fma_f32 v[84:85], v[84:85], v[0:1], v[78:79] op_sel_hi:[0,1,1]
	v_pk_mul_f32 v[88:89], v[196:197], v[84:85] op_sel:[1,1] op_sel_hi:[1,0]
	v_pk_fma_f32 v[78:79], v[196:197], v[84:85], v[88:89] op_sel_hi:[0,1,1] neg_hi:[1,0,0]
	v_pk_mul_f32 v[82:83], v[84:85], v[0:1] op_sel:[1,1] op_sel_hi:[1,0] neg_lo:[1,0]
	v_pk_fma_f32 v[92:93], v[84:85], v[0:1], v[82:83] op_sel_hi:[0,1,1]
	s_waitcnt lgkmcnt(7)
; #define SINCOSPI(x, s, c) do { const float hx_ = 0.5f * (x); *(s) = __builtin_amdgcn_sinf(hx_); *(c) = __builtin_amdgcn_cosf(hx_); } while (0)
; DEV void fft_i2(LAS cf* buf, int t8) {
;     ...
;     float sn, cs; SINCOSPI(-(float)(t8 & 15) * (2.0f / 512.0f), &sn, &cs);
;     const cf w = cf{cs, sn}; cf wp = cf{1.f, 0.f};
;     cf v[32];
; #pragma unroll
;     for (int p = 0; p < 32; ++p) { v[p] = cmulc(pb[17 * p], wp); wp = cmul(wp, w); }
	v_pk_mul_f32 v[82:83], v[198:199], v[92:93] op_sel:[1,1] op_sel_hi:[1,0]
	v_pk_fma_f32 v[84:85], v[198:199], v[92:93], v[82:83] op_sel_hi:[0,1,1] neg_hi:[1,0,0]
	s_nop 0
	v_pk_mul_f32 v[82:83], v[92:93], v[0:1] op_sel:[1,1] op_sel_hi:[1,0] neg_lo:[1,0]
	v_pk_fma_f32 v[88:89], v[92:93], v[0:1], v[82:83] op_sel_hi:[0,1,1]
	v_pk_mul_f32 v[92:93], v[200:201], v[88:89] op_sel:[1,1] op_sel_hi:[1,0]
	v_pk_fma_f32 v[82:83], v[200:201], v[88:89], v[92:93] op_sel_hi:[0,1,1] neg_hi:[1,0,0]
	s_nop 0
	v_pk_mul_f32 v[90:91], v[88:89], v[0:1] op_sel:[1,1] op_sel_hi:[1,0] neg_lo:[1,0]
	v_pk_fma_f32 v[92:93], v[88:89], v[0:1], v[90:91] op_sel_hi:[0,1,1]
	s_waitcnt lgkmcnt(6)
	v_pk_mul_f32 v[96:97], v[202:203], v[92:93] op_sel:[1,1] op_sel_hi:[1,0]
	v_pk_fma_f32 v[94:95], v[202:203], v[92:93], v[96:97] op_sel_hi:[0,1,1] neg_hi:[1,0,0]
	v_pk_mul_f32 v[88:89], v[92:93], v[0:1] op_sel:[1,1] op_sel_hi:[1,0] neg_lo:[1,0]
	v_pk_fma_f32 v[92:93], v[92:93], v[0:1], v[88:89] op_sel_hi:[0,1,1]
	v_pk_mul_f32 v[88:89], v[204:205], v[92:93] op_sel:[1,1] op_sel_hi:[1,0]
	v_pk_fma_f32 v[96:97], v[204:205], v[92:93], v[88:89] op_sel_hi:[0,1,1] neg_hi:[1,0,0]
	s_nop 0
	v_pk_mul_f32 v[88:89], v[92:93], v[0:1] op_sel:[1,1] op_sel_hi:[1,0] neg_lo:[1,0]
	v_pk_fma_f32 v[92:93], v[92:93], v[0:1], v[88:89] op_sel_hi:[0,1,1]
	s_waitcnt lgkmcnt(5)
	v_pk_mul_f32 v[100:101], v[208:209], v[92:93] op_sel:[1,1] op_sel_hi:[1,0]
	v_pk_fma_f32 v[98:99], v[208:209], v[92:93], v[100:101] op_sel_hi:[0,1,1] neg_hi:[1,0,0]
	v_pk_mul_f32 v[88:89], v[92:93], v[0:1] op_sel:[1,1] op_sel_hi:[1,0] neg_lo:[1,0]
	v_pk_fma_f32 v[92:93], v[92:93], v[0:1], v[88:89] op_sel_hi:[0,1,1]
	v_pk_mul_f32 v[88:89], v[210:211], v[92:93] op_sel:[1,1] op_sel_hi:[1,0]
	v_pk_fma_f32 v[100:101], v[210:211], v[92:93], v[88:89] op_sel_hi:[0,1,1] neg_hi:[1,0,0]
	s_nop 0
	v_pk_mul_f32 v[88:89], v[92:93], v[0:1] op_sel:[1,1] op_sel_hi:[1,0] neg_lo:[1,0]
	v_pk_fma_f32 v[92:93], v[92:93], v[0:1], v[88:89] op_sel_hi:[0,1,1]
	s_waitcnt lgkmcnt(4)
	v_pk_mul_f32 v[104:105], v[214:215], v[92:93] op_sel:[1,1] op_sel_hi:[1,0]
	v_pk_fma_f32 v[102:103], v[214:215], v[92:93], v[104:105] op_sel_hi:[0,1,1] neg_hi:[1,0,0]
	v_pk_mul_f32 v[88:89], v[92:93], v[0:1] op_sel:[1,1] op_sel_hi:[1,0] neg_lo:[1,0]
	v_pk_fma_f32 v[92:93], v[92:93], v[0:1], v[88:89] op_sel_hi:[0,1,1]
	v_pk_mul_f32 v[88:89], v[216:217], v[92:93] op_sel:[1,1] op_sel_hi:[1,0]
	v_pk_fma_f32 v[104:105], v[216:217], v[92:93], v[88:89] op_sel_hi:[0,1,1] neg_hi:[1,0,0]
	s_nop 0
	v_pk_mul_f32 v[88:89], v[92:93], v[0:1] op_sel:[1,1] op_sel_hi:[1,0] neg_lo:[1,0]
	v_pk_fma_f32 v[92:93], v[92:93], v[0:1], v[88:89] op_sel_hi:[0,1,1]
	s_waitcnt lgkmcnt(3)
	v_pk_mul_f32 v[108:109], v[218:219], v[92:93] op_sel:[1,1] op_sel_hi:[1,0]
	v_pk_fma_f32 v[106:107], v[218:219], v[92:93], v[108:109] op_sel_hi:[0,1,1] neg_hi:[1,0,0]
	v_pk_mul_f32 v[88:89], v[92:93], v[0:1] op_sel:[1,1] op_sel_hi:[1,0] neg_lo:[1,0]
	v_pk_fma_f32 v[92:93], v[92:93], v[0:1], v[88:89] op_sel_hi:[0,1,1]
	v_pk_mul_f32 v[88:89], v[220:221], v[92:93] op_sel:[1,1] op_sel_hi:[1,0]
	v_pk_fma_f32 v[108:109], v[220:221], v[92:93], v[88:89] op_sel_hi:[0,1,1] neg_hi:[1,0,0]
	s_nop 0
	v_pk_mul_f32 v[88:89], v[92:93], v[0:1] op_sel:[1,1] op_sel_hi:[1,0] neg_lo:[1,0]
	v_pk_fma_f32 v[92:93], v[92:93], v[0:1], v[88:89] op_sel_hi:[0,1,1]
	s_waitcnt lgkmcnt(2)
	v_pk_mul_f32 v[112:113], v[166:167], v[92:93] op_sel:[1,1] op_sel_hi:[1,0]
	v_pk_fma_f32 v[110:111], v[166:167], v[92:93], v[112:113] op_sel_hi:[0,1,1] neg_hi:[1,0,0]
	v_pk_mul_f32 v[88:89], v[92:93], v[0:1] op_sel:[1,1] op_sel_hi:[1,0] neg_lo:[1,0]
	v_pk_fma_f32 v[92:93], v[92:93], v[0:1], v[88:89] op_sel_hi:[0,1,1]
	v_pk_mul_f32 v[88:89], v[168:169], v[92:93] op_sel:[1,1] op_sel_hi:[1,0]
	v_pk_fma_f32 v[112:113], v[168:169], v[92:93], v[88:89] op_sel_hi:[0,1,1] neg_hi:[1,0,0]
	s_nop 0
	v_pk_mul_f32 v[88:89], v[92:93], v[0:1] op_sel:[1,1] op_sel_hi:[1,0] neg_lo:[1,0]
	v_pk_fma_f32 v[92:93], v[92:93], v[0:1], v[88:89] op_sel_hi:[0,1,1]
	s_waitcnt lgkmcnt(1)
	v_pk_mul_f32 v[116:117], v[170:171], v[92:93] op_sel:[1,1] op_sel_hi:[1,0]
	v_pk_fma_f32 v[114:115], v[170:171], v[92:93], v[116:117] op_sel_hi:[0,1,1] neg_hi:[1,0,0]
	v_pk_mul_f32 v[88:89], v[92:93], v[0:1] op_sel:[1,1] op_sel_hi:[1,0] neg_lo:[1,0]
	v_pk_fma_f32 v[92:93], v[92:93], v[0:1], v[88:89] op_sel_hi:[0,1,1]
	v_pk_mul_f32 v[88:89], v[172:173], v[92:93] op_sel:[1,1] op_sel_hi:[1,0]
	v_pk_fma_f32 v[116:117], v[172:173], v[92:93], v[88:89] op_sel_hi:[0,1,1] neg_hi:[1,0,0]
	s_nop 0
	v_pk_mul_f32 v[88:89], v[92:93], v[0:1] op_sel:[1,1] op_sel_hi:[1,0] neg_lo:[1,0]
	v_pk_fma_f32 v[118:119], v[92:93], v[0:1], v[88:89] op_sel_hi:[0,1,1]
	s_nop 0
	v_add_u32_e32 v88, 0xc00, v86
	v_pk_mul_f32 v[120:121], v[118:119], v[0:1] op_sel:[1,1] op_sel_hi:[1,0] neg_lo:[1,0]
	v_pk_fma_f32 v[0:1], v[118:119], v[0:1], v[120:121] op_sel_hi:[0,1,1]
	s_waitcnt lgkmcnt(0)
; template <int R, bool INV> DEV void dft_regs(cf (&v)[R]) {
; #pragma unroll
;     for (int s = R; s >= 2; s >>= 1) {
;         const int h = s >> 1;
; #pragma unroll
;         for (int b = 0; b < R; b += s) {
; #pragma unroll
;             for (int k = 0; k < h; ++k) {
;                 const cf a = v[b + k], c = v[b + k + h];
;                 v[b + k] = a + c;
;                 const cf d = a - c;
;                 const int m = k * (32 / s);
;                 const float wr = tw_cos(m), wi = INV ? tw_sin(m) : -tw_sin(m);
;                 v[b + k + h] = cf{d.x * wr - d.y * wi, d.x * wi + d.y * wr};
;             }
;         }
;     }
; DEV void fft_i2(LAS cf* buf, int t8) {
;     ...
;     for (int p = 0; p < 32; ++p) { v[p] = cmulc(pb[17 * p], wp); wp = cmul(wp, w); }
;     dft_regs<32, true>(v);
	v_pk_mul_f32 v[120:121], v[174:175], v[118:119] op_sel:[1,1] op_sel_hi:[1,0]
	v_pk_fma_f32 v[90:91], v[174:175], v[118:119], v[120:121] op_sel_hi:[0,1,1] neg_hi:[1,0,0]
	v_pk_mul_f32 v[118:119], v[176:177], v[0:1] op_sel:[1,1] op_sel_hi:[1,0]
	v_pk_fma_f32 v[0:1], v[176:177], v[0:1], v[118:119] op_sel_hi:[0,1,1] neg_hi:[1,0,0]
	v_pk_add_f32 v[92:93], v[4:5], v[84:85]
	v_pk_add_f32 v[4:5], v[4:5], v[84:85] neg_lo:[0,1] neg_hi:[0,1]
	v_pk_mul_f32 v[84:85], v[4:5], 0 op_sel_hi:[1,0]
	v_pk_add_f32 v[118:119], v[4:5], v[84:85] op_sel:[0,1] op_sel_hi:[1,0]
	v_pk_add_f32 v[4:5], v[4:5], v[84:85] op_sel:[0,1] op_sel_hi:[1,0] neg_lo:[0,1] neg_hi:[0,1]
	v_mov_b32_e32 v119, v5
	v_pk_add_f32 v[4:5], v[2:3], v[82:83]
	v_pk_add_f32 v[2:3], v[2:3], v[82:83] neg_lo:[0,1] neg_hi:[0,1]
	v_pk_mul_f32 v[82:83], v[2:3], s[82:83] op_sel_hi:[1,0]
	v_pk_fma_f32 v[84:85], v[2:3], s[94:95], v[82:83] op_sel:[0,0,1] op_sel_hi:[1,0,0] neg_lo:[0,0,1] neg_hi:[0,0,1]
	v_pk_fma_f32 v[2:3], v[2:3], s[94:95], v[82:83] op_sel:[0,0,1] op_sel_hi:[1,0,0]
	v_mov_b32_e32 v85, v3
	v_pk_add_f32 v[2:3], v[10:11], v[94:95]
	v_pk_add_f32 v[10:11], v[10:11], v[94:95] neg_lo:[0,1] neg_hi:[0,1]
	v_pk_mul_f32 v[82:83], v[10:11], s[84:85] op_sel_hi:[1,0]
	v_pk_fma_f32 v[94:95], v[10:11], s[16:17], v[82:83] op_sel:[0,0,1] op_sel_hi:[1,0,0] neg_lo:[0,0,1] neg_hi:[0,0,1]
	v_pk_fma_f32 v[10:11], v[10:11], s[16:17], v[82:83] op_sel:[0,0,1] op_sel_hi:[1,0,0]
	v_mov_b32_e32 v95, v11
	v_pk_add_f32 v[10:11], v[6:7], v[96:97]
	v_pk_add_f32 v[6:7], v[6:7], v[96:97] neg_lo:[0,1] neg_hi:[0,1]
	v_pk_mul_f32 v[82:83], v[6:7], s[4:5] op_sel_hi:[1,0]
	v_pk_fma_f32 v[96:97], v[6:7], s[86:87], v[82:83] op_sel:[0,0,1] op_sel_hi:[1,0,0] neg_lo:[0,0,1] neg_hi:[0,0,1]
	v_pk_fma_f32 v[6:7], v[6:7], s[86:87], v[82:83] op_sel:[0,0,1] op_sel_hi:[1,0,0]
	v_mov_b32_e32 v97, v7
	v_pk_add_f32 v[6:7], v[12:13], v[98:99]
	v_pk_add_f32 v[12:13], v[12:13], v[98:99] neg_lo:[0,1] neg_hi:[0,1]
	v_pk_mul_f32 v[82:83], v[12:13], s[18:19] op_sel_hi:[1,0]
	v_pk_fma_f32 v[98:99], v[12:13], s[18:19], v[82:83] op_sel:[0,0,1] op_sel_hi:[1,0,0] neg_lo:[0,0,1] neg_hi:[0,0,1]
	v_pk_fma_f32 v[12:13], v[12:13], s[18:19], v[82:83] op_sel_hi:[1,0,0]
	v_mov_b32_e32 v99, v13
	v_pk_add_f32 v[12:13], v[8:9], v[100:101]
	v_pk_add_f32 v[8:9], v[8:9], v[100:101] neg_lo:[0,1] neg_hi:[0,1]
	v_pk_mul_f32 v[82:83], v[8:9], s[86:87] op_sel_hi:[1,0]
	v_pk_fma_f32 v[100:101], v[8:9], s[4:5], v[82:83] op_sel:[0,0,1] op_sel_hi:[1,0,0] neg_lo:[0,0,1] neg_hi:[0,0,1]
	v_pk_fma_f32 v[8:9], v[8:9], s[4:5], v[82:83] op_sel:[0,0,1] op_sel_hi:[1,0,0]
	v_mov_b32_e32 v101, v9
	v_pk_add_f32 v[8:9], v[16:17], v[102:103]
	v_pk_add_f32 v[16:17], v[16:17], v[102:103] neg_lo:[0,1] neg_hi:[0,1]
	v_pk_mul_f32 v[82:83], v[16:17], s[16:17] op_sel_hi:[1,0]
	v_pk_fma_f32 v[102:103], v[16:17], s[84:85], v[82:83] op_sel:[0,0,1] op_sel_hi:[1,0,0] neg_lo:[0,0,1] neg_hi:[0,0,1]
	v_pk_fma_f32 v[16:17], v[16:17], s[84:85], v[82:83] op_sel:[0,0,1] op_sel_hi:[1,0,0]
	v_mov_b32_e32 v103, v17
	v_pk_add_f32 v[16:17], v[14:15], v[104:105]
	v_pk_add_f32 v[14:15], v[14:15], v[104:105] neg_lo:[0,1] neg_hi:[0,1]
	v_pk_mul_f32 v[82:83], v[14:15], s[94:95] op_sel_hi:[1,0]
	v_pk_fma_f32 v[104:105], v[14:15], s[82:83], v[82:83] op_sel:[0,0,1] op_sel_hi:[1,0,0] neg_lo:[0,0,1] neg_hi:[0,0,1]
	v_pk_fma_f32 v[14:15], v[14:15], s[82:83], v[82:83] op_sel:[0,0,1] op_sel_hi:[1,0,0]
	v_mov_b32_e32 v105, v15
	v_pk_add_f32 v[14:15], v[68:69], v[106:107]
	v_pk_add_f32 v[68:69], v[68:69], v[106:107] neg_lo:[0,1] neg_hi:[0,1]
	v_pk_fma_f32 v[82:83], v[68:69], 0, v[68:69] op_sel:[0,0,1] op_sel_hi:[1,0,0] neg_lo:[0,0,1] neg_hi:[0,0,1]
	v_pk_fma_f32 v[68:69], v[68:69], 0, v[68:69] op_sel:[0,0,1] op_sel_hi:[1,0,0]
	v_mov_b32_e32 v83, v69
	v_pk_add_f32 v[68:69], v[18:19], v[108:109]
	v_pk_add_f32 v[18:19], v[18:19], v[108:109] neg_lo:[0,1] neg_hi:[0,1]
	v_pk_mul_f32 v[106:107], v[18:19], s[6:7] op_sel:[1,0]
	s_mov_b32 s6, s87
	v_pk_fma_f32 v[18:19], v[18:19], s[28:29], v[106:107] op_sel_hi:[0,1,1] neg_lo:[0,0,1] neg_hi:[0,0,1]
	v_pk_add_f32 v[106:107], v[72:73], v[110:111]
	v_pk_add_f32 v[72:73], v[72:73], v[110:111] neg_lo:[0,1] neg_hi:[0,1]
	s_mov_b32 s7, s86
	v_pk_mul_f32 v[108:109], v[72:73], s[24:25] op_sel:[1,0]
	v_pk_fma_f32 v[72:73], v[72:73], s[0:1], v[108:109] op_sel_hi:[0,1,1] neg_lo:[0,0,1] neg_hi:[0,0,1]
	v_pk_add_f32 v[108:109], v[70:71], v[112:113]
	v_pk_add_f32 v[70:71], v[70:71], v[112:113] neg_lo:[0,1] neg_hi:[0,1]
	v_pk_mul_f32 v[110:111], v[70:71], s[2:3] op_sel:[1,0]
	s_mov_b32 s2, s11
	v_pk_fma_f32 v[70:71], v[70:71], s[6:7], v[110:111] op_sel_hi:[0,1,1] neg_lo:[0,0,1] neg_hi:[0,0,1]
	v_pk_add_f32 v[110:111], v[76:77], v[114:115]
	v_pk_add_f32 v[76:77], v[76:77], v[114:115] neg_lo:[0,1] neg_hi:[0,1]
	v_mul_f32_e32 v112, 0x3f3504f3, v77
	v_pk_fma_f32 v[76:77], v[76:77], s[96:97], v[112:113] op_sel_hi:[0,1,0] neg_lo:[0,0,1] neg_hi:[0,0,1]
	v_pk_add_f32 v[112:113], v[74:75], v[116:117]
	v_pk_add_f32 v[74:75], v[74:75], v[116:117] neg_lo:[0,1] neg_hi:[0,1]
	v_pk_mul_f32 v[114:115], v[74:75], s[4:5] op_sel:[1,0]
	s_lshl_b32 s5, s19, 10
	v_pk_fma_f32 v[74:75], v[74:75], s[2:3], v[114:115] op_sel_hi:[0,1,1] neg_lo:[0,0,1] neg_hi:[0,0,1]
	v_pk_add_f32 v[114:115], v[80:81], v[90:91]
	v_pk_add_f32 v[80:81], v[80:81], v[90:91] neg_lo:[0,1] neg_hi:[0,1]
	s_mov_b32 s2, s9
	v_pk_mul_f32 v[90:91], v[80:81], s[84:85] op_sel:[1,0]
	s_mov_b32 s3, s82
	v_pk_fma_f32 v[80:81], v[80:81], s[88:89], v[90:91] op_sel_hi:[0,1,1] neg_lo:[0,0,1] neg_hi:[0,0,1]
	v_pk_add_f32 v[90:91], v[78:79], v[0:1]
	v_pk_add_f32 v[0:1], v[78:79], v[0:1] neg_lo:[0,1] neg_hi:[0,1]
	s_add_i32 s6, s79, s5
	v_pk_mul_f32 v[78:79], v[0:1], s[82:83] op_sel:[1,0]
; template <int R, bool INV> DEV void dft_regs(cf (&v)[R]) {
; #pragma unroll
;     for (int s = R; s >= 2; s >>= 1) {
;         const int h = s >> 1;
; #pragma unroll
;         for (int b = 0; b < R; b += s) {
; #pragma unroll
;             for (int k = 0; k < h; ++k) {
;                 const cf a = v[b + k], c = v[b + k + h];
;                 v[b + k] = a + c;
;                 const cf d = a - c;
;                 const int m = k * (32 / s);
;                 const float wr = tw_cos(m), wi = INV ? tw_sin(m) : -tw_sin(m);
;                 v[b + k + h] = cf{d.x * wr - d.y * wi, d.x * wi + d.y * wr};
;             }
;         }
;     }
; DEV void fft_i2(LAS cf* buf, int t8) {
;     ...
;     dft_regs<32, true>(v);
	s_ashr_i32 s7, s6, 31
	v_pk_fma_f32 v[0:1], v[0:1], s[2:3], v[78:79] op_sel_hi:[0,1,1] neg_lo:[0,0,1] neg_hi:[0,0,1]
	v_pk_add_f32 v[78:79], v[92:93], v[14:15]
	v_pk_add_f32 v[14:15], v[92:93], v[14:15] neg_lo:[0,1] neg_hi:[0,1]
	s_lshl_b64 s[2:3], s[6:7], 13
	v_pk_mul_f32 v[92:93], v[14:15], 0 op_sel_hi:[1,0]
	v_pk_add_f32 v[116:117], v[14:15], v[92:93] op_sel:[0,1] op_sel_hi:[1,0]
	v_pk_add_f32 v[14:15], v[14:15], v[92:93] op_sel:[0,1] op_sel_hi:[1,0] neg_lo:[0,1] neg_hi:[0,1]
	v_mov_b32_e32 v117, v15
	v_pk_add_f32 v[14:15], v[4:5], v[68:69]
	v_pk_add_f32 v[4:5], v[4:5], v[68:69] neg_lo:[0,1] neg_hi:[0,1]
	v_pk_mul_f32 v[68:69], v[4:5], s[84:85] op_sel_hi:[1,0]
	v_pk_fma_f32 v[92:93], v[4:5], s[16:17], v[68:69] op_sel:[0,0,1] op_sel_hi:[1,0,0] neg_lo:[0,0,1] neg_hi:[0,0,1]
	v_pk_fma_f32 v[4:5], v[4:5], s[16:17], v[68:69] op_sel:[0,0,1] op_sel_hi:[1,0,0]
	v_mov_b32_e32 v93, v5
	v_pk_add_f32 v[4:5], v[2:3], v[106:107]
	v_pk_add_f32 v[2:3], v[2:3], v[106:107] neg_lo:[0,1] neg_hi:[0,1]
	v_pk_mul_f32 v[68:69], v[2:3], s[18:19] op_sel_hi:[1,0]
	v_pk_fma_f32 v[106:107], v[2:3], s[18:19], v[68:69] op_sel:[0,0,1] op_sel_hi:[1,0,0] neg_lo:[0,0,1] neg_hi:[0,0,1]
	v_pk_fma_f32 v[2:3], v[2:3], s[18:19], v[68:69] op_sel_hi:[1,0,0]
	v_mov_b32_e32 v107, v3
	v_pk_add_f32 v[2:3], v[10:11], v[108:109]
	v_pk_add_f32 v[10:11], v[10:11], v[108:109] neg_lo:[0,1] neg_hi:[0,1]
	v_pk_mul_f32 v[68:69], v[10:11], s[16:17] op_sel_hi:[1,0]
	v_pk_fma_f32 v[108:109], v[10:11], s[84:85], v[68:69] op_sel:[0,0,1] op_sel_hi:[1,0,0] neg_lo:[0,0,1] neg_hi:[0,0,1]
	v_pk_fma_f32 v[10:11], v[10:11], s[84:85], v[68:69] op_sel:[0,0,1] op_sel_hi:[1,0,0]
	v_mov_b32_e32 v109, v11
	v_pk_add_f32 v[10:11], v[6:7], v[110:111]
	v_pk_add_f32 v[6:7], v[6:7], v[110:111] neg_lo:[0,1] neg_hi:[0,1]
	v_pk_fma_f32 v[68:69], v[6:7], 0, v[6:7] op_sel:[0,0,1] op_sel_hi:[1,0,0] neg_lo:[0,0,1] neg_hi:[0,0,1]
	v_pk_fma_f32 v[6:7], v[6:7], 0, v[6:7] op_sel:[0,0,1] op_sel_hi:[1,0,0]
	v_mov_b32_e32 v69, v7
	v_pk_add_f32 v[6:7], v[12:13], v[112:113]
	v_pk_add_f32 v[12:13], v[12:13], v[112:113] neg_lo:[0,1] neg_hi:[0,1]
	v_pk_mul_f32 v[110:111], v[12:13], s[24:25] op_sel:[1,0]
	v_pk_fma_f32 v[12:13], v[12:13], s[0:1], v[110:111] op_sel_hi:[0,1,1] neg_lo:[0,0,1] neg_hi:[0,0,1]
	v_pk_add_f32 v[110:111], v[8:9], v[114:115]
	v_pk_add_f32 v[8:9], v[8:9], v[114:115] neg_lo:[0,1] neg_hi:[0,1]
	v_mul_f32_e32 v112, 0x3f3504f3, v9
	v_pk_fma_f32 v[8:9], v[8:9], s[96:97], v[112:113] op_sel_hi:[0,1,0] neg_lo:[0,0,1] neg_hi:[0,0,1]
	v_pk_add_f32 v[112:113], v[16:17], v[90:91]
	v_pk_add_f32 v[16:17], v[16:17], v[90:91] neg_lo:[0,1] neg_hi:[0,1]
	v_pk_mul_f32 v[90:91], v[16:17], s[84:85] op_sel:[1,0]
	v_pk_fma_f32 v[16:17], v[16:17], s[88:89], v[90:91] op_sel_hi:[0,1,1] neg_lo:[0,0,1] neg_hi:[0,0,1]
	v_pk_add_f32 v[90:91], v[118:119], v[82:83]
	v_pk_add_f32 v[82:83], v[118:119], v[82:83] neg_lo:[0,1] neg_hi:[0,1]
	v_pk_mul_f32 v[114:115], v[82:83], 0 op_sel_hi:[1,0]
	v_pk_add_f32 v[118:119], v[82:83], v[114:115] op_sel:[0,1] op_sel_hi:[1,0]
	v_pk_add_f32 v[82:83], v[82:83], v[114:115] op_sel:[0,1] op_sel_hi:[1,0] neg_lo:[0,1] neg_hi:[0,1]
	v_mov_b32_e32 v119, v83
	v_pk_add_f32 v[82:83], v[84:85], v[18:19]
	v_pk_add_f32 v[18:19], v[84:85], v[18:19] neg_lo:[0,1] neg_hi:[0,1]
	v_pk_mul_f32 v[84:85], v[18:19], s[84:85] op_sel_hi:[1,0]
	v_pk_fma_f32 v[114:115], v[18:19], s[16:17], v[84:85] op_sel:[0,0,1] op_sel_hi:[1,0,0] neg_lo:[0,0,1] neg_hi:[0,0,1]
	v_pk_fma_f32 v[18:19], v[18:19], s[16:17], v[84:85] op_sel:[0,0,1] op_sel_hi:[1,0,0]
	v_mov_b32_e32 v115, v19
	v_pk_add_f32 v[18:19], v[94:95], v[72:73]
	v_pk_add_f32 v[72:73], v[94:95], v[72:73] neg_lo:[0,1] neg_hi:[0,1]
	v_pk_mul_f32 v[84:85], v[72:73], s[18:19] op_sel_hi:[1,0]
	v_pk_fma_f32 v[94:95], v[72:73], s[18:19], v[84:85] op_sel:[0,0,1] op_sel_hi:[1,0,0] neg_lo:[0,0,1] neg_hi:[0,0,1]
	v_pk_fma_f32 v[72:73], v[72:73], s[18:19], v[84:85] op_sel_hi:[1,0,0]
	v_mov_b32_e32 v95, v73
	v_pk_add_f32 v[72:73], v[96:97], v[70:71]
	v_pk_add_f32 v[70:71], v[96:97], v[70:71] neg_lo:[0,1] neg_hi:[0,1]
	v_pk_mul_f32 v[84:85], v[70:71], s[16:17] op_sel_hi:[1,0]
	v_pk_fma_f32 v[96:97], v[70:71], s[84:85], v[84:85] op_sel:[0,0,1] op_sel_hi:[1,0,0] neg_lo:[0,0,1] neg_hi:[0,0,1]
	v_pk_fma_f32 v[70:71], v[70:71], s[84:85], v[84:85] op_sel:[0,0,1] op_sel_hi:[1,0,0]
	v_mov_b32_e32 v97, v71
	v_pk_add_f32 v[70:71], v[98:99], v[76:77]
	v_pk_add_f32 v[76:77], v[98:99], v[76:77] neg_lo:[0,1] neg_hi:[0,1]
	v_pk_fma_f32 v[84:85], v[76:77], 0, v[76:77] op_sel:[0,0,1] op_sel_hi:[1,0,0] neg_lo:[0,0,1] neg_hi:[0,0,1]
	v_pk_fma_f32 v[76:77], v[76:77], 0, v[76:77] op_sel:[0,0,1] op_sel_hi:[1,0,0]
	v_mov_b32_e32 v85, v77
	v_pk_add_f32 v[76:77], v[100:101], v[74:75]
	v_pk_add_f32 v[74:75], v[100:101], v[74:75] neg_lo:[0,1] neg_hi:[0,1]
	v_pk_mul_f32 v[98:99], v[74:75], s[24:25] op_sel:[1,0]
	v_pk_fma_f32 v[74:75], v[74:75], s[0:1], v[98:99] op_sel_hi:[0,1,1] neg_lo:[0,0,1] neg_hi:[0,0,1]
	v_pk_add_f32 v[98:99], v[102:103], v[80:81]
	v_pk_add_f32 v[80:81], v[102:103], v[80:81] neg_lo:[0,1] neg_hi:[0,1]
	v_mul_f32_e32 v100, 0x3f3504f3, v81
	v_pk_fma_f32 v[80:81], v[80:81], s[96:97], v[100:101] op_sel_hi:[0,1,0] neg_lo:[0,0,1] neg_hi:[0,0,1]
	v_pk_add_f32 v[100:101], v[104:105], v[0:1]
	v_pk_add_f32 v[0:1], v[104:105], v[0:1] neg_lo:[0,1] neg_hi:[0,1]
	v_pk_mul_f32 v[102:103], v[0:1], s[84:85] op_sel:[1,0]
	v_pk_fma_f32 v[0:1], v[0:1], s[88:89], v[102:103] op_sel_hi:[0,1,1] neg_lo:[0,0,1] neg_hi:[0,0,1]
	v_pk_add_f32 v[102:103], v[78:79], v[10:11]
	v_pk_add_f32 v[10:11], v[78:79], v[10:11] neg_lo:[0,1] neg_hi:[0,1]
	v_pk_mul_f32 v[78:79], v[10:11], 0 op_sel_hi:[1,0]
	v_pk_add_f32 v[104:105], v[10:11], v[78:79] op_sel:[0,1] op_sel_hi:[1,0]
; DEV void fft_i2(LAS cf* buf, int t8) {
;     ...
;     dft_regs<32, true>(v);
	v_pk_add_f32 v[10:11], v[10:11], v[78:79] op_sel:[0,1] op_sel_hi:[1,0] neg_lo:[0,1] neg_hi:[0,1]
	v_mov_b32_e32 v105, v11
	v_pk_add_f32 v[10:11], v[14:15], v[6:7]
	v_pk_add_f32 v[6:7], v[14:15], v[6:7] neg_lo:[0,1] neg_hi:[0,1]
	v_pk_mul_f32 v[14:15], v[6:7], s[18:19] op_sel_hi:[1,0]
	v_pk_fma_f32 v[78:79], v[6:7], s[18:19], v[14:15] op_sel:[0,0,1] op_sel_hi:[1,0,0] neg_lo:[0,0,1] neg_hi:[0,0,1]
	v_pk_fma_f32 v[6:7], v[6:7], s[18:19], v[14:15] op_sel_hi:[1,0,0]
	v_mov_b32_e32 v79, v7
	v_pk_add_f32 v[6:7], v[4:5], v[110:111]
	v_pk_add_f32 v[4:5], v[4:5], v[110:111] neg_lo:[0,1] neg_hi:[0,1]
	v_pk_fma_f32 v[14:15], v[4:5], 0, v[4:5] op_sel:[0,0,1] op_sel_hi:[1,0,0] neg_lo:[0,0,1] neg_hi:[0,0,1]
	v_pk_fma_f32 v[4:5], v[4:5], 0, v[4:5] op_sel:[0,0,1] op_sel_hi:[1,0,0]
	v_mov_b32_e32 v15, v5
	v_pk_add_f32 v[4:5], v[2:3], v[112:113]
	v_pk_add_f32 v[2:3], v[2:3], v[112:113] neg_lo:[0,1] neg_hi:[0,1]
	v_mul_f32_e32 v110, 0x3f3504f3, v3
	v_pk_fma_f32 v[2:3], v[2:3], s[96:97], v[110:111] op_sel_hi:[0,1,0] neg_lo:[0,0,1] neg_hi:[0,0,1]
	v_pk_add_f32 v[110:111], v[116:117], v[68:69]
	v_pk_add_f32 v[68:69], v[116:117], v[68:69] neg_lo:[0,1] neg_hi:[0,1]
	v_pk_mul_f32 v[112:113], v[68:69], 0 op_sel_hi:[1,0]
	v_pk_add_f32 v[116:117], v[68:69], v[112:113] op_sel:[0,1] op_sel_hi:[1,0]
	v_pk_add_f32 v[68:69], v[68:69], v[112:113] op_sel:[0,1] op_sel_hi:[1,0] neg_lo:[0,1] neg_hi:[0,1]
	v_mov_b32_e32 v117, v69
	v_pk_add_f32 v[68:69], v[92:93], v[12:13]
	v_pk_add_f32 v[12:13], v[92:93], v[12:13] neg_lo:[0,1] neg_hi:[0,1]
	v_pk_mul_f32 v[92:93], v[12:13], s[18:19] op_sel_hi:[1,0]
	v_pk_fma_f32 v[112:113], v[12:13], s[18:19], v[92:93] op_sel:[0,0,1] op_sel_hi:[1,0,0] neg_lo:[0,0,1] neg_hi:[0,0,1]
	v_pk_fma_f32 v[12:13], v[12:13], s[18:19], v[92:93] op_sel_hi:[1,0,0]
	v_mov_b32_e32 v113, v13
	v_pk_add_f32 v[12:13], v[106:107], v[8:9]
	v_pk_add_f32 v[8:9], v[106:107], v[8:9] neg_lo:[0,1] neg_hi:[0,1]
	v_pk_fma_f32 v[92:93], v[8:9], 0, v[8:9] op_sel:[0,0,1] op_sel_hi:[1,0,0] neg_lo:[0,0,1] neg_hi:[0,0,1]
	v_pk_fma_f32 v[8:9], v[8:9], 0, v[8:9] op_sel:[0,0,1] op_sel_hi:[1,0,0]
	v_mov_b32_e32 v93, v9
	v_pk_add_f32 v[8:9], v[108:109], v[16:17]
	v_pk_add_f32 v[16:17], v[108:109], v[16:17] neg_lo:[0,1] neg_hi:[0,1]
	v_mul_f32_e32 v106, 0x3f3504f3, v17
	v_pk_fma_f32 v[16:17], v[16:17], s[96:97], v[106:107] op_sel_hi:[0,1,0] neg_lo:[0,0,1] neg_hi:[0,0,1]
	v_pk_add_f32 v[106:107], v[90:91], v[70:71]
	v_pk_add_f32 v[70:71], v[90:91], v[70:71] neg_lo:[0,1] neg_hi:[0,1]
	v_pk_mul_f32 v[90:91], v[70:71], 0 op_sel_hi:[1,0]
	v_pk_add_f32 v[108:109], v[70:71], v[90:91] op_sel:[0,1] op_sel_hi:[1,0]
	v_pk_add_f32 v[70:71], v[70:71], v[90:91] op_sel:[0,1] op_sel_hi:[1,0] neg_lo:[0,1] neg_hi:[0,1]
	v_mov_b32_e32 v109, v71
	v_pk_add_f32 v[70:71], v[82:83], v[76:77]
	v_pk_add_f32 v[76:77], v[82:83], v[76:77] neg_lo:[0,1] neg_hi:[0,1]
	v_pk_mul_f32 v[82:83], v[76:77], s[18:19] op_sel_hi:[1,0]
	v_pk_fma_f32 v[90:91], v[76:77], s[18:19], v[82:83] op_sel:[0,0,1] op_sel_hi:[1,0,0] neg_lo:[0,0,1] neg_hi:[0,0,1]
	v_pk_fma_f32 v[76:77], v[76:77], s[18:19], v[82:83] op_sel_hi:[1,0,0]
	v_mov_b32_e32 v91, v77
	v_pk_add_f32 v[76:77], v[18:19], v[98:99]
	v_pk_add_f32 v[18:19], v[18:19], v[98:99] neg_lo:[0,1] neg_hi:[0,1]
	v_pk_fma_f32 v[82:83], v[18:19], 0, v[18:19] op_sel:[0,0,1] op_sel_hi:[1,0,0] neg_lo:[0,0,1] neg_hi:[0,0,1]
	v_pk_fma_f32 v[18:19], v[18:19], 0, v[18:19] op_sel:[0,0,1] op_sel_hi:[1,0,0]
	v_mov_b32_e32 v83, v19
	v_pk_add_f32 v[18:19], v[72:73], v[100:101]
	v_pk_add_f32 v[72:73], v[72:73], v[100:101] neg_lo:[0,1] neg_hi:[0,1]
	v_mul_f32_e32 v98, 0x3f3504f3, v73
	v_pk_fma_f32 v[72:73], v[72:73], s[96:97], v[98:99] op_sel_hi:[0,1,0] neg_lo:[0,0,1] neg_hi:[0,0,1]
	v_pk_add_f32 v[98:99], v[118:119], v[84:85]
	v_pk_add_f32 v[84:85], v[118:119], v[84:85] neg_lo:[0,1] neg_hi:[0,1]
	v_pk_mul_f32 v[100:101], v[84:85], 0 op_sel_hi:[1,0]
	v_pk_add_f32 v[118:119], v[84:85], v[100:101] op_sel:[0,1] op_sel_hi:[1,0]
	v_pk_add_f32 v[84:85], v[84:85], v[100:101] op_sel:[0,1] op_sel_hi:[1,0] neg_lo:[0,1] neg_hi:[0,1]
	v_mov_b32_e32 v119, v85
	v_pk_add_f32 v[84:85], v[114:115], v[74:75]
	v_pk_add_f32 v[74:75], v[114:115], v[74:75] neg_lo:[0,1] neg_hi:[0,1]
	v_pk_mul_f32 v[100:101], v[74:75], s[18:19] op_sel_hi:[1,0]
	v_pk_fma_f32 v[114:115], v[74:75], s[18:19], v[100:101] op_sel:[0,0,1] op_sel_hi:[1,0,0] neg_lo:[0,0,1] neg_hi:[0,0,1]
	v_pk_fma_f32 v[74:75], v[74:75], s[18:19], v[100:101] op_sel_hi:[1,0,0]
	v_mov_b32_e32 v115, v75
	v_pk_add_f32 v[74:75], v[94:95], v[80:81]
	v_pk_add_f32 v[80:81], v[94:95], v[80:81] neg_lo:[0,1] neg_hi:[0,1]
	v_pk_fma_f32 v[94:95], v[80:81], 0, v[80:81] op_sel:[0,0,1] op_sel_hi:[1,0,0] neg_lo:[0,0,1] neg_hi:[0,0,1]
	v_pk_fma_f32 v[80:81], v[80:81], 0, v[80:81] op_sel:[0,0,1] op_sel_hi:[1,0,0]
	v_mov_b32_e32 v95, v81
	v_pk_add_f32 v[80:81], v[96:97], v[0:1]
	v_pk_add_f32 v[0:1], v[96:97], v[0:1] neg_lo:[0,1] neg_hi:[0,1]
	v_mul_f32_e32 v96, 0x3f3504f3, v1
	v_pk_fma_f32 v[0:1], v[0:1], s[96:97], v[96:97] op_sel_hi:[0,1,0] neg_lo:[0,0,1] neg_hi:[0,0,1]
	v_pk_add_f32 v[96:97], v[102:103], v[6:7]
	v_pk_add_f32 v[6:7], v[102:103], v[6:7] neg_lo:[0,1] neg_hi:[0,1]
	v_pk_mul_f32 v[100:101], v[6:7], 0 op_sel_hi:[1,0]
	v_pk_add_f32 v[102:103], v[6:7], v[100:101] op_sel:[0,1] op_sel_hi:[1,0]
	v_pk_add_f32 v[6:7], v[6:7], v[100:101] op_sel:[0,1] op_sel_hi:[1,0] neg_lo:[0,1] neg_hi:[0,1]
	v_mov_b32_e32 v103, v7
	v_pk_add_f32 v[6:7], v[10:11], v[4:5]
	v_pk_add_f32 v[4:5], v[10:11], v[4:5] neg_lo:[0,1] neg_hi:[0,1]
	v_pk_fma_f32 v[10:11], v[4:5], 0, v[4:5] op_sel:[0,0,1] op_sel_hi:[1,0,0] neg_lo:[0,0,1] neg_hi:[0,0,1]
	v_pk_fma_f32 v[4:5], v[4:5], 0, v[4:5] op_sel:[0,0,1] op_sel_hi:[1,0,0]
; DEV void fft_i2(LAS cf* buf, int t8) {
;     ...
;     dft_regs<32, true>(v);
	v_mov_b32_e32 v11, v5
	v_pk_add_f32 v[4:5], v[104:105], v[14:15]
	v_pk_add_f32 v[14:15], v[104:105], v[14:15] neg_lo:[0,1] neg_hi:[0,1]
	v_pk_mul_f32 v[100:101], v[14:15], 0 op_sel_hi:[1,0]
	v_pk_add_f32 v[104:105], v[14:15], v[100:101] op_sel:[0,1] op_sel_hi:[1,0]
	v_pk_add_f32 v[14:15], v[14:15], v[100:101] op_sel:[0,1] op_sel_hi:[1,0] neg_lo:[0,1] neg_hi:[0,1]
	v_mov_b32_e32 v105, v15
	v_pk_add_f32 v[14:15], v[78:79], v[2:3]
	v_pk_add_f32 v[2:3], v[78:79], v[2:3] neg_lo:[0,1] neg_hi:[0,1]
	v_pk_fma_f32 v[78:79], v[2:3], 0, v[2:3] op_sel:[0,0,1] op_sel_hi:[1,0,0] neg_lo:[0,0,1] neg_hi:[0,0,1]
	v_pk_fma_f32 v[2:3], v[2:3], 0, v[2:3] op_sel:[0,0,1] op_sel_hi:[1,0,0]
	v_mov_b32_e32 v79, v3
	v_pk_add_f32 v[2:3], v[110:111], v[12:13]
	v_pk_add_f32 v[12:13], v[110:111], v[12:13] neg_lo:[0,1] neg_hi:[0,1]
	v_pk_mul_f32 v[100:101], v[12:13], 0 op_sel_hi:[1,0]
	v_pk_add_f32 v[110:111], v[12:13], v[100:101] op_sel:[0,1] op_sel_hi:[1,0]
	v_pk_add_f32 v[12:13], v[12:13], v[100:101] op_sel:[0,1] op_sel_hi:[1,0] neg_lo:[0,1] neg_hi:[0,1]
	v_mov_b32_e32 v111, v13
	v_pk_add_f32 v[12:13], v[68:69], v[8:9]
	v_pk_add_f32 v[8:9], v[68:69], v[8:9] neg_lo:[0,1] neg_hi:[0,1]
	v_pk_fma_f32 v[68:69], v[8:9], 0, v[8:9] op_sel:[0,0,1] op_sel_hi:[1,0,0] neg_lo:[0,0,1] neg_hi:[0,0,1]
	v_pk_fma_f32 v[8:9], v[8:9], 0, v[8:9] op_sel:[0,0,1] op_sel_hi:[1,0,0]
	v_mov_b32_e32 v69, v9
	v_pk_add_f32 v[8:9], v[116:117], v[92:93]
	v_pk_add_f32 v[92:93], v[116:117], v[92:93] neg_lo:[0,1] neg_hi:[0,1]
	v_pk_mul_f32 v[100:101], v[92:93], 0 op_sel_hi:[1,0]
	v_pk_add_f32 v[116:117], v[92:93], v[100:101] op_sel:[0,1] op_sel_hi:[1,0]
	v_pk_add_f32 v[92:93], v[92:93], v[100:101] op_sel:[0,1] op_sel_hi:[1,0] neg_lo:[0,1] neg_hi:[0,1]
	v_mov_b32_e32 v117, v93
	v_pk_add_f32 v[92:93], v[112:113], v[16:17]
	v_pk_add_f32 v[16:17], v[112:113], v[16:17] neg_lo:[0,1] neg_hi:[0,1]
	v_pk_fma_f32 v[100:101], v[16:17], 0, v[16:17] op_sel:[0,0,1] op_sel_hi:[1,0,0] neg_lo:[0,0,1] neg_hi:[0,0,1]
	v_pk_fma_f32 v[16:17], v[16:17], 0, v[16:17] op_sel:[0,0,1] op_sel_hi:[1,0,0]
	v_mov_b32_e32 v101, v17
	v_pk_add_f32 v[16:17], v[106:107], v[76:77]
	v_pk_add_f32 v[76:77], v[106:107], v[76:77] neg_lo:[0,1] neg_hi:[0,1]
	v_pk_mul_f32 v[106:107], v[76:77], 0 op_sel_hi:[1,0]
	v_pk_add_f32 v[112:113], v[76:77], v[106:107] op_sel:[0,1] op_sel_hi:[1,0]
	v_pk_add_f32 v[76:77], v[76:77], v[106:107] op_sel:[0,1] op_sel_hi:[1,0] neg_lo:[0,1] neg_hi:[0,1]
	v_mov_b32_e32 v113, v77
	v_pk_add_f32 v[76:77], v[70:71], v[18:19]
	v_pk_add_f32 v[18:19], v[70:71], v[18:19] neg_lo:[0,1] neg_hi:[0,1]
	v_pk_fma_f32 v[70:71], v[18:19], 0, v[18:19] op_sel:[0,0,1] op_sel_hi:[1,0,0] neg_lo:[0,0,1] neg_hi:[0,0,1]
	v_pk_fma_f32 v[18:19], v[18:19], 0, v[18:19] op_sel:[0,0,1] op_sel_hi:[1,0,0]
	v_mov_b32_e32 v71, v19
	v_pk_add_f32 v[18:19], v[108:109], v[82:83]
	v_pk_add_f32 v[82:83], v[108:109], v[82:83] neg_lo:[0,1] neg_hi:[0,1]
	v_pk_mul_f32 v[106:107], v[82:83], 0 op_sel_hi:[1,0]
	v_pk_add_f32 v[108:109], v[82:83], v[106:107] op_sel:[0,1] op_sel_hi:[1,0]
	v_pk_add_f32 v[82:83], v[82:83], v[106:107] op_sel:[0,1] op_sel_hi:[1,0] neg_lo:[0,1] neg_hi:[0,1]
	v_mov_b32_e32 v109, v83
	v_pk_add_f32 v[82:83], v[90:91], v[72:73]
	v_pk_add_f32 v[72:73], v[90:91], v[72:73] neg_lo:[0,1] neg_hi:[0,1]
	v_pk_fma_f32 v[90:91], v[72:73], 0, v[72:73] op_sel:[0,0,1] op_sel_hi:[1,0,0] neg_lo:[0,0,1] neg_hi:[0,0,1]
	v_pk_fma_f32 v[72:73], v[72:73], 0, v[72:73] op_sel:[0,0,1] op_sel_hi:[1,0,0]
	v_mov_b32_e32 v91, v73
	v_pk_add_f32 v[72:73], v[98:99], v[74:75]
	v_pk_add_f32 v[74:75], v[98:99], v[74:75] neg_lo:[0,1] neg_hi:[0,1]
	v_pk_mul_f32 v[98:99], v[74:75], 0 op_sel_hi:[1,0]
	v_pk_add_f32 v[106:107], v[74:75], v[98:99] op_sel:[0,1] op_sel_hi:[1,0]
	v_pk_add_f32 v[74:75], v[74:75], v[98:99] op_sel:[0,1] op_sel_hi:[1,0] neg_lo:[0,1] neg_hi:[0,1]
	v_mov_b32_e32 v107, v75
	v_pk_add_f32 v[74:75], v[84:85], v[80:81]
	v_pk_add_f32 v[80:81], v[84:85], v[80:81] neg_lo:[0,1] neg_hi:[0,1]
	v_pk_fma_f32 v[84:85], v[80:81], 0, v[80:81] op_sel:[0,0,1] op_sel_hi:[1,0,0] neg_lo:[0,0,1] neg_hi:[0,0,1]
	v_pk_fma_f32 v[80:81], v[80:81], 0, v[80:81] op_sel:[0,0,1] op_sel_hi:[1,0,0]
	v_mov_b32_e32 v85, v81
	v_pk_add_f32 v[80:81], v[118:119], v[94:95]
	v_pk_add_f32 v[94:95], v[118:119], v[94:95] neg_lo:[0,1] neg_hi:[0,1]
	v_pk_mul_f32 v[98:99], v[94:95], 0 op_sel_hi:[1,0]
	v_pk_add_f32 v[118:119], v[94:95], v[98:99] op_sel:[0,1] op_sel_hi:[1,0]
	v_pk_add_f32 v[94:95], v[94:95], v[98:99] op_sel:[0,1] op_sel_hi:[1,0] neg_lo:[0,1] neg_hi:[0,1]
	v_mov_b32_e32 v119, v95
	v_pk_add_f32 v[94:95], v[114:115], v[0:1]
	v_pk_add_f32 v[0:1], v[114:115], v[0:1] neg_lo:[0,1] neg_hi:[0,1]
	v_pk_fma_f32 v[98:99], v[0:1], 0, v[0:1] op_sel:[0,0,1] op_sel_hi:[1,0,0] neg_lo:[0,0,1] neg_hi:[0,0,1]
	v_pk_fma_f32 v[0:1], v[0:1], 0, v[0:1] op_sel:[0,0,1] op_sel_hi:[1,0,0]
	v_mov_b32_e32 v99, v1
	v_pk_add_f32 v[0:1], v[96:97], v[6:7]
	v_pk_add_f32 v[6:7], v[96:97], v[6:7] neg_lo:[0,1] neg_hi:[0,1]
	v_pk_mul_f32 v[96:97], v[6:7], 0 op_sel_hi:[1,0]
	v_pk_add_f32 v[114:115], v[6:7], v[96:97] op_sel:[0,1] op_sel_hi:[1,0]
	v_pk_add_f32 v[6:7], v[6:7], v[96:97] op_sel:[0,1] op_sel_hi:[1,0] neg_lo:[0,1] neg_hi:[0,1]
	v_mov_b32_e32 v115, v7
	v_pk_add_f32 v[6:7], v[102:103], v[10:11]
	v_pk_add_f32 v[10:11], v[102:103], v[10:11] neg_lo:[0,1] neg_hi:[0,1]
	v_pk_mul_f32 v[96:97], v[10:11], 0 op_sel_hi:[1,0]
	v_pk_add_f32 v[102:103], v[10:11], v[96:97] op_sel:[0,1] op_sel_hi:[1,0]
	v_pk_add_f32 v[10:11], v[10:11], v[96:97] op_sel:[0,1] op_sel_hi:[1,0] neg_lo:[0,1] neg_hi:[0,1]
	v_mov_b32_e32 v103, v11
	v_pk_add_f32 v[10:11], v[4:5], v[14:15]
	v_pk_add_f32 v[4:5], v[4:5], v[14:15] neg_lo:[0,1] neg_hi:[0,1]
; DEV void fft_i2(LAS cf* buf, int t8) {
;     ...
;     dft_regs<32, true>(v);
; #pragma unroll
;     for (int q = 0; q < 32; ++q) pb[17 * q] = v[BR32[q]];
	v_pk_mul_f32 v[14:15], v[4:5], 0 op_sel_hi:[1,0]
	v_pk_add_f32 v[96:97], v[4:5], v[14:15] op_sel:[0,1] op_sel_hi:[1,0]
	v_pk_add_f32 v[4:5], v[4:5], v[14:15] op_sel:[0,1] op_sel_hi:[1,0] neg_lo:[0,1] neg_hi:[0,1]
	v_pk_add_f32 v[14:15], v[104:105], v[78:79] neg_lo:[0,1] neg_hi:[0,1]
	v_mov_b32_e32 v97, v5
	v_pk_add_f32 v[4:5], v[104:105], v[78:79]
	v_pk_mul_f32 v[78:79], v[14:15], 0 op_sel_hi:[1,0]
	v_pk_add_f32 v[104:105], v[14:15], v[78:79] op_sel:[0,1] op_sel_hi:[1,0]
	v_pk_add_f32 v[14:15], v[14:15], v[78:79] op_sel:[0,1] op_sel_hi:[1,0] neg_lo:[0,1] neg_hi:[0,1]
	v_mov_b32_e32 v105, v15
	v_pk_add_f32 v[14:15], v[2:3], v[12:13]
	v_pk_add_f32 v[2:3], v[2:3], v[12:13] neg_lo:[0,1] neg_hi:[0,1]
	v_pk_mul_f32 v[12:13], v[2:3], 0 op_sel_hi:[1,0]
	v_pk_add_f32 v[78:79], v[2:3], v[12:13] op_sel:[0,1] op_sel_hi:[1,0]
	v_pk_add_f32 v[2:3], v[2:3], v[12:13] op_sel:[0,1] op_sel_hi:[1,0] neg_lo:[0,1] neg_hi:[0,1]
	v_pk_add_f32 v[12:13], v[110:111], v[68:69] neg_lo:[0,1] neg_hi:[0,1]
	v_mov_b32_e32 v79, v3
	v_pk_add_f32 v[2:3], v[110:111], v[68:69]
	v_pk_mul_f32 v[68:69], v[12:13], 0 op_sel_hi:[1,0]
	v_pk_add_f32 v[110:111], v[12:13], v[68:69] op_sel:[0,1] op_sel_hi:[1,0]
	v_pk_add_f32 v[12:13], v[12:13], v[68:69] op_sel:[0,1] op_sel_hi:[1,0] neg_lo:[0,1] neg_hi:[0,1]
	v_mov_b32_e32 v111, v13
	v_pk_add_f32 v[12:13], v[8:9], v[92:93]
	v_pk_add_f32 v[8:9], v[8:9], v[92:93] neg_lo:[0,1] neg_hi:[0,1]
	v_pk_mul_f32 v[68:69], v[8:9], 0 op_sel_hi:[1,0]
	v_pk_add_f32 v[92:93], v[8:9], v[68:69] op_sel:[0,1] op_sel_hi:[1,0]
	v_pk_add_f32 v[8:9], v[8:9], v[68:69] op_sel:[0,1] op_sel_hi:[1,0] neg_lo:[0,1] neg_hi:[0,1]
	v_pk_add_f32 v[68:69], v[116:117], v[100:101] neg_lo:[0,1] neg_hi:[0,1]
	v_mov_b32_e32 v93, v9
	v_pk_add_f32 v[8:9], v[116:117], v[100:101]
	v_pk_mul_f32 v[100:101], v[68:69], 0 op_sel_hi:[1,0]
	v_pk_add_f32 v[116:117], v[68:69], v[100:101] op_sel:[0,1] op_sel_hi:[1,0]
	v_pk_add_f32 v[68:69], v[68:69], v[100:101] op_sel:[0,1] op_sel_hi:[1,0] neg_lo:[0,1] neg_hi:[0,1]
	v_mov_b32_e32 v117, v69
	v_pk_add_f32 v[68:69], v[16:17], v[76:77]
	v_pk_add_f32 v[16:17], v[16:17], v[76:77] neg_lo:[0,1] neg_hi:[0,1]
	v_pk_mul_f32 v[76:77], v[16:17], 0 op_sel_hi:[1,0]
	v_pk_add_f32 v[100:101], v[16:17], v[76:77] op_sel:[0,1] op_sel_hi:[1,0]
	v_pk_add_f32 v[16:17], v[16:17], v[76:77] op_sel:[0,1] op_sel_hi:[1,0] neg_lo:[0,1] neg_hi:[0,1]
	v_mov_b32_e32 v101, v17
	v_pk_add_f32 v[16:17], v[112:113], v[70:71]
	v_pk_add_f32 v[70:71], v[112:113], v[70:71] neg_lo:[0,1] neg_hi:[0,1]
	v_pk_mul_f32 v[76:77], v[70:71], 0 op_sel_hi:[1,0]
	v_pk_add_f32 v[112:113], v[70:71], v[76:77] op_sel:[0,1] op_sel_hi:[1,0]
	v_pk_add_f32 v[70:71], v[70:71], v[76:77] op_sel:[0,1] op_sel_hi:[1,0] neg_lo:[0,1] neg_hi:[0,1]
	v_mov_b32_e32 v113, v71
	v_pk_add_f32 v[70:71], v[18:19], v[82:83]
	v_pk_add_f32 v[18:19], v[18:19], v[82:83] neg_lo:[0,1] neg_hi:[0,1]
	v_pk_mul_f32 v[76:77], v[18:19], 0 op_sel_hi:[1,0]
	v_pk_add_f32 v[82:83], v[18:19], v[76:77] op_sel:[0,1] op_sel_hi:[1,0]
	v_pk_add_f32 v[18:19], v[18:19], v[76:77] op_sel:[0,1] op_sel_hi:[1,0] neg_lo:[0,1] neg_hi:[0,1]
	v_pk_add_f32 v[76:77], v[108:109], v[90:91] neg_lo:[0,1] neg_hi:[0,1]
	v_mov_b32_e32 v83, v19
	v_pk_add_f32 v[18:19], v[108:109], v[90:91]
	v_pk_mul_f32 v[90:91], v[76:77], 0 op_sel_hi:[1,0]
	v_pk_add_f32 v[108:109], v[76:77], v[90:91] op_sel:[0,1] op_sel_hi:[1,0]
	v_pk_add_f32 v[76:77], v[76:77], v[90:91] op_sel:[0,1] op_sel_hi:[1,0] neg_lo:[0,1] neg_hi:[0,1]
	v_mov_b32_e32 v109, v77
	v_pk_add_f32 v[76:77], v[72:73], v[74:75]
	v_pk_add_f32 v[72:73], v[72:73], v[74:75] neg_lo:[0,1] neg_hi:[0,1]
	v_pk_mul_f32 v[74:75], v[72:73], 0 op_sel_hi:[1,0]
	v_pk_add_f32 v[90:91], v[72:73], v[74:75] op_sel:[0,1] op_sel_hi:[1,0]
	v_pk_add_f32 v[72:73], v[72:73], v[74:75] op_sel:[0,1] op_sel_hi:[1,0] neg_lo:[0,1] neg_hi:[0,1]
	v_pk_add_f32 v[74:75], v[106:107], v[84:85] neg_lo:[0,1] neg_hi:[0,1]
	v_mov_b32_e32 v91, v73
	v_pk_add_f32 v[72:73], v[106:107], v[84:85]
	v_pk_mul_f32 v[84:85], v[74:75], 0 op_sel_hi:[1,0]
	v_pk_add_f32 v[106:107], v[74:75], v[84:85] op_sel:[0,1] op_sel_hi:[1,0]
	v_pk_add_f32 v[74:75], v[74:75], v[84:85] op_sel:[0,1] op_sel_hi:[1,0] neg_lo:[0,1] neg_hi:[0,1]
	v_mov_b32_e32 v107, v75
	v_pk_add_f32 v[74:75], v[80:81], v[94:95]
	v_pk_add_f32 v[80:81], v[80:81], v[94:95] neg_lo:[0,1] neg_hi:[0,1]
	v_pk_mul_f32 v[84:85], v[80:81], 0 op_sel_hi:[1,0]
	v_pk_add_f32 v[94:95], v[80:81], v[84:85] op_sel:[0,1] op_sel_hi:[1,0]
	v_pk_add_f32 v[80:81], v[80:81], v[84:85] op_sel:[0,1] op_sel_hi:[1,0] neg_lo:[0,1] neg_hi:[0,1]
	v_pk_add_f32 v[84:85], v[118:119], v[98:99] neg_lo:[0,1] neg_hi:[0,1]
	v_mov_b32_e32 v95, v81
	v_pk_add_f32 v[80:81], v[118:119], v[98:99]
	v_pk_mul_f32 v[98:99], v[84:85], 0 op_sel_hi:[1,0]
	v_pk_add_f32 v[118:119], v[84:85], v[98:99] op_sel:[0,1] op_sel_hi:[1,0]
	v_pk_add_f32 v[84:85], v[84:85], v[98:99] op_sel:[0,1] op_sel_hi:[1,0] neg_lo:[0,1] neg_hi:[0,1]
	v_mov_b32_e32 v119, v85
	ds_write2_b64 v86, v[0:1], v[68:69] offset1:17
	ds_write2_b64 v86, v[14:15], v[76:77] offset0:34 offset1:51
	ds_write2_b64 v86, v[10:11], v[70:71] offset0:68 offset1:85
	ds_write2_b64 v86, v[12:13], v[74:75] offset0:102 offset1:119
	ds_write2_b64 v86, v[6:7], v[16:17] offset0:136 offset1:153
	ds_write2_b64 v86, v[2:3], v[72:73] offset0:170 offset1:187
	ds_write2_b64 v86, v[4:5], v[18:19] offset0:204 offset1:221
	ds_write2_b64 v86, v[8:9], v[80:81] offset0:238 offset1:255
	ds_write2_b64 v87, v[114:115], v[100:101] offset0:16 offset1:33
	ds_write2_b64 v87, v[78:79], v[90:91] offset0:50 offset1:67
	ds_write2_b64 v87, v[96:97], v[82:83] offset0:84 offset1:101
	ds_write2_b64 v87, v[92:93], v[94:95] offset0:118 offset1:135
	ds_write2_b64 v87, v[102:103], v[112:113] offset0:152 offset1:169
	ds_write2_b64 v87, v[110:111], v[106:107] offset0:186 offset1:203
	ds_write2_b64 v87, v[104:105], v[108:109] offset0:220 offset1:237
	ds_write2_b64 v88, v[116:117], v[118:119] offset0:126 offset1:143
	s_mov_b32 s2, 0x1800000
	s_mov_b32 s2, 0x3000000
	s_nop 0
	s_mov_b32 s2, 0x4800000
	s_nop 0
	s_waitcnt lgkmcnt(0)
	s_barrier
; #define LAS __attribute__((address_space(3)))
; #define SINCOSPI(x, s, c) do { const float hx_ = 0.5f * (x); *(s) = __builtin_amdgcn_sinf(hx_); *(c) = __builtin_amdgcn_cosf(hx_); } while (0)
; #define OPAQUE_I(x) asm volatile("" : "+v"(x))
; DEV void fft_i1x2(LAS cf* buf0, LAS cf* buf1, cf (&y0)[8], cf (&y1)[8], int tid) {
;     OPAQUE_I(tid);
;     float sn, cs; SINCOSPI(-(float)tid * (2.0f / 8192.0f), &sn, &cs);
;     const cf w = cf{cs, sn}; cf wp = cf{1.f, 0.f};
;     cf v[16], u[16];
;     const LAS cf* p0 = buf0 + PADI(tid); const LAS cf* p1 = buf1 + PADI(tid);
; #pragma unroll
;     for (int p = 0; p < 16; ++p) { v[p] = cmulc(p0[544 * p], wp); u[p] = cmulc(p1[544 * p], wp); wp = cmul(wp, w); }
	s_nop 0
	v_mov_b32_e32 v16, v21
	s_andn2_b64 vcc, exec, s[26:27]
	v_cvt_f32_i32_e32 v17, v16
	v_mul_f32_e32 v17, 0xb9800000, v17
	v_mul_f32_e32 v17, 0.5, v17
	v_sin_f32_e32 v93, v17
	v_cos_f32_e32 v92, v17
	v_ashrrev_i32_e32 v17, 4, v16
	v_add_lshl_u32 v16, v17, v16, 3
	v_add_u32_e32 v163, 0, v16
	v_add_u32_e32 v164, s33, v16
	ds_read_b64 v[166:167], v163
	ds_read_b64 v[168:169], v164
	ds_read_b64 v[170:171], v163 offset:4352
	ds_read_b64 v[172:173], v164 offset:4352
	ds_read_b64 v[174:175], v163 offset:8704
	ds_read_b64 v[176:177], v164 offset:8704
	ds_read_b64 v[178:179], v163 offset:13056
	ds_read_b64 v[180:181], v164 offset:13056
	ds_read_b64 v[182:183], v163 offset:17408
	ds_read_b64 v[184:185], v164 offset:17408
	ds_read_b64 v[186:187], v163 offset:21760
	ds_read_b64 v[188:189], v164 offset:21760
	ds_read_b64 v[190:191], v163 offset:26112
	s_waitcnt lgkmcnt(12)
	v_pk_mul_f32 v[18:19], v[166:167], v[66:67] op_sel:[1,1] op_sel_hi:[1,0]
	v_pk_fma_f32 v[76:77], v[166:167], v[66:67], v[18:19] op_sel_hi:[0,1,1] neg_hi:[1,0,0]
	ds_read_b64 v[166:167], v164 offset:26112
	s_waitcnt lgkmcnt(12)
	v_pk_mul_f32 v[18:19], v[168:169], v[66:67] op_sel:[1,1] op_sel_hi:[1,0]
	v_pk_fma_f32 v[16:17], v[168:169], v[66:67], v[18:19] op_sel_hi:[0,1,1] neg_hi:[1,0,0]
	s_nop 0
	v_pk_mul_f32 v[18:19], v[66:67], v[92:93] op_sel:[1,1] op_sel_hi:[1,0] neg_lo:[1,0]
	v_pk_fma_f32 v[66:67], v[66:67], v[92:93], v[18:19] op_sel_hi:[0,1,1]
	ds_read_b64 v[168:169], v163 offset:30464
	s_waitcnt lgkmcnt(12)
	v_pk_mul_f32 v[68:69], v[170:171], v[66:67] op_sel:[1,1] op_sel_hi:[1,0]
	v_pk_fma_f32 v[78:79], v[170:171], v[66:67], v[68:69] op_sel_hi:[0,1,1] neg_hi:[1,0,0]
	ds_read_b64 v[170:171], v164 offset:30464
	s_waitcnt lgkmcnt(12)
	v_pk_mul_f32 v[68:69], v[172:173], v[66:67] op_sel:[1,1] op_sel_hi:[1,0]
	v_pk_fma_f32 v[18:19], v[172:173], v[66:67], v[68:69] op_sel_hi:[0,1,1] neg_hi:[1,0,0]
	s_nop 0
	v_pk_mul_f32 v[68:69], v[66:67], v[92:93] op_sel:[1,1] op_sel_hi:[1,0] neg_lo:[1,0]
	v_pk_fma_f32 v[70:71], v[66:67], v[92:93], v[68:69] op_sel_hi:[0,1,1]
	ds_read_b64 v[172:173], v163 offset:34816
	s_waitcnt lgkmcnt(12)
	v_pk_mul_f32 v[68:69], v[174:175], v[70:71] op_sel:[1,1] op_sel_hi:[1,0]
	v_pk_fma_f32 v[82:83], v[174:175], v[70:71], v[68:69] op_sel_hi:[0,1,1] neg_hi:[1,0,0]
	ds_read_b64 v[174:175], v164 offset:34816
	s_waitcnt lgkmcnt(12)
	v_pk_mul_f32 v[68:69], v[176:177], v[70:71] op_sel:[1,1] op_sel_hi:[1,0]
	v_pk_fma_f32 v[66:67], v[176:177], v[70:71], v[68:69] op_sel_hi:[0,1,1] neg_hi:[1,0,0]
	s_nop 0
	v_pk_mul_f32 v[68:69], v[70:71], v[92:93] op_sel:[1,1] op_sel_hi:[1,0] neg_lo:[1,0]
	v_pk_fma_f32 v[70:71], v[70:71], v[92:93], v[68:69] op_sel_hi:[0,1,1]
	ds_read_b64 v[176:177], v163 offset:39168
	s_waitcnt lgkmcnt(12)
	v_pk_mul_f32 v[72:73], v[178:179], v[70:71] op_sel:[1,1] op_sel_hi:[1,0]
	v_pk_fma_f32 v[84:85], v[178:179], v[70:71], v[72:73] op_sel_hi:[0,1,1] neg_hi:[1,0,0]
	ds_read_b64 v[178:179], v164 offset:39168
	s_waitcnt lgkmcnt(12)
	v_pk_mul_f32 v[72:73], v[180:181], v[70:71] op_sel:[1,1] op_sel_hi:[1,0]
	v_pk_fma_f32 v[68:69], v[180:181], v[70:71], v[72:73] op_sel_hi:[0,1,1] neg_hi:[1,0,0]
	s_nop 0
	v_pk_mul_f32 v[72:73], v[70:71], v[92:93] op_sel:[1,1] op_sel_hi:[1,0] neg_lo:[1,0]
	v_pk_fma_f32 v[74:75], v[70:71], v[92:93], v[72:73] op_sel_hi:[0,1,1]
	ds_read_b64 v[180:181], v163 offset:43520
	s_waitcnt lgkmcnt(12)
	v_pk_mul_f32 v[72:73], v[182:183], v[74:75] op_sel:[1,1] op_sel_hi:[1,0]
	v_pk_fma_f32 v[86:87], v[182:183], v[74:75], v[72:73] op_sel_hi:[0,1,1] neg_hi:[1,0,0]
	ds_read_b64 v[182:183], v164 offset:43520
	s_waitcnt lgkmcnt(12)
	v_pk_mul_f32 v[72:73], v[184:185], v[74:75] op_sel:[1,1] op_sel_hi:[1,0]
	v_pk_fma_f32 v[70:71], v[184:185], v[74:75], v[72:73] op_sel_hi:[0,1,1] neg_hi:[1,0,0]
	s_nop 0
	v_pk_mul_f32 v[72:73], v[74:75], v[92:93] op_sel:[1,1] op_sel_hi:[1,0] neg_lo:[1,0]
	v_pk_fma_f32 v[74:75], v[74:75], v[92:93], v[72:73] op_sel_hi:[0,1,1]
	ds_read_b64 v[184:185], v163 offset:47872
	s_waitcnt lgkmcnt(12)
	v_pk_mul_f32 v[80:81], v[186:187], v[74:75] op_sel:[1,1] op_sel_hi:[1,0]
	v_pk_fma_f32 v[90:91], v[186:187], v[74:75], v[80:81] op_sel_hi:[0,1,1] neg_hi:[1,0,0]
	ds_read_b64 v[186:187], v164 offset:47872
	s_waitcnt lgkmcnt(12)
	v_pk_mul_f32 v[80:81], v[188:189], v[74:75] op_sel:[1,1] op_sel_hi:[1,0]
	v_pk_fma_f32 v[72:73], v[188:189], v[74:75], v[80:81] op_sel_hi:[0,1,1] neg_hi:[1,0,0]
	s_nop 0
	v_pk_mul_f32 v[80:81], v[74:75], v[92:93] op_sel:[1,1] op_sel_hi:[1,0] neg_lo:[1,0]
	v_pk_fma_f32 v[88:89], v[74:75], v[92:93], v[80:81] op_sel_hi:[0,1,1]
	ds_read_b64 v[188:189], v163 offset:52224
	s_waitcnt lgkmcnt(12)
	v_pk_mul_f32 v[80:81], v[190:191], v[88:89] op_sel:[1,1] op_sel_hi:[1,0]
	v_pk_fma_f32 v[94:95], v[190:191], v[88:89], v[80:81] op_sel_hi:[0,1,1] neg_hi:[1,0,0]
	ds_read_b64 v[190:191], v164 offset:52224
	s_waitcnt lgkmcnt(12)
	v_pk_mul_f32 v[80:81], v[166:167], v[88:89] op_sel:[1,1] op_sel_hi:[1,0]
	v_pk_fma_f32 v[74:75], v[166:167], v[88:89], v[80:81] op_sel_hi:[0,1,1] neg_hi:[1,0,0]
	s_nop 0
	v_pk_mul_f32 v[80:81], v[88:89], v[92:93] op_sel:[1,1] op_sel_hi:[1,0] neg_lo:[1,0]
	v_pk_fma_f32 v[88:89], v[88:89], v[92:93], v[80:81] op_sel_hi:[0,1,1]
	ds_read_b64 v[166:167], v163 offset:56576
	s_waitcnt lgkmcnt(12)
	v_pk_mul_f32 v[96:97], v[168:169], v[88:89] op_sel:[1,1] op_sel_hi:[1,0]
	v_pk_fma_f32 v[98:99], v[168:169], v[88:89], v[96:97] op_sel_hi:[0,1,1] neg_hi:[1,0,0]
	ds_read_b64 v[168:169], v164 offset:56576
	s_waitcnt lgkmcnt(12)
; #define LAS __attribute__((address_space(3)))
; DEV void fft_i1x2(LAS cf* buf0, LAS cf* buf1, cf (&y0)[8], cf (&y1)[8], int tid) {
;     ...
;     const LAS cf* p0 = buf0 + PADI(tid); const LAS cf* p1 = buf1 + PADI(tid);
; #pragma unroll
;     for (int p = 0; p < 16; ++p) { v[p] = cmulc(p0[544 * p], wp); u[p] = cmulc(p1[544 * p], wp); wp = cmul(wp, w); }
; DEV void hyena_commit_rows(LAS unsigned char* lds, const u32x4 (&r)[4], int tid) {
; #pragma unroll
;     for (int b = 0; b < 4; ++b) *(LAS u32x4*)(lds + b * 8192 + tid * 16) = r[b];
; }
	v_pk_mul_f32 v[96:97], v[170:171], v[88:89] op_sel:[1,1] op_sel_hi:[1,0]
	v_pk_fma_f32 v[80:81], v[170:171], v[88:89], v[96:97] op_sel_hi:[0,1,1] neg_hi:[1,0,0]
	s_nop 0
	v_pk_mul_f32 v[96:97], v[88:89], v[92:93] op_sel:[1,1] op_sel_hi:[1,0] neg_lo:[1,0]
	v_pk_fma_f32 v[102:103], v[88:89], v[92:93], v[96:97] op_sel_hi:[0,1,1]
	ds_read_b64 v[170:171], v163 offset:60928
	s_waitcnt lgkmcnt(12)
	v_pk_mul_f32 v[96:97], v[172:173], v[102:103] op_sel:[1,1] op_sel_hi:[1,0]
	v_pk_fma_f32 v[100:101], v[172:173], v[102:103], v[96:97] op_sel_hi:[0,1,1] neg_hi:[1,0,0]
	ds_read_b64 v[172:173], v164 offset:60928
	s_waitcnt lgkmcnt(12)
	v_pk_mul_f32 v[96:97], v[174:175], v[102:103] op_sel:[1,1] op_sel_hi:[1,0]
	v_pk_fma_f32 v[88:89], v[174:175], v[102:103], v[96:97] op_sel_hi:[0,1,1] neg_hi:[1,0,0]
	s_nop 0
	v_pk_mul_f32 v[96:97], v[102:103], v[92:93] op_sel:[1,1] op_sel_hi:[1,0] neg_lo:[1,0]
	v_pk_fma_f32 v[102:103], v[102:103], v[92:93], v[96:97] op_sel_hi:[0,1,1]
	ds_read_b64 v[174:175], v163 offset:65280
	s_waitcnt lgkmcnt(12)
	v_pk_mul_f32 v[104:105], v[176:177], v[102:103] op_sel:[1,1] op_sel_hi:[1,0]
	v_pk_fma_f32 v[112:113], v[176:177], v[102:103], v[104:105] op_sel_hi:[0,1,1] neg_hi:[1,0,0]
	ds_read_b64 v[176:177], v164 offset:65280
	s_waitcnt lgkmcnt(12)
	v_pk_mul_f32 v[104:105], v[178:179], v[102:103] op_sel:[1,1] op_sel_hi:[1,0]
	v_pk_fma_f32 v[96:97], v[178:179], v[102:103], v[104:105] op_sel_hi:[0,1,1] neg_hi:[1,0,0]
	s_nop 0
	v_pk_mul_f32 v[104:105], v[102:103], v[92:93] op_sel:[1,1] op_sel_hi:[1,0] neg_lo:[1,0]
	v_pk_fma_f32 v[106:107], v[102:103], v[92:93], v[104:105] op_sel_hi:[0,1,1]
	s_waitcnt lgkmcnt(11)
	v_pk_mul_f32 v[104:105], v[180:181], v[106:107] op_sel:[1,1] op_sel_hi:[1,0]
	v_pk_fma_f32 v[116:117], v[180:181], v[106:107], v[104:105] op_sel_hi:[0,1,1] neg_hi:[1,0,0]
	s_waitcnt lgkmcnt(10)
	v_pk_mul_f32 v[104:105], v[182:183], v[106:107] op_sel:[1,1] op_sel_hi:[1,0]
	v_pk_fma_f32 v[102:103], v[182:183], v[106:107], v[104:105] op_sel_hi:[0,1,1] neg_hi:[1,0,0]
	s_nop 0
	v_pk_mul_f32 v[104:105], v[106:107], v[92:93] op_sel:[1,1] op_sel_hi:[1,0] neg_lo:[1,0]
	v_pk_fma_f32 v[106:107], v[106:107], v[92:93], v[104:105] op_sel_hi:[0,1,1]
	s_waitcnt lgkmcnt(9)
	v_pk_mul_f32 v[108:109], v[184:185], v[106:107] op_sel:[1,1] op_sel_hi:[1,0]
	v_pk_fma_f32 v[118:119], v[184:185], v[106:107], v[108:109] op_sel_hi:[0,1,1] neg_hi:[1,0,0]
	s_waitcnt lgkmcnt(8)
	v_pk_mul_f32 v[108:109], v[186:187], v[106:107] op_sel:[1,1] op_sel_hi:[1,0]
	v_pk_fma_f32 v[104:105], v[186:187], v[106:107], v[108:109] op_sel_hi:[0,1,1] neg_hi:[1,0,0]
	s_nop 0
	v_pk_mul_f32 v[108:109], v[106:107], v[92:93] op_sel:[1,1] op_sel_hi:[1,0] neg_lo:[1,0]
	v_pk_fma_f32 v[110:111], v[106:107], v[92:93], v[108:109] op_sel_hi:[0,1,1]
	s_waitcnt lgkmcnt(7)
	v_pk_mul_f32 v[108:109], v[188:189], v[110:111] op_sel:[1,1] op_sel_hi:[1,0]
	v_pk_fma_f32 v[120:121], v[188:189], v[110:111], v[108:109] op_sel_hi:[0,1,1] neg_hi:[1,0,0]
	s_waitcnt lgkmcnt(6)
	v_pk_mul_f32 v[108:109], v[190:191], v[110:111] op_sel:[1,1] op_sel_hi:[1,0]
	v_pk_fma_f32 v[106:107], v[190:191], v[110:111], v[108:109] op_sel_hi:[0,1,1] neg_hi:[1,0,0]
	s_nop 0
	v_pk_mul_f32 v[108:109], v[110:111], v[92:93] op_sel:[1,1] op_sel_hi:[1,0] neg_lo:[1,0]
	v_pk_fma_f32 v[110:111], v[110:111], v[92:93], v[108:109] op_sel_hi:[0,1,1]
	s_waitcnt lgkmcnt(5)
	v_pk_mul_f32 v[114:115], v[166:167], v[110:111] op_sel:[1,1] op_sel_hi:[1,0]
	v_pk_fma_f32 v[122:123], v[166:167], v[110:111], v[114:115] op_sel_hi:[0,1,1] neg_hi:[1,0,0]
	s_waitcnt lgkmcnt(4)
	v_pk_mul_f32 v[114:115], v[168:169], v[110:111] op_sel:[1,1] op_sel_hi:[1,0]
	v_pk_fma_f32 v[108:109], v[168:169], v[110:111], v[114:115] op_sel_hi:[0,1,1] neg_hi:[1,0,0]
	s_nop 0
	v_pk_mul_f32 v[114:115], v[110:111], v[92:93] op_sel:[1,1] op_sel_hi:[1,0] neg_lo:[1,0]
	v_pk_fma_f32 v[126:127], v[110:111], v[92:93], v[114:115] op_sel_hi:[0,1,1]
	s_waitcnt lgkmcnt(3)
	v_pk_mul_f32 v[114:115], v[170:171], v[126:127] op_sel:[1,1] op_sel_hi:[1,0]
	v_pk_fma_f32 v[124:125], v[170:171], v[126:127], v[114:115] op_sel_hi:[0,1,1] neg_hi:[1,0,0]
	s_waitcnt lgkmcnt(2)
	v_pk_mul_f32 v[114:115], v[172:173], v[126:127] op_sel:[1,1] op_sel_hi:[1,0]
	v_pk_fma_f32 v[110:111], v[172:173], v[126:127], v[114:115] op_sel_hi:[0,1,1] neg_hi:[1,0,0]
	s_nop 0
	v_pk_mul_f32 v[114:115], v[126:127], v[92:93] op_sel:[1,1] op_sel_hi:[1,0] neg_lo:[1,0]
	v_pk_fma_f32 v[126:127], v[126:127], v[92:93], v[114:115] op_sel_hi:[0,1,1]
	s_waitcnt lgkmcnt(1)
	v_pk_mul_f32 v[114:115], v[174:175], v[126:127] op_sel:[1,1] op_sel_hi:[1,0]
	v_pk_fma_f32 v[92:93], v[174:175], v[126:127], v[114:115] op_sel_hi:[0,1,1] neg_hi:[1,0,0]
	s_waitcnt lgkmcnt(0)
	v_pk_mul_f32 v[164:165], v[176:177], v[126:127] op_sel:[1,1] op_sel_hi:[1,0]
	v_pk_fma_f32 v[114:115], v[176:177], v[126:127], v[164:165] op_sel_hi:[0,1,1] neg_hi:[1,0,0]
	s_barrier
	s_waitcnt vmcnt(3)
	ds_write_b128 v128, v[222:225]
	s_waitcnt vmcnt(2)
	ds_write_b128 v128, v[226:229] offset:8192
	s_waitcnt vmcnt(1)
	ds_write_b128 v128, v[236:239] offset:16384
	s_waitcnt vmcnt(0)
	ds_write_b128 v128, v[240:243] offset:24576
	s_cbranch_vccnz .LBB0_518
	s_andn2_b64 vcc, exec, s[20:21]
	s_cbranch_vccnz .LBB0_518
	global_load_dwordx4 v[0:3], v[58:59], off
	global_load_dwordx4 v[4:7], v[60:61], off
	global_load_dwordx4 v[8:11], v[62:63], off
	global_load_dwordx4 v[12:15], v[64:65], off
	s_branch .LBB0_518

; __global__ void __launch_bounds__(512, 2) mega_fwd(Args args) {
	.amdhsa_kernel _Z8mega_fwd4Args
		.amdhsa_group_segment_fixed_size 0
		.amdhsa_private_segment_fixed_size 0
		.amdhsa_kernarg_size 512
		.amdhsa_user_sgpr_count 2
		.amdhsa_user_sgpr_dispatch_ptr 0
		.amdhsa_user_sgpr_queue_ptr 0
		.amdhsa_user_sgpr_kernarg_segment_ptr 1
		.amdhsa_user_sgpr_dispatch_id 0
		.amdhsa_user_sgpr_kernarg_preload_length 0
		.amdhsa_user_sgpr_kernarg_preload_offset 0
		.amdhsa_user_sgpr_private_segment_size 0
		.amdhsa_uses_dynamic_stack 0
		.amdhsa_enable_private_segment 0
		.amdhsa_system_sgpr_workgroup_id_x 1
		.amdhsa_system_sgpr_workgroup_id_y 0
		.amdhsa_system_sgpr_workgroup_id_z 0
		.amdhsa_system_sgpr_workgroup_info 0
		.amdhsa_system_vgpr_workitem_id 0
		.amdhsa_next_free_vgpr 256
		.amdhsa_next_free_sgpr 102
		.amdhsa_accum_offset 256
		.amdhsa_reserve_vcc 1
		.amdhsa_float_round_mode_32 0
		.amdhsa_float_round_mode_16_64 0
		.amdhsa_float_denorm_mode_32 3
		.amdhsa_float_denorm_mode_16_64 3
		.amdhsa_dx10_clamp 1
		.amdhsa_ieee_mode 1
		.amdhsa_fp16_overflow 0
		.amdhsa_tg_split 0
		.amdhsa_exception_fp_ieee_invalid_op 0
		.amdhsa_exception_fp_denorm_src 0
		.amdhsa_exception_fp_ieee_div_zero 0
		.amdhsa_exception_fp_ieee_overflow 0
		.amdhsa_exception_fp_ieee_underflow 0
		.amdhsa_exception_fp_ieee_inexact 0
		.amdhsa_exception_int_div_zero 0
	.end_amdhsa_kernel

; __global__ void __launch_bounds__(512, 2) mega_fwd(Args args) {
amdhsa.kernels:
  - .agpr_count:     0
    .args:
      - .offset:         0
        .size:           256
        .value_kind:     by_value
      - .offset:         256
        .size:           4
        .value_kind:     hidden_block_count_x
      - .offset:         260
        .size:           4
        .value_kind:     hidden_block_count_y
      - .offset:         264
        .size:           4
        .value_kind:     hidden_block_count_z
      - .offset:         268
        .size:           2
        .value_kind:     hidden_group_size_x
      - .offset:         270
        .size:           2
        .value_kind:     hidden_group_size_y
      - .offset:         272
        .size:           2
        .value_kind:     hidden_group_size_z
      - .offset:         274
        .size:           2
        .value_kind:     hidden_remainder_x
      - .offset:         276
        .size:           2
        .value_kind:     hidden_remainder_y
      - .offset:         278
        .size:           2
        .value_kind:     hidden_remainder_z
      - .offset:         296
        .size:           8
        .value_kind:     hidden_global_offset_x
      - .offset:         304
        .size:           8
        .value_kind:     hidden_global_offset_y
      - .offset:         312
        .size:           8
        .value_kind:     hidden_global_offset_z
      - .offset:         320
        .size:           2
        .value_kind:     hidden_grid_dims
      - .offset:         376
        .size:           4
        .value_kind:     hidden_dynamic_lds_size
    .group_segment_fixed_size: 0
    .kernarg_segment_align: 8
    .kernarg_segment_size: 512
    .language:       OpenCL C
    .language_version:
      - 2
      - 0
    .max_flat_workgroup_size: 512
    .name:           _Z8mega_fwd4Args
    .private_segment_fixed_size: 0
    .sgpr_count:     108
    .sgpr_spill_count: 240
    .symbol:         _Z8mega_fwd4Args.kd
    .uniform_work_group_size: 1
    .uses_dynamic_stack: false
    .vgpr_count:     256
    .vgpr_spill_count: 0
    .wavefront_size: 64
